# priority lowered after MFMA group 5 (instead of 7) of each K-stage for workgroups < 256; workgroups >= 256 stay at priority 1
# speedup vs baseline: 1.0225x; 1.0053x over previous
; #define LWRITE(S, buf) do { bf16_t* sA_ = sbase + (buf) * BUF; bf16_t* sB_ = sA_ + 256 * PITCH; \
;     _Pragma("unroll") for (int i_ = 0; i_ < 4; ++i_) *(u32x4*)(sA_ + (sr + i_ * 64) * PITCH + scv * 8) = ra[S][i_]; \
;     _Pragma("unroll") for (int i_ = 0; i_ < 2; ++i_) *(u32x4*)(sB_ + (sr + i_ * 64) * PITCH + scv * 8) = rb[S][i_]; } while (0)
; template <class Epi>
; DI void gemm_tile(char* smem, const bf16_t* __restrict__ A0, int lda0, int ksplit, const bf16_t* __restrict__ A1, int lda1,
;                   const bf16_t* __restrict__ Bt, int K, int row0, int col0, const Epi& epi, int tid) {
;     ...
;   __syncthreads();
;   {
;     const int last = nk - 1;
;     GLOAD(0, 0);
;     __builtin_amdgcn_sched_barrier(0);
;     GLOAD(1, 1);
;     __builtin_amdgcn_sched_barrier(0);
;     LWRITE(0, 0);
;     __builtin_amdgcn_sched_barrier(0);
;     GLOAD(0, (2 < last ? 2 : last));
;     __builtin_amdgcn_sched_barrier(0);
;     __syncthreads();
;     for (int kt = 0; kt < nk; kt += 2) {
;       LWRITE(1, 1);
;       __builtin_amdgcn_sched_barrier(0);
;       GLOAD(1, (kt + 3 < last ? kt + 3 : last));
;       __builtin_amdgcn_sched_barrier(0);
;       COMPUTE(0);
;       __syncthreads();
;       LWRITE(0, 0);
;       __builtin_amdgcn_sched_barrier(0);
;       GLOAD(0, (kt + 4 < last ? kt + 4 : last));
;       __builtin_amdgcn_sched_barrier(0);
;       COMPUTE(1);
;       __syncthreads();
;     }
.Lg1_kloop:
	s_waitcnt vmcnt(6)
	s_waitcnt lgkmcnt(0)
	s_barrier
	v_add_u32_e32 v232, s31, v230
	v_add_u32_e32 v233, s31, v231
	s_add_u32 s22, s30, s100
	s_setprio 1
	v_mfma_f32_16x16x32_bf16 v[0:3], v[128:131], v[144:147], v[0:3]
	v_mfma_f32_16x16x32_bf16 v[4:7], v[132:135], v[144:147], v[4:7]
	v_mfma_f32_16x16x32_bf16 v[8:11], v[136:139], v[144:147], v[8:11]
	v_mfma_f32_16x16x32_bf16 v[12:15], v[140:143], v[144:147], v[12:15]
	ds_read_b128 v[176:179], v233 offset:0
	ds_read_b128 v[180:183], v233 offset:1024
	s_add_u32 m0, s22, 0
	s_nop 0
	global_load_lds_dwordx4 v224, s[0:1]
	v_mfma_f32_16x16x32_bf16 v[16:19], v[128:131], v[148:151], v[16:19]
	v_mfma_f32_16x16x32_bf16 v[20:23], v[132:135], v[148:151], v[20:23]
	v_mfma_f32_16x16x32_bf16 v[24:27], v[136:139], v[148:151], v[24:27]
	v_mfma_f32_16x16x32_bf16 v[28:31], v[140:143], v[148:151], v[28:31]
	ds_read_b128 v[184:187], v233 offset:2048
	ds_read_b128 v[188:191], v233 offset:3072
	s_add_u32 m0, s22, 4096
	s_nop 0
	global_load_lds_dwordx4 v225, s[0:1]
	v_mfma_f32_16x16x32_bf16 v[32:35], v[128:131], v[152:155], v[32:35]
	v_mfma_f32_16x16x32_bf16 v[36:39], v[132:135], v[152:155], v[36:39]
	v_mfma_f32_16x16x32_bf16 v[40:43], v[136:139], v[152:155], v[40:43]
	v_mfma_f32_16x16x32_bf16 v[44:47], v[140:143], v[152:155], v[44:47]
	ds_read_b128 v[192:195], v232 offset:0
	ds_read_b128 v[196:199], v232 offset:1024
	s_add_u32 m0, s22, 8192
	s_nop 0
	global_load_lds_dwordx4 v226, s[0:1]
	v_mfma_f32_16x16x32_bf16 v[48:51], v[128:131], v[156:159], v[48:51]
	v_mfma_f32_16x16x32_bf16 v[52:55], v[132:135], v[156:159], v[52:55]
	v_mfma_f32_16x16x32_bf16 v[56:59], v[136:139], v[156:159], v[56:59]
	v_mfma_f32_16x16x32_bf16 v[60:63], v[140:143], v[156:159], v[60:63]
	ds_read_b128 v[200:203], v232 offset:2048
	ds_read_b128 v[204:207], v232 offset:3072
	s_add_u32 m0, s22, 12288
	s_nop 0
	global_load_lds_dwordx4 v227, s[0:1]
	v_mfma_f32_16x16x32_bf16 v[64:67], v[128:131], v[160:163], v[64:67]
	v_mfma_f32_16x16x32_bf16 v[68:71], v[132:135], v[160:163], v[68:71]
	v_mfma_f32_16x16x32_bf16 v[72:75], v[136:139], v[160:163], v[72:75]
	v_mfma_f32_16x16x32_bf16 v[76:79], v[140:143], v[160:163], v[76:79]
	ds_read_b128 v[208:211], v232 offset:4096
	s_add_u32 m0, s22, 16384
	s_nop 0
	global_load_lds_dwordx4 v228, s[2:3]
	v_mfma_f32_16x16x32_bf16 v[80:83], v[128:131], v[164:167], v[80:83]
	v_mfma_f32_16x16x32_bf16 v[84:87], v[132:135], v[164:167], v[84:87]
	v_mfma_f32_16x16x32_bf16 v[88:91], v[136:139], v[164:167], v[88:91]
	v_mfma_f32_16x16x32_bf16 v[92:95], v[140:143], v[164:167], v[92:95]
	ds_read_b128 v[212:215], v232 offset:5120
	s_add_u32 m0, s22, 20480
	s_nop 0
	global_load_lds_dwordx4 v229, s[2:3]
	s_cmp_eq_u32 s21, 0
	s_cbranch_scc0 .Lg1_hi0
	s_setprio 0
.Lg1_hi0:
	v_mfma_f32_16x16x32_bf16 v[96:99], v[128:131], v[168:171], v[96:99]
	v_mfma_f32_16x16x32_bf16 v[100:103], v[132:135], v[168:171], v[100:103]
	v_mfma_f32_16x16x32_bf16 v[104:107], v[136:139], v[168:171], v[104:107]
	v_mfma_f32_16x16x32_bf16 v[108:111], v[140:143], v[168:171], v[108:111]
	ds_read_b128 v[216:219], v232 offset:6144
	s_add_u32 s0, s0, 64
	s_addc_u32 s1, s1, 0
	s_add_u32 s2, s2, 64
	s_addc_u32 s3, s3, 0
	s_add_u32 s99, s99, 1
	s_add_u32 s30, s30, 24576
	s_cmp_eq_u32 s30, 73728
	s_cselect_b32 s30, 0, s30
	s_add_u32 s31, s31, 24576
	s_cmp_eq_u32 s31, 73728
	s_cselect_b32 s31, 0, s31
	v_mfma_f32_16x16x32_bf16 v[112:115], v[128:131], v[172:175], v[112:115]
	v_mfma_f32_16x16x32_bf16 v[116:119], v[132:135], v[172:175], v[116:119]
	v_mfma_f32_16x16x32_bf16 v[120:123], v[136:139], v[172:175], v[120:123]
	v_mfma_f32_16x16x32_bf16 v[124:127], v[140:143], v[172:175], v[124:127]
	ds_read_b128 v[220:223], v232 offset:7168
	s_waitcnt vmcnt(6)
	s_waitcnt lgkmcnt(0)
	s_barrier
	v_add_u32_e32 v232, s31, v230
	v_add_u32_e32 v233, s31, v231
	s_add_u32 s22, s30, s100
	s_setprio 1
	v_mfma_f32_16x16x32_bf16 v[0:3], v[176:179], v[192:195], v[0:3]
	v_mfma_f32_16x16x32_bf16 v[4:7], v[180:183], v[192:195], v[4:7]
	v_mfma_f32_16x16x32_bf16 v[8:11], v[184:187], v[192:195], v[8:11]
	v_mfma_f32_16x16x32_bf16 v[12:15], v[188:191], v[192:195], v[12:15]
	ds_read_b128 v[128:131], v233 offset:0
	ds_read_b128 v[132:135], v233 offset:1024
	s_add_u32 m0, s22, 0
	s_nop 0
	global_load_lds_dwordx4 v224, s[0:1]
	v_mfma_f32_16x16x32_bf16 v[16:19], v[176:179], v[196:199], v[16:19]
	v_mfma_f32_16x16x32_bf16 v[20:23], v[180:183], v[196:199], v[20:23]
	v_mfma_f32_16x16x32_bf16 v[24:27], v[184:187], v[196:199], v[24:27]
	v_mfma_f32_16x16x32_bf16 v[28:31], v[188:191], v[196:199], v[28:31]
	ds_read_b128 v[136:139], v233 offset:2048
	ds_read_b128 v[140:143], v233 offset:3072
	s_add_u32 m0, s22, 4096
	s_nop 0
	global_load_lds_dwordx4 v225, s[0:1]
	v_mfma_f32_16x16x32_bf16 v[32:35], v[176:179], v[200:203], v[32:35]
	v_mfma_f32_16x16x32_bf16 v[36:39], v[180:183], v[200:203], v[36:39]
	v_mfma_f32_16x16x32_bf16 v[40:43], v[184:187], v[200:203], v[40:43]
	v_mfma_f32_16x16x32_bf16 v[44:47], v[188:191], v[200:203], v[44:47]
	ds_read_b128 v[144:147], v232 offset:0
	ds_read_b128 v[148:151], v232 offset:1024
	s_add_u32 m0, s22, 8192
	s_nop 0
	global_load_lds_dwordx4 v226, s[0:1]
	v_mfma_f32_16x16x32_bf16 v[48:51], v[176:179], v[204:207], v[48:51]
	v_mfma_f32_16x16x32_bf16 v[52:55], v[180:183], v[204:207], v[52:55]
	v_mfma_f32_16x16x32_bf16 v[56:59], v[184:187], v[204:207], v[56:59]
	v_mfma_f32_16x16x32_bf16 v[60:63], v[188:191], v[204:207], v[60:63]
	ds_read_b128 v[152:155], v232 offset:2048
	ds_read_b128 v[156:159], v232 offset:3072
	s_add_u32 m0, s22, 12288
	s_nop 0
	global_load_lds_dwordx4 v227, s[0:1]
	v_mfma_f32_16x16x32_bf16 v[64:67], v[176:179], v[208:211], v[64:67]
	v_mfma_f32_16x16x32_bf16 v[68:71], v[180:183], v[208:211], v[68:71]
	v_mfma_f32_16x16x32_bf16 v[72:75], v[184:187], v[208:211], v[72:75]
	v_mfma_f32_16x16x32_bf16 v[76:79], v[188:191], v[208:211], v[76:79]
	ds_read_b128 v[160:163], v232 offset:4096
	s_add_u32 m0, s22, 16384
	s_nop 0
	global_load_lds_dwordx4 v228, s[2:3]
	v_mfma_f32_16x16x32_bf16 v[80:83], v[176:179], v[212:215], v[80:83]
	v_mfma_f32_16x16x32_bf16 v[84:87], v[180:183], v[212:215], v[84:87]
	v_mfma_f32_16x16x32_bf16 v[88:91], v[184:187], v[212:215], v[88:91]
	v_mfma_f32_16x16x32_bf16 v[92:95], v[188:191], v[212:215], v[92:95]
	ds_read_b128 v[164:167], v232 offset:5120
	s_add_u32 m0, s22, 20480
	s_nop 0
	global_load_lds_dwordx4 v229, s[2:3]
	s_cmp_eq_u32 s21, 0
	s_cbranch_scc0 .Lg1_hi1
	s_setprio 0
; #define LWRITE(S, buf) do { bf16_t* sA_ = sbase + (buf) * BUF; bf16_t* sB_ = sA_ + 256 * PITCH; \
;     _Pragma("unroll") for (int i_ = 0; i_ < 4; ++i_) *(u32x4*)(sA_ + (sr + i_ * 64) * PITCH + scv * 8) = ra[S][i_]; \
;     _Pragma("unroll") for (int i_ = 0; i_ < 2; ++i_) *(u32x4*)(sB_ + (sr + i_ * 64) * PITCH + scv * 8) = rb[S][i_]; } while (0)
; template <class Epi>
; DI void gemm_tile(char* smem, const bf16_t* __restrict__ A0, int lda0, int ksplit, const bf16_t* __restrict__ A1, int lda1,
;                   const bf16_t* __restrict__ Bt, int K, int row0, int col0, const Epi& epi, int tid) {
;     ...
;   __syncthreads();
;   {
;     const int last = nk - 1;
;     GLOAD(0, 0);
;     __builtin_amdgcn_sched_barrier(0);
;     GLOAD(1, 1);
;     __builtin_amdgcn_sched_barrier(0);
;     LWRITE(0, 0);
;     __builtin_amdgcn_sched_barrier(0);
;     GLOAD(0, (2 < last ? 2 : last));
;     __builtin_amdgcn_sched_barrier(0);
;     __syncthreads();
;     for (int kt = 0; kt < nk; kt += 2) {
;       LWRITE(1, 1);
;       __builtin_amdgcn_sched_barrier(0);
;       GLOAD(1, (kt + 3 < last ? kt + 3 : last));
;       __builtin_amdgcn_sched_barrier(0);
;       COMPUTE(0);
;       __syncthreads();
;       LWRITE(0, 0);
;       __builtin_amdgcn_sched_barrier(0);
;       GLOAD(0, (kt + 4 < last ? kt + 4 : last));
;       __builtin_amdgcn_sched_barrier(0);
;       COMPUTE(1);
;       __syncthreads();
;     }
.Lg1_hi1:
	v_mfma_f32_16x16x32_bf16 v[96:99], v[176:179], v[216:219], v[96:99]
	v_mfma_f32_16x16x32_bf16 v[100:103], v[180:183], v[216:219], v[100:103]
	v_mfma_f32_16x16x32_bf16 v[104:107], v[184:187], v[216:219], v[104:107]
	v_mfma_f32_16x16x32_bf16 v[108:111], v[188:191], v[216:219], v[108:111]
	ds_read_b128 v[168:171], v232 offset:6144
	s_add_u32 s0, s0, 64
	s_addc_u32 s1, s1, 0
	s_add_u32 s2, s2, 64
	s_addc_u32 s3, s3, 0
	s_add_u32 s99, s99, 1
	s_add_u32 s30, s30, 24576
	s_cmp_eq_u32 s30, 73728
	s_cselect_b32 s30, 0, s30
	s_add_u32 s31, s31, 24576
	s_cmp_eq_u32 s31, 73728
	s_cselect_b32 s31, 0, s31
	v_mfma_f32_16x16x32_bf16 v[112:115], v[176:179], v[220:223], v[112:115]
	v_mfma_f32_16x16x32_bf16 v[116:119], v[180:183], v[220:223], v[116:119]
	v_mfma_f32_16x16x32_bf16 v[120:123], v[184:187], v[220:223], v[120:123]
	v_mfma_f32_16x16x32_bf16 v[124:127], v[188:191], v[220:223], v[124:127]
	ds_read_b128 v[172:175], v232 offset:7168
	s_add_u32 s98, s98, 2
	s_cmp_lt_u32 s98, 28
	s_cbranch_scc1 .Lg1_kloop
	s_waitcnt vmcnt(6)
	s_waitcnt lgkmcnt(0)
	s_barrier
	v_add_u32_e32 v232, s31, v230
	v_add_u32_e32 v233, s31, v231
	s_add_u32 s22, s30, s100
	s_setprio 1
	v_mfma_f32_16x16x32_bf16 v[0:3], v[128:131], v[144:147], v[0:3]
	v_mfma_f32_16x16x32_bf16 v[4:7], v[132:135], v[144:147], v[4:7]
	v_mfma_f32_16x16x32_bf16 v[8:11], v[136:139], v[144:147], v[8:11]
	v_mfma_f32_16x16x32_bf16 v[12:15], v[140:143], v[144:147], v[12:15]
	ds_read_b128 v[176:179], v233 offset:0
	ds_read_b128 v[180:183], v233 offset:1024
	s_add_u32 m0, s22, 0
	s_nop 0
	global_load_lds_dwordx4 v224, s[0:1]
	v_mfma_f32_16x16x32_bf16 v[16:19], v[128:131], v[148:151], v[16:19]
	v_mfma_f32_16x16x32_bf16 v[20:23], v[132:135], v[148:151], v[20:23]
	v_mfma_f32_16x16x32_bf16 v[24:27], v[136:139], v[148:151], v[24:27]
	v_mfma_f32_16x16x32_bf16 v[28:31], v[140:143], v[148:151], v[28:31]
	ds_read_b128 v[184:187], v233 offset:2048
	ds_read_b128 v[188:191], v233 offset:3072
	s_add_u32 m0, s22, 4096
	s_nop 0
	global_load_lds_dwordx4 v225, s[0:1]
	v_mfma_f32_16x16x32_bf16 v[32:35], v[128:131], v[152:155], v[32:35]
	v_mfma_f32_16x16x32_bf16 v[36:39], v[132:135], v[152:155], v[36:39]
	v_mfma_f32_16x16x32_bf16 v[40:43], v[136:139], v[152:155], v[40:43]
	v_mfma_f32_16x16x32_bf16 v[44:47], v[140:143], v[152:155], v[44:47]
	ds_read_b128 v[192:195], v232 offset:0
	ds_read_b128 v[196:199], v232 offset:1024
	s_add_u32 m0, s22, 8192
	s_nop 0
	global_load_lds_dwordx4 v226, s[0:1]
	v_mfma_f32_16x16x32_bf16 v[48:51], v[128:131], v[156:159], v[48:51]
	v_mfma_f32_16x16x32_bf16 v[52:55], v[132:135], v[156:159], v[52:55]
	v_mfma_f32_16x16x32_bf16 v[56:59], v[136:139], v[156:159], v[56:59]
	v_mfma_f32_16x16x32_bf16 v[60:63], v[140:143], v[156:159], v[60:63]
	ds_read_b128 v[200:203], v232 offset:2048
	ds_read_b128 v[204:207], v232 offset:3072
	s_add_u32 m0, s22, 12288
	s_nop 0
	global_load_lds_dwordx4 v227, s[0:1]
	v_mfma_f32_16x16x32_bf16 v[64:67], v[128:131], v[160:163], v[64:67]
	v_mfma_f32_16x16x32_bf16 v[68:71], v[132:135], v[160:163], v[68:71]
	v_mfma_f32_16x16x32_bf16 v[72:75], v[136:139], v[160:163], v[72:75]
	v_mfma_f32_16x16x32_bf16 v[76:79], v[140:143], v[160:163], v[76:79]
	ds_read_b128 v[208:211], v232 offset:4096
	s_add_u32 m0, s22, 16384
	s_nop 0
	global_load_lds_dwordx4 v228, s[2:3]
	v_mfma_f32_16x16x32_bf16 v[80:83], v[128:131], v[164:167], v[80:83]
	v_mfma_f32_16x16x32_bf16 v[84:87], v[132:135], v[164:167], v[84:87]
	v_mfma_f32_16x16x32_bf16 v[88:91], v[136:139], v[164:167], v[88:91]
	v_mfma_f32_16x16x32_bf16 v[92:95], v[140:143], v[164:167], v[92:95]
	ds_read_b128 v[212:215], v232 offset:5120
	s_add_u32 m0, s22, 20480
	s_nop 0
	global_load_lds_dwordx4 v229, s[2:3]
	s_cmp_eq_u32 s21, 0
	s_cbranch_scc0 .Lg1_hi2
	s_setprio 0
.Lg1_hi2:
	v_mfma_f32_16x16x32_bf16 v[96:99], v[128:131], v[168:171], v[96:99]
	v_mfma_f32_16x16x32_bf16 v[100:103], v[132:135], v[168:171], v[100:103]
	v_mfma_f32_16x16x32_bf16 v[104:107], v[136:139], v[168:171], v[104:107]
	v_mfma_f32_16x16x32_bf16 v[108:111], v[140:143], v[168:171], v[108:111]
	ds_read_b128 v[216:219], v232 offset:6144
	s_add_u32 s0, s0, 64
	s_addc_u32 s1, s1, 0
	s_add_u32 s2, s2, 64
	s_addc_u32 s3, s3, 0
	s_add_u32 s99, s99, 1
	s_add_u32 s30, s30, 24576
	s_cmp_eq_u32 s30, 73728
	s_cselect_b32 s30, 0, s30
	s_add_u32 s31, s31, 24576
	s_cmp_eq_u32 s31, 73728
	s_cselect_b32 s31, 0, s31
	v_mfma_f32_16x16x32_bf16 v[112:115], v[128:131], v[172:175], v[112:115]
	v_mfma_f32_16x16x32_bf16 v[116:119], v[132:135], v[172:175], v[116:119]
	v_mfma_f32_16x16x32_bf16 v[120:123], v[136:139], v[172:175], v[120:123]
	v_mfma_f32_16x16x32_bf16 v[124:127], v[140:143], v[172:175], v[124:127]
	ds_read_b128 v[220:223], v232 offset:7168
	s_waitcnt vmcnt(6)
	s_waitcnt lgkmcnt(0)
	s_barrier
	v_add_u32_e32 v232, s31, v230
	v_add_u32_e32 v233, s31, v231
	s_setprio 1
	v_mfma_f32_16x16x32_bf16 v[0:3], v[176:179], v[192:195], v[0:3]
	v_mfma_f32_16x16x32_bf16 v[4:7], v[180:183], v[192:195], v[4:7]
	v_mfma_f32_16x16x32_bf16 v[8:11], v[184:187], v[192:195], v[8:11]
	v_mfma_f32_16x16x32_bf16 v[12:15], v[188:191], v[192:195], v[12:15]
	ds_read_b128 v[128:131], v233 offset:0
	ds_read_b128 v[132:135], v233 offset:1024
	v_mfma_f32_16x16x32_bf16 v[16:19], v[176:179], v[196:199], v[16:19]
	v_mfma_f32_16x16x32_bf16 v[20:23], v[180:183], v[196:199], v[20:23]
	v_mfma_f32_16x16x32_bf16 v[24:27], v[184:187], v[196:199], v[24:27]
	v_mfma_f32_16x16x32_bf16 v[28:31], v[188:191], v[196:199], v[28:31]
	ds_read_b128 v[136:139], v233 offset:2048
	ds_read_b128 v[140:143], v233 offset:3072
	v_mfma_f32_16x16x32_bf16 v[32:35], v[176:179], v[200:203], v[32:35]
	v_mfma_f32_16x16x32_bf16 v[36:39], v[180:183], v[200:203], v[36:39]
	v_mfma_f32_16x16x32_bf16 v[40:43], v[184:187], v[200:203], v[40:43]
	v_mfma_f32_16x16x32_bf16 v[44:47], v[188:191], v[200:203], v[44:47]
	ds_read_b128 v[144:147], v232 offset:0
	ds_read_b128 v[148:151], v232 offset:1024
	v_mfma_f32_16x16x32_bf16 v[48:51], v[176:179], v[204:207], v[48:51]
	v_mfma_f32_16x16x32_bf16 v[52:55], v[180:183], v[204:207], v[52:55]
	v_mfma_f32_16x16x32_bf16 v[56:59], v[184:187], v[204:207], v[56:59]
	v_mfma_f32_16x16x32_bf16 v[60:63], v[188:191], v[204:207], v[60:63]
	ds_read_b128 v[152:155], v232 offset:2048
	ds_read_b128 v[156:159], v232 offset:3072
	v_mfma_f32_16x16x32_bf16 v[64:67], v[176:179], v[208:211], v[64:67]
	v_mfma_f32_16x16x32_bf16 v[68:71], v[180:183], v[208:211], v[68:71]
	v_mfma_f32_16x16x32_bf16 v[72:75], v[184:187], v[208:211], v[72:75]
	v_mfma_f32_16x16x32_bf16 v[76:79], v[188:191], v[208:211], v[76:79]
	ds_read_b128 v[160:163], v232 offset:4096
	v_mfma_f32_16x16x32_bf16 v[80:83], v[176:179], v[212:215], v[80:83]
	v_mfma_f32_16x16x32_bf16 v[84:87], v[180:183], v[212:215], v[84:87]
	v_mfma_f32_16x16x32_bf16 v[88:91], v[184:187], v[212:215], v[88:91]
	v_mfma_f32_16x16x32_bf16 v[92:95], v[188:191], v[212:215], v[92:95]
	ds_read_b128 v[164:167], v232 offset:5120
	s_cmp_eq_u32 s21, 0
	s_cbranch_scc0 .Lg1_hi3
	s_setprio 0
; #define LWRITE(S, buf) do { bf16_t* sA_ = sbase + (buf) * BUF; bf16_t* sB_ = sA_ + 256 * PITCH; \
;     _Pragma("unroll") for (int i_ = 0; i_ < 4; ++i_) *(u32x4*)(sA_ + (sr + i_ * 64) * PITCH + scv * 8) = ra[S][i_]; \
;     _Pragma("unroll") for (int i_ = 0; i_ < 2; ++i_) *(u32x4*)(sB_ + (sr + i_ * 64) * PITCH + scv * 8) = rb[S][i_]; } while (0)
; template <class Epi>
; DI void gemm_tile(char* smem, const bf16_t* __restrict__ A0, int lda0, int ksplit, const bf16_t* __restrict__ A1, int lda1,
;                   const bf16_t* __restrict__ Bt, int K, int row0, int col0, const Epi& epi, int tid) {
;     ...
;   __syncthreads();
;   {
;     const int last = nk - 1;
;     GLOAD(0, 0);
;     __builtin_amdgcn_sched_barrier(0);
;     GLOAD(1, 1);
;     __builtin_amdgcn_sched_barrier(0);
;     LWRITE(0, 0);
;     __builtin_amdgcn_sched_barrier(0);
;     GLOAD(0, (2 < last ? 2 : last));
;     __builtin_amdgcn_sched_barrier(0);
;     __syncthreads();
;     for (int kt = 0; kt < nk; kt += 2) {
;       LWRITE(1, 1);
;       __builtin_amdgcn_sched_barrier(0);
;       GLOAD(1, (kt + 3 < last ? kt + 3 : last));
;       __builtin_amdgcn_sched_barrier(0);
;       COMPUTE(0);
;       __syncthreads();
;       LWRITE(0, 0);
;       __builtin_amdgcn_sched_barrier(0);
;       GLOAD(0, (kt + 4 < last ? kt + 4 : last));
;       __builtin_amdgcn_sched_barrier(0);
;       COMPUTE(1);
;       __syncthreads();
;     }
.Lg1_hi3:
	v_mfma_f32_16x16x32_bf16 v[96:99], v[176:179], v[216:219], v[96:99]
	v_mfma_f32_16x16x32_bf16 v[100:103], v[180:183], v[216:219], v[100:103]
	v_mfma_f32_16x16x32_bf16 v[104:107], v[184:187], v[216:219], v[104:107]
	v_mfma_f32_16x16x32_bf16 v[108:111], v[188:191], v[216:219], v[108:111]
	ds_read_b128 v[168:171], v232 offset:6144
	s_add_u32 s31, s31, 24576
	s_cmp_eq_u32 s31, 73728
	s_cselect_b32 s31, 0, s31
	v_mfma_f32_16x16x32_bf16 v[112:115], v[176:179], v[220:223], v[112:115]
	v_mfma_f32_16x16x32_bf16 v[116:119], v[180:183], v[220:223], v[116:119]
	v_mfma_f32_16x16x32_bf16 v[120:123], v[184:187], v[220:223], v[120:123]
	v_mfma_f32_16x16x32_bf16 v[124:127], v[188:191], v[220:223], v[124:127]
	ds_read_b128 v[172:175], v232 offset:7168
	s_waitcnt vmcnt(0)
	s_waitcnt lgkmcnt(0)
	s_barrier
	v_add_u32_e32 v232, s31, v230
	v_add_u32_e32 v233, s31, v231
	s_setprio 1
	v_mfma_f32_16x16x32_bf16 v[0:3], v[128:131], v[144:147], v[0:3]
	v_mfma_f32_16x16x32_bf16 v[4:7], v[132:135], v[144:147], v[4:7]
	v_mfma_f32_16x16x32_bf16 v[8:11], v[136:139], v[144:147], v[8:11]
	v_mfma_f32_16x16x32_bf16 v[12:15], v[140:143], v[144:147], v[12:15]
	ds_read_b128 v[176:179], v233 offset:0
	ds_read_b128 v[180:183], v233 offset:1024
	v_mfma_f32_16x16x32_bf16 v[16:19], v[128:131], v[148:151], v[16:19]
	v_mfma_f32_16x16x32_bf16 v[20:23], v[132:135], v[148:151], v[20:23]
	v_mfma_f32_16x16x32_bf16 v[24:27], v[136:139], v[148:151], v[24:27]
	v_mfma_f32_16x16x32_bf16 v[28:31], v[140:143], v[148:151], v[28:31]
	ds_read_b128 v[184:187], v233 offset:2048
	ds_read_b128 v[188:191], v233 offset:3072
	v_mfma_f32_16x16x32_bf16 v[32:35], v[128:131], v[152:155], v[32:35]
	v_mfma_f32_16x16x32_bf16 v[36:39], v[132:135], v[152:155], v[36:39]
	v_mfma_f32_16x16x32_bf16 v[40:43], v[136:139], v[152:155], v[40:43]
	v_mfma_f32_16x16x32_bf16 v[44:47], v[140:143], v[152:155], v[44:47]
	ds_read_b128 v[192:195], v232 offset:0
	ds_read_b128 v[196:199], v232 offset:1024
	v_mfma_f32_16x16x32_bf16 v[48:51], v[128:131], v[156:159], v[48:51]
	v_mfma_f32_16x16x32_bf16 v[52:55], v[132:135], v[156:159], v[52:55]
	v_mfma_f32_16x16x32_bf16 v[56:59], v[136:139], v[156:159], v[56:59]
	v_mfma_f32_16x16x32_bf16 v[60:63], v[140:143], v[156:159], v[60:63]
	ds_read_b128 v[200:203], v232 offset:2048
	ds_read_b128 v[204:207], v232 offset:3072
	v_mfma_f32_16x16x32_bf16 v[64:67], v[128:131], v[160:163], v[64:67]
	v_mfma_f32_16x16x32_bf16 v[68:71], v[132:135], v[160:163], v[68:71]
	v_mfma_f32_16x16x32_bf16 v[72:75], v[136:139], v[160:163], v[72:75]
	v_mfma_f32_16x16x32_bf16 v[76:79], v[140:143], v[160:163], v[76:79]
	ds_read_b128 v[208:211], v232 offset:4096
	v_mfma_f32_16x16x32_bf16 v[80:83], v[128:131], v[164:167], v[80:83]
	v_mfma_f32_16x16x32_bf16 v[84:87], v[132:135], v[164:167], v[84:87]
	v_mfma_f32_16x16x32_bf16 v[88:91], v[136:139], v[164:167], v[88:91]
	v_mfma_f32_16x16x32_bf16 v[92:95], v[140:143], v[164:167], v[92:95]
	ds_read_b128 v[212:215], v232 offset:5120
	s_cmp_eq_u32 s21, 0
	s_cbranch_scc0 .Lg1_hi4
	s_setprio 0
.Lg1_hi4:
	v_mfma_f32_16x16x32_bf16 v[96:99], v[128:131], v[168:171], v[96:99]
	v_mfma_f32_16x16x32_bf16 v[100:103], v[132:135], v[168:171], v[100:103]
	v_mfma_f32_16x16x32_bf16 v[104:107], v[136:139], v[168:171], v[104:107]
	v_mfma_f32_16x16x32_bf16 v[108:111], v[140:143], v[168:171], v[108:111]
	ds_read_b128 v[216:219], v232 offset:6144
	s_add_u32 s31, s31, 24576
	s_cmp_eq_u32 s31, 73728
	s_cselect_b32 s31, 0, s31
	v_mfma_f32_16x16x32_bf16 v[112:115], v[128:131], v[172:175], v[112:115]
	v_mfma_f32_16x16x32_bf16 v[116:119], v[132:135], v[172:175], v[116:119]
	v_mfma_f32_16x16x32_bf16 v[120:123], v[136:139], v[172:175], v[120:123]
	v_mfma_f32_16x16x32_bf16 v[124:127], v[140:143], v[172:175], v[124:127]
	ds_read_b128 v[220:223], v232 offset:7168
	s_waitcnt lgkmcnt(0)
	s_barrier
	s_setprio 1
	v_mfma_f32_16x16x32_bf16 v[0:3], v[176:179], v[192:195], v[0:3]
	v_mfma_f32_16x16x32_bf16 v[4:7], v[180:183], v[192:195], v[4:7]
	v_mfma_f32_16x16x32_bf16 v[8:11], v[184:187], v[192:195], v[8:11]
	v_mfma_f32_16x16x32_bf16 v[12:15], v[188:191], v[192:195], v[12:15]
	v_mfma_f32_16x16x32_bf16 v[16:19], v[176:179], v[196:199], v[16:19]
	v_mfma_f32_16x16x32_bf16 v[20:23], v[180:183], v[196:199], v[20:23]
	v_mfma_f32_16x16x32_bf16 v[24:27], v[184:187], v[196:199], v[24:27]
	v_mfma_f32_16x16x32_bf16 v[28:31], v[188:191], v[196:199], v[28:31]
	v_mfma_f32_16x16x32_bf16 v[32:35], v[176:179], v[200:203], v[32:35]
	v_mfma_f32_16x16x32_bf16 v[36:39], v[180:183], v[200:203], v[36:39]
	v_mfma_f32_16x16x32_bf16 v[40:43], v[184:187], v[200:203], v[40:43]
	v_mfma_f32_16x16x32_bf16 v[44:47], v[188:191], v[200:203], v[44:47]
	v_mfma_f32_16x16x32_bf16 v[48:51], v[176:179], v[204:207], v[48:51]
	v_mfma_f32_16x16x32_bf16 v[52:55], v[180:183], v[204:207], v[52:55]
	v_mfma_f32_16x16x32_bf16 v[56:59], v[184:187], v[204:207], v[56:59]
	v_mfma_f32_16x16x32_bf16 v[60:63], v[188:191], v[204:207], v[60:63]
	v_mfma_f32_16x16x32_bf16 v[64:67], v[176:179], v[208:211], v[64:67]
	v_mfma_f32_16x16x32_bf16 v[68:71], v[180:183], v[208:211], v[68:71]
	v_mfma_f32_16x16x32_bf16 v[72:75], v[184:187], v[208:211], v[72:75]
	v_mfma_f32_16x16x32_bf16 v[76:79], v[188:191], v[208:211], v[76:79]
	v_mfma_f32_16x16x32_bf16 v[80:83], v[176:179], v[212:215], v[80:83]
	v_mfma_f32_16x16x32_bf16 v[84:87], v[180:183], v[212:215], v[84:87]
	v_mfma_f32_16x16x32_bf16 v[88:91], v[184:187], v[212:215], v[88:91]
	v_mfma_f32_16x16x32_bf16 v[92:95], v[188:191], v[212:215], v[92:95]
	s_cmp_eq_u32 s21, 0
	s_cbranch_scc0 .Lg1_hi5
	s_setprio 0
.Lg1_hi5:
	v_mfma_f32_16x16x32_bf16 v[96:99], v[176:179], v[216:219], v[96:99]
	v_mfma_f32_16x16x32_bf16 v[100:103], v[180:183], v[216:219], v[100:103]
	v_mfma_f32_16x16x32_bf16 v[104:107], v[184:187], v[216:219], v[104:107]
	v_mfma_f32_16x16x32_bf16 v[108:111], v[188:191], v[216:219], v[108:111]
	v_mfma_f32_16x16x32_bf16 v[112:115], v[176:179], v[220:223], v[112:115]
	v_mfma_f32_16x16x32_bf16 v[116:119], v[180:183], v[220:223], v[116:119]
	v_mfma_f32_16x16x32_bf16 v[120:123], v[184:187], v[220:223], v[120:123]
	v_mfma_f32_16x16x32_bf16 v[124:127], v[188:191], v[220:223], v[124:127]
	s_branch .Lg1_epi

; #define LWRITE(S, buf) do { bf16_t* sA_ = sbase + (buf) * BUF; bf16_t* sB_ = sA_ + 256 * PITCH; \
;     _Pragma("unroll") for (int i_ = 0; i_ < 4; ++i_) *(u32x4*)(sA_ + (sr + i_ * 64) * PITCH + scv * 8) = ra[S][i_]; \
;     _Pragma("unroll") for (int i_ = 0; i_ < 2; ++i_) *(u32x4*)(sB_ + (sr + i_ * 64) * PITCH + scv * 8) = rb[S][i_]; } while (0)
; template <class Epi>
; DI void gemm_tile(char* smem, const bf16_t* __restrict__ A0, int lda0, int ksplit, const bf16_t* __restrict__ A1, int lda1,
;                   const bf16_t* __restrict__ Bt, int K, int row0, int col0, const Epi& epi, int tid) {
;     ...
;   const int lane = tid & 63, wid = tid >> 6, wr = wid >> 1, wc = wid & 1, fr = lane & 15, fq = lane >> 4;
;   f32x4 acc[8][4];
; #pragma unroll
;   for (int m = 0; m < 8; ++m)
; #pragma unroll
;     for (int n = 0; n < 4; ++n) acc[m][n] = (f32x4){0.f, 0.f, 0.f, 0.f};
;   u32x4 ra[2][4], rb[2][2];
;   const int nk = K / BK;
;   const int sr = tid >> 2, scv = tid & 3;
;     ...
;   __syncthreads();
;   {
;     const int last = nk - 1;
;     GLOAD(0, 0);
;     __builtin_amdgcn_sched_barrier(0);
;     GLOAD(1, 1);
;     __builtin_amdgcn_sched_barrier(0);
;     LWRITE(0, 0);
;     __builtin_amdgcn_sched_barrier(0);
;     GLOAD(0, (2 < last ? 2 : last));
;     __builtin_amdgcn_sched_barrier(0);
;     __syncthreads();
; template <class Epi>
; DI void gemm_phase(char* smem, const bf16_t* A0, int lda0, int ksplit, const bf16_t* A1, int lda1, const bf16_t* Bt, int K, int nN, const Epi& epi, int tid) {
;     ...
;     const int x = blockIdx.x & 7, l = blockIdx.x >> 3, L = G >> 3, per = 8 * nN, tot = 2 * per;
;     for (int q = l; q < tot; q += L) { const int rgl = q / per, rem = q % per, ct = rem >> 3, rt = (x * 2 + rgl) * 8 + (rem & 7);
;       gemm_tile(smem, A0, lda0, ksplit, A1, lda1, Bt, K, rt * 256, ct * 128, epi, tid); }
.Lg3a_tile:
	s_cmpk_ge_u32 s15, 64
	s_cbranch_scc1 .Lg3a_done
	s_cmpk_ge_u32 s15, 32
	s_cselect_b32 s27, 1, 0
	s_cselect_b32 s26, 32, 0
	s_sub_u32 s26, s15, s26
	s_add_u32 s27, s27, s101
	s_lshl_b32 s27, s27, 3
	s_and_b32 s29, s26, 7
	s_add_u32 s29, s29, s27
	s_lshl_b32 s29, s29, 8
	s_lshr_b32 s28, s26, 3
	s_lshl_b32 s28, s28, 7
	s_mul_i32 s27, s29, 512
	s_add_u32 s27, s27, 0x1ea00000
	s_add_u32 s0, s92, s27
	s_addc_u32 s1, s93, 0
	s_mul_i32 s27, s28, 128
	s_add_u32 s27, s27, 0x34a0000
	s_add_u32 s2, s92, s27
	s_addc_u32 s3, s93, 0
	s_waitcnt lgkmcnt(0)
	s_barrier
	s_mov_b32 s99, 0
	s_mov_b32 s30, 0
	s_add_u32 s26, s30, s100
	s_add_u32 m0, s26, 0
	s_nop 0
	global_load_lds_dwordx4 v224, s[0:1]
	s_add_u32 m0, s26, 4096
	s_nop 0
	global_load_lds_dwordx4 v225, s[0:1]
	s_add_u32 m0, s26, 8192
	s_nop 0
	global_load_lds_dwordx4 v226, s[0:1]
	s_add_u32 m0, s26, 12288
	s_nop 0
	global_load_lds_dwordx4 v227, s[0:1]
	s_add_u32 m0, s26, 16384
	s_nop 0
	global_load_lds_dwordx4 v228, s[2:3]
	s_add_u32 m0, s26, 20480
	s_nop 0
	global_load_lds_dwordx4 v229, s[2:3]
	s_add_u32 s0, s0, 64
	s_addc_u32 s1, s1, 0
	s_add_u32 s2, s2, 64
	s_addc_u32 s3, s3, 0
	s_add_u32 s99, s99, 1
	s_add_u32 s30, s30, 24576
	s_cmp_eq_u32 s30, 73728
	s_cselect_b32 s30, 0, s30
	s_add_u32 s26, s30, s100
	s_add_u32 m0, s26, 0
	s_nop 0
	global_load_lds_dwordx4 v224, s[0:1]
	s_add_u32 m0, s26, 4096
	s_nop 0
	global_load_lds_dwordx4 v225, s[0:1]
	s_add_u32 m0, s26, 8192
	s_nop 0
	global_load_lds_dwordx4 v226, s[0:1]
	s_add_u32 m0, s26, 12288
	s_nop 0
	global_load_lds_dwordx4 v227, s[0:1]
	s_add_u32 m0, s26, 16384
	s_nop 0
	global_load_lds_dwordx4 v228, s[2:3]
	s_add_u32 m0, s26, 20480
	s_nop 0
	global_load_lds_dwordx4 v229, s[2:3]
	s_add_u32 s0, s0, 64
	s_addc_u32 s1, s1, 0
	s_add_u32 s2, s2, 64
	s_addc_u32 s3, s3, 0
	s_add_u32 s99, s99, 1
	s_add_u32 s30, s30, 24576
	s_cmp_eq_u32 s30, 73728
	s_cselect_b32 s30, 0, s30
	v_mov_b32_e32 v0, 0
	v_mov_b32_e32 v1, 0
	v_mov_b32_e32 v2, 0
	v_mov_b32_e32 v3, 0
	v_mov_b32_e32 v4, 0
	v_mov_b32_e32 v5, 0
	v_mov_b32_e32 v6, 0
	v_mov_b32_e32 v7, 0
	v_mov_b32_e32 v8, 0
	v_mov_b32_e32 v9, 0
	v_mov_b32_e32 v10, 0
	v_mov_b32_e32 v11, 0
	v_mov_b32_e32 v12, 0
	v_mov_b32_e32 v13, 0
	v_mov_b32_e32 v14, 0
	v_mov_b32_e32 v15, 0
	v_mov_b32_e32 v16, 0
	v_mov_b32_e32 v17, 0
	v_mov_b32_e32 v18, 0
	v_mov_b32_e32 v19, 0
	v_mov_b32_e32 v20, 0
	v_mov_b32_e32 v21, 0
	v_mov_b32_e32 v22, 0
	v_mov_b32_e32 v23, 0
	v_mov_b32_e32 v24, 0
	v_mov_b32_e32 v25, 0
	v_mov_b32_e32 v26, 0
	v_mov_b32_e32 v27, 0
	v_mov_b32_e32 v28, 0
	v_mov_b32_e32 v29, 0
	v_mov_b32_e32 v30, 0
	v_mov_b32_e32 v31, 0
	v_mov_b32_e32 v32, 0
	v_mov_b32_e32 v33, 0
	v_mov_b32_e32 v34, 0
	v_mov_b32_e32 v35, 0
	v_mov_b32_e32 v36, 0
	v_mov_b32_e32 v37, 0
	v_mov_b32_e32 v38, 0
	v_mov_b32_e32 v39, 0
	v_mov_b32_e32 v40, 0
	v_mov_b32_e32 v41, 0
	v_mov_b32_e32 v42, 0
	v_mov_b32_e32 v43, 0
	v_mov_b32_e32 v44, 0
	v_mov_b32_e32 v45, 0
	v_mov_b32_e32 v46, 0
	v_mov_b32_e32 v47, 0
	v_mov_b32_e32 v48, 0
	v_mov_b32_e32 v49, 0
	v_mov_b32_e32 v50, 0
	v_mov_b32_e32 v51, 0
	v_mov_b32_e32 v52, 0
	v_mov_b32_e32 v53, 0
	v_mov_b32_e32 v54, 0
	v_mov_b32_e32 v55, 0
	v_mov_b32_e32 v56, 0
	v_mov_b32_e32 v57, 0
	v_mov_b32_e32 v58, 0
	v_mov_b32_e32 v59, 0
	v_mov_b32_e32 v60, 0
	v_mov_b32_e32 v61, 0
	v_mov_b32_e32 v62, 0
	v_mov_b32_e32 v63, 0
	v_mov_b32_e32 v64, 0
	v_mov_b32_e32 v65, 0
	v_mov_b32_e32 v66, 0
	v_mov_b32_e32 v67, 0
	v_mov_b32_e32 v68, 0
	v_mov_b32_e32 v69, 0
	v_mov_b32_e32 v70, 0
	v_mov_b32_e32 v71, 0
	v_mov_b32_e32 v72, 0
	v_mov_b32_e32 v73, 0
	v_mov_b32_e32 v74, 0
	v_mov_b32_e32 v75, 0
	v_mov_b32_e32 v76, 0
	v_mov_b32_e32 v77, 0
	v_mov_b32_e32 v78, 0
	v_mov_b32_e32 v79, 0
	v_mov_b32_e32 v80, 0
	v_mov_b32_e32 v81, 0
	v_mov_b32_e32 v82, 0
	v_mov_b32_e32 v83, 0
	v_mov_b32_e32 v84, 0
	v_mov_b32_e32 v85, 0
	v_mov_b32_e32 v86, 0
	v_mov_b32_e32 v87, 0
	v_mov_b32_e32 v88, 0
	v_mov_b32_e32 v89, 0
	v_mov_b32_e32 v90, 0
	v_mov_b32_e32 v91, 0
	v_mov_b32_e32 v92, 0
	v_mov_b32_e32 v93, 0
	v_mov_b32_e32 v94, 0
	v_mov_b32_e32 v95, 0
	v_mov_b32_e32 v96, 0
	v_mov_b32_e32 v97, 0
	v_mov_b32_e32 v98, 0
	v_mov_b32_e32 v99, 0
	v_mov_b32_e32 v100, 0
	v_mov_b32_e32 v101, 0
	v_mov_b32_e32 v102, 0
	v_mov_b32_e32 v103, 0
	v_mov_b32_e32 v104, 0
	v_mov_b32_e32 v105, 0
	v_mov_b32_e32 v106, 0
	v_mov_b32_e32 v107, 0
	v_mov_b32_e32 v108, 0
	v_mov_b32_e32 v109, 0
	v_mov_b32_e32 v110, 0
	v_mov_b32_e32 v111, 0
	v_mov_b32_e32 v112, 0
	v_mov_b32_e32 v113, 0
	v_mov_b32_e32 v114, 0
	v_mov_b32_e32 v115, 0
	v_mov_b32_e32 v116, 0
	v_mov_b32_e32 v117, 0
	v_mov_b32_e32 v118, 0
	v_mov_b32_e32 v119, 0
	v_mov_b32_e32 v120, 0
	v_mov_b32_e32 v121, 0
	v_mov_b32_e32 v122, 0
	v_mov_b32_e32 v123, 0
	v_mov_b32_e32 v124, 0
	v_mov_b32_e32 v125, 0
	v_mov_b32_e32 v126, 0
	v_mov_b32_e32 v127, 0
	s_mov_b32 s98, 0
	s_mov_b32 s31, 24576
	s_waitcnt vmcnt(6)
	s_barrier
; #define LWRITE(S, buf) do { bf16_t* sA_ = sbase + (buf) * BUF; bf16_t* sB_ = sA_ + 256 * PITCH; \
;     _Pragma("unroll") for (int i_ = 0; i_ < 4; ++i_) *(u32x4*)(sA_ + (sr + i_ * 64) * PITCH + scv * 8) = ra[S][i_]; \
;     _Pragma("unroll") for (int i_ = 0; i_ < 2; ++i_) *(u32x4*)(sB_ + (sr + i_ * 64) * PITCH + scv * 8) = rb[S][i_]; } while (0)
; template <class Epi>
; DI void gemm_tile(char* smem, const bf16_t* __restrict__ A0, int lda0, int ksplit, const bf16_t* __restrict__ A1, int lda1,
;                   const bf16_t* __restrict__ Bt, int K, int row0, int col0, const Epi& epi, int tid) {
;     ...
;   __syncthreads();
;   {
;     const int last = nk - 1;
;     GLOAD(0, 0);
;     __builtin_amdgcn_sched_barrier(0);
;     GLOAD(1, 1);
;     __builtin_amdgcn_sched_barrier(0);
;     LWRITE(0, 0);
;     __builtin_amdgcn_sched_barrier(0);
;     GLOAD(0, (2 < last ? 2 : last));
;     __builtin_amdgcn_sched_barrier(0);
;     __syncthreads();
;     for (int kt = 0; kt < nk; kt += 2) {
;       LWRITE(1, 1);
;       __builtin_amdgcn_sched_barrier(0);
;       GLOAD(1, (kt + 3 < last ? kt + 3 : last));
;       __builtin_amdgcn_sched_barrier(0);
;       COMPUTE(0);
;       __syncthreads();
;       LWRITE(0, 0);
;       __builtin_amdgcn_sched_barrier(0);
;       GLOAD(0, (kt + 4 < last ? kt + 4 : last));
;       __builtin_amdgcn_sched_barrier(0);
;       COMPUTE(1);
;       __syncthreads();
;     }
	ds_read_b128 v[128:131], v231 offset:0
	ds_read_b128 v[132:135], v231 offset:1024
	ds_read_b128 v[136:139], v231 offset:2048
	ds_read_b128 v[140:143], v231 offset:3072
	ds_read_b128 v[144:147], v230 offset:0
	ds_read_b128 v[148:151], v230 offset:1024
	ds_read_b128 v[152:155], v230 offset:2048
	ds_read_b128 v[156:159], v230 offset:3072
	ds_read_b128 v[160:163], v230 offset:4096
	ds_read_b128 v[164:167], v230 offset:5120
	ds_read_b128 v[168:171], v230 offset:6144
	ds_read_b128 v[172:175], v230 offset:7168
	s_waitcnt vmcnt(0)
	s_waitcnt lgkmcnt(0)
	s_barrier
	v_add_u32_e32 v232, s31, v230
	v_add_u32_e32 v233, s31, v231
	s_setprio 1
	v_mfma_f32_16x16x32_bf16 v[0:3], v[128:131], v[144:147], v[0:3]
	v_mfma_f32_16x16x32_bf16 v[4:7], v[132:135], v[144:147], v[4:7]
	v_mfma_f32_16x16x32_bf16 v[8:11], v[136:139], v[144:147], v[8:11]
	v_mfma_f32_16x16x32_bf16 v[12:15], v[140:143], v[144:147], v[12:15]
	ds_read_b128 v[176:179], v233 offset:0
	ds_read_b128 v[180:183], v233 offset:1024
	v_mfma_f32_16x16x32_bf16 v[16:19], v[128:131], v[148:151], v[16:19]
	v_mfma_f32_16x16x32_bf16 v[20:23], v[132:135], v[148:151], v[20:23]
	v_mfma_f32_16x16x32_bf16 v[24:27], v[136:139], v[148:151], v[24:27]
	v_mfma_f32_16x16x32_bf16 v[28:31], v[140:143], v[148:151], v[28:31]
	ds_read_b128 v[184:187], v233 offset:2048
	ds_read_b128 v[188:191], v233 offset:3072
	v_mfma_f32_16x16x32_bf16 v[32:35], v[128:131], v[152:155], v[32:35]
	v_mfma_f32_16x16x32_bf16 v[36:39], v[132:135], v[152:155], v[36:39]
	v_mfma_f32_16x16x32_bf16 v[40:43], v[136:139], v[152:155], v[40:43]
	v_mfma_f32_16x16x32_bf16 v[44:47], v[140:143], v[152:155], v[44:47]
	ds_read_b128 v[192:195], v232 offset:0
	ds_read_b128 v[196:199], v232 offset:1024
	v_mfma_f32_16x16x32_bf16 v[48:51], v[128:131], v[156:159], v[48:51]
	v_mfma_f32_16x16x32_bf16 v[52:55], v[132:135], v[156:159], v[52:55]
	v_mfma_f32_16x16x32_bf16 v[56:59], v[136:139], v[156:159], v[56:59]
	v_mfma_f32_16x16x32_bf16 v[60:63], v[140:143], v[156:159], v[60:63]
	ds_read_b128 v[200:203], v232 offset:2048
	ds_read_b128 v[204:207], v232 offset:3072
	v_mfma_f32_16x16x32_bf16 v[64:67], v[128:131], v[160:163], v[64:67]
	v_mfma_f32_16x16x32_bf16 v[68:71], v[132:135], v[160:163], v[68:71]
	v_mfma_f32_16x16x32_bf16 v[72:75], v[136:139], v[160:163], v[72:75]
	v_mfma_f32_16x16x32_bf16 v[76:79], v[140:143], v[160:163], v[76:79]
	ds_read_b128 v[208:211], v232 offset:4096
	v_mfma_f32_16x16x32_bf16 v[80:83], v[128:131], v[164:167], v[80:83]
	v_mfma_f32_16x16x32_bf16 v[84:87], v[132:135], v[164:167], v[84:87]
	v_mfma_f32_16x16x32_bf16 v[88:91], v[136:139], v[164:167], v[88:91]
	v_mfma_f32_16x16x32_bf16 v[92:95], v[140:143], v[164:167], v[92:95]
	ds_read_b128 v[212:215], v232 offset:5120
	s_cmp_eq_u32 s25, 0
	s_cbranch_scc0 .Lg3a_hi0
	s_setprio 0
.Lg3a_hi0:
	v_mfma_f32_16x16x32_bf16 v[96:99], v[128:131], v[168:171], v[96:99]
	v_mfma_f32_16x16x32_bf16 v[100:103], v[132:135], v[168:171], v[100:103]
	v_mfma_f32_16x16x32_bf16 v[104:107], v[136:139], v[168:171], v[104:107]
	v_mfma_f32_16x16x32_bf16 v[108:111], v[140:143], v[168:171], v[108:111]
	ds_read_b128 v[216:219], v232 offset:6144
	s_add_u32 s31, s31, 24576
	s_cmp_eq_u32 s31, 73728
	s_cselect_b32 s31, 0, s31
	v_mfma_f32_16x16x32_bf16 v[112:115], v[128:131], v[172:175], v[112:115]
	v_mfma_f32_16x16x32_bf16 v[116:119], v[132:135], v[172:175], v[116:119]
	v_mfma_f32_16x16x32_bf16 v[120:123], v[136:139], v[172:175], v[120:123]
	v_mfma_f32_16x16x32_bf16 v[124:127], v[140:143], v[172:175], v[124:127]
	ds_read_b128 v[220:223], v232 offset:7168
	s_waitcnt lgkmcnt(0)
	s_barrier
	s_setprio 1
	v_mfma_f32_16x16x32_bf16 v[0:3], v[176:179], v[192:195], v[0:3]
	v_mfma_f32_16x16x32_bf16 v[4:7], v[180:183], v[192:195], v[4:7]
	v_mfma_f32_16x16x32_bf16 v[8:11], v[184:187], v[192:195], v[8:11]
	v_mfma_f32_16x16x32_bf16 v[12:15], v[188:191], v[192:195], v[12:15]
	v_mfma_f32_16x16x32_bf16 v[16:19], v[176:179], v[196:199], v[16:19]
	v_mfma_f32_16x16x32_bf16 v[20:23], v[180:183], v[196:199], v[20:23]
	v_mfma_f32_16x16x32_bf16 v[24:27], v[184:187], v[196:199], v[24:27]
	v_mfma_f32_16x16x32_bf16 v[28:31], v[188:191], v[196:199], v[28:31]
	v_mfma_f32_16x16x32_bf16 v[32:35], v[176:179], v[200:203], v[32:35]
	v_mfma_f32_16x16x32_bf16 v[36:39], v[180:183], v[200:203], v[36:39]
	v_mfma_f32_16x16x32_bf16 v[40:43], v[184:187], v[200:203], v[40:43]
	v_mfma_f32_16x16x32_bf16 v[44:47], v[188:191], v[200:203], v[44:47]
	v_mfma_f32_16x16x32_bf16 v[48:51], v[176:179], v[204:207], v[48:51]
	v_mfma_f32_16x16x32_bf16 v[52:55], v[180:183], v[204:207], v[52:55]
	v_mfma_f32_16x16x32_bf16 v[56:59], v[184:187], v[204:207], v[56:59]
	v_mfma_f32_16x16x32_bf16 v[60:63], v[188:191], v[204:207], v[60:63]
	v_mfma_f32_16x16x32_bf16 v[64:67], v[176:179], v[208:211], v[64:67]
	v_mfma_f32_16x16x32_bf16 v[68:71], v[180:183], v[208:211], v[68:71]
	v_mfma_f32_16x16x32_bf16 v[72:75], v[184:187], v[208:211], v[72:75]
	v_mfma_f32_16x16x32_bf16 v[76:79], v[188:191], v[208:211], v[76:79]
	v_mfma_f32_16x16x32_bf16 v[80:83], v[176:179], v[212:215], v[80:83]
	v_mfma_f32_16x16x32_bf16 v[84:87], v[180:183], v[212:215], v[84:87]
	v_mfma_f32_16x16x32_bf16 v[88:91], v[184:187], v[212:215], v[88:91]
	v_mfma_f32_16x16x32_bf16 v[92:95], v[188:191], v[212:215], v[92:95]
	s_cmp_eq_u32 s25, 0
	s_cbranch_scc0 .Lg3a_hi1
	s_setprio 0

; #define LWRITE(S, buf) do { bf16_t* sA_ = sbase + (buf) * BUF; bf16_t* sB_ = sA_ + 256 * PITCH; \
;     _Pragma("unroll") for (int i_ = 0; i_ < 4; ++i_) *(u32x4*)(sA_ + (sr + i_ * 64) * PITCH + scv * 8) = ra[S][i_]; \
;     _Pragma("unroll") for (int i_ = 0; i_ < 2; ++i_) *(u32x4*)(sB_ + (sr + i_ * 64) * PITCH + scv * 8) = rb[S][i_]; } while (0)
; template <class Epi>
; DI void gemm_tile(char* smem, const bf16_t* __restrict__ A0, int lda0, int ksplit, const bf16_t* __restrict__ A1, int lda1,
;                   const bf16_t* __restrict__ Bt, int K, int row0, int col0, const Epi& epi, int tid) {
;     ...
;   const int lane = tid & 63, wid = tid >> 6, wr = wid >> 1, wc = wid & 1, fr = lane & 15, fq = lane >> 4;
;   f32x4 acc[8][4];
; #pragma unroll
;   for (int m = 0; m < 8; ++m)
; #pragma unroll
;     for (int n = 0; n < 4; ++n) acc[m][n] = (f32x4){0.f, 0.f, 0.f, 0.f};
;   u32x4 ra[2][4], rb[2][2];
;   const int nk = K / BK;
;   const int sr = tid >> 2, scv = tid & 3;
;     ...
;   __syncthreads();
;   {
;     const int last = nk - 1;
;     GLOAD(0, 0);
;     __builtin_amdgcn_sched_barrier(0);
;     GLOAD(1, 1);
;     __builtin_amdgcn_sched_barrier(0);
;     LWRITE(0, 0);
;     __builtin_amdgcn_sched_barrier(0);
;     GLOAD(0, (2 < last ? 2 : last));
;     __builtin_amdgcn_sched_barrier(0);
;     __syncthreads();
; template <class Epi>
; DI void gemm_phase(char* smem, const bf16_t* A0, int lda0, int ksplit, const bf16_t* A1, int lda1, const bf16_t* Bt, int K, int nN, const Epi& epi, int tid) {
;     ...
;     const int x = blockIdx.x & 7, l = blockIdx.x >> 3, L = G >> 3, per = 8 * nN, tot = 2 * per;
;     for (int q = l; q < tot; q += L) { const int rgl = q / per, rem = q % per, ct = rem >> 3, rt = (x * 2 + rgl) * 8 + (rem & 7);
;       gemm_tile(smem, A0, lda0, ksplit, A1, lda1, Bt, K, rt * 256, ct * 128, epi, tid); }
.Lg3b_tile:
	s_cmpk_ge_u32 s15, 64
	s_cbranch_scc1 .Lg3b_done
	s_cmpk_ge_u32 s15, 32
	s_cselect_b32 s27, 1, 0
	s_cselect_b32 s26, 32, 0
	s_sub_u32 s26, s15, s26
	s_add_u32 s27, s27, s101
	s_lshl_b32 s27, s27, 3
	s_and_b32 s29, s26, 7
	s_add_u32 s29, s29, s27
	s_lshl_b32 s29, s29, 8
	s_lshr_b32 s28, s26, 3
	s_lshl_b32 s28, s28, 7
	s_mul_i32 s27, s29, 512
	s_add_u32 s27, s27, 0x1ea00000
	s_add_u32 s0, s92, s27
	s_addc_u32 s1, s93, 0
	s_mul_i32 s27, s28, 128
	s_add_u32 s27, s27, 0x34b0000
	s_add_u32 s2, s92, s27
	s_addc_u32 s3, s93, 0
	s_waitcnt lgkmcnt(0)
	s_barrier
	s_mov_b32 s99, 0
	s_mov_b32 s30, 0
	s_add_u32 s26, s30, s100
	s_add_u32 m0, s26, 0
	s_nop 0
	global_load_lds_dwordx4 v224, s[0:1]
	s_add_u32 m0, s26, 4096
	s_nop 0
	global_load_lds_dwordx4 v225, s[0:1]
	s_add_u32 m0, s26, 8192
	s_nop 0
	global_load_lds_dwordx4 v226, s[0:1]
	s_add_u32 m0, s26, 12288
	s_nop 0
	global_load_lds_dwordx4 v227, s[0:1]
	s_add_u32 m0, s26, 16384
	s_nop 0
	global_load_lds_dwordx4 v228, s[2:3]
	s_add_u32 m0, s26, 20480
	s_nop 0
	global_load_lds_dwordx4 v229, s[2:3]
	s_add_u32 s0, s0, 64
	s_addc_u32 s1, s1, 0
	s_add_u32 s2, s2, 64
	s_addc_u32 s3, s3, 0
	s_add_u32 s99, s99, 1
	s_add_u32 s30, s30, 24576
	s_cmp_eq_u32 s30, 73728
	s_cselect_b32 s30, 0, s30
	s_add_u32 s26, s30, s100
	s_add_u32 m0, s26, 0
	s_nop 0
	global_load_lds_dwordx4 v224, s[0:1]
	s_add_u32 m0, s26, 4096
	s_nop 0
	global_load_lds_dwordx4 v225, s[0:1]
	s_add_u32 m0, s26, 8192
	s_nop 0
	global_load_lds_dwordx4 v226, s[0:1]
	s_add_u32 m0, s26, 12288
	s_nop 0
	global_load_lds_dwordx4 v227, s[0:1]
	s_add_u32 m0, s26, 16384
	s_nop 0
	global_load_lds_dwordx4 v228, s[2:3]
	s_add_u32 m0, s26, 20480
	s_nop 0
	global_load_lds_dwordx4 v229, s[2:3]
	s_add_u32 s0, s0, 64
	s_addc_u32 s1, s1, 0
	s_add_u32 s2, s2, 64
	s_addc_u32 s3, s3, 0
	s_add_u32 s99, s99, 1
	s_add_u32 s30, s30, 24576
	s_cmp_eq_u32 s30, 73728
	s_cselect_b32 s30, 0, s30
	v_mov_b32_e32 v0, 0
	v_mov_b32_e32 v1, 0
	v_mov_b32_e32 v2, 0
	v_mov_b32_e32 v3, 0
	v_mov_b32_e32 v4, 0
	v_mov_b32_e32 v5, 0
	v_mov_b32_e32 v6, 0
	v_mov_b32_e32 v7, 0
	v_mov_b32_e32 v8, 0
	v_mov_b32_e32 v9, 0
	v_mov_b32_e32 v10, 0
	v_mov_b32_e32 v11, 0
	v_mov_b32_e32 v12, 0
	v_mov_b32_e32 v13, 0
	v_mov_b32_e32 v14, 0
	v_mov_b32_e32 v15, 0
	v_mov_b32_e32 v16, 0
	v_mov_b32_e32 v17, 0
	v_mov_b32_e32 v18, 0
	v_mov_b32_e32 v19, 0
	v_mov_b32_e32 v20, 0
	v_mov_b32_e32 v21, 0
	v_mov_b32_e32 v22, 0
	v_mov_b32_e32 v23, 0
	v_mov_b32_e32 v24, 0
	v_mov_b32_e32 v25, 0
	v_mov_b32_e32 v26, 0
	v_mov_b32_e32 v27, 0
	v_mov_b32_e32 v28, 0
	v_mov_b32_e32 v29, 0
	v_mov_b32_e32 v30, 0
	v_mov_b32_e32 v31, 0
	v_mov_b32_e32 v32, 0
	v_mov_b32_e32 v33, 0
	v_mov_b32_e32 v34, 0
	v_mov_b32_e32 v35, 0
	v_mov_b32_e32 v36, 0
	v_mov_b32_e32 v37, 0
	v_mov_b32_e32 v38, 0
	v_mov_b32_e32 v39, 0
	v_mov_b32_e32 v40, 0
	v_mov_b32_e32 v41, 0
	v_mov_b32_e32 v42, 0
	v_mov_b32_e32 v43, 0
	v_mov_b32_e32 v44, 0
	v_mov_b32_e32 v45, 0
	v_mov_b32_e32 v46, 0
	v_mov_b32_e32 v47, 0
	v_mov_b32_e32 v48, 0
	v_mov_b32_e32 v49, 0
	v_mov_b32_e32 v50, 0
	v_mov_b32_e32 v51, 0
	v_mov_b32_e32 v52, 0
	v_mov_b32_e32 v53, 0
	v_mov_b32_e32 v54, 0
	v_mov_b32_e32 v55, 0
	v_mov_b32_e32 v56, 0
	v_mov_b32_e32 v57, 0
	v_mov_b32_e32 v58, 0
	v_mov_b32_e32 v59, 0
	v_mov_b32_e32 v60, 0
	v_mov_b32_e32 v61, 0
	v_mov_b32_e32 v62, 0
	v_mov_b32_e32 v63, 0
	v_mov_b32_e32 v64, 0
	v_mov_b32_e32 v65, 0
	v_mov_b32_e32 v66, 0
	v_mov_b32_e32 v67, 0
	v_mov_b32_e32 v68, 0
	v_mov_b32_e32 v69, 0
	v_mov_b32_e32 v70, 0
	v_mov_b32_e32 v71, 0
	v_mov_b32_e32 v72, 0
	v_mov_b32_e32 v73, 0
	v_mov_b32_e32 v74, 0
	v_mov_b32_e32 v75, 0
	v_mov_b32_e32 v76, 0
	v_mov_b32_e32 v77, 0
	v_mov_b32_e32 v78, 0
	v_mov_b32_e32 v79, 0
	v_mov_b32_e32 v80, 0
	v_mov_b32_e32 v81, 0
	v_mov_b32_e32 v82, 0
	v_mov_b32_e32 v83, 0
	v_mov_b32_e32 v84, 0
	v_mov_b32_e32 v85, 0
	v_mov_b32_e32 v86, 0
	v_mov_b32_e32 v87, 0
	v_mov_b32_e32 v88, 0
	v_mov_b32_e32 v89, 0
	v_mov_b32_e32 v90, 0
	v_mov_b32_e32 v91, 0
	v_mov_b32_e32 v92, 0
	v_mov_b32_e32 v93, 0
	v_mov_b32_e32 v94, 0
	v_mov_b32_e32 v95, 0
	v_mov_b32_e32 v96, 0
	v_mov_b32_e32 v97, 0
	v_mov_b32_e32 v98, 0
	v_mov_b32_e32 v99, 0
	v_mov_b32_e32 v100, 0
	v_mov_b32_e32 v101, 0
	v_mov_b32_e32 v102, 0
	v_mov_b32_e32 v103, 0
	v_mov_b32_e32 v104, 0
	v_mov_b32_e32 v105, 0
	v_mov_b32_e32 v106, 0
	v_mov_b32_e32 v107, 0
	v_mov_b32_e32 v108, 0
	v_mov_b32_e32 v109, 0
	v_mov_b32_e32 v110, 0
	v_mov_b32_e32 v111, 0
	v_mov_b32_e32 v112, 0
	v_mov_b32_e32 v113, 0
	v_mov_b32_e32 v114, 0
	v_mov_b32_e32 v115, 0
	v_mov_b32_e32 v116, 0
	v_mov_b32_e32 v117, 0
	v_mov_b32_e32 v118, 0
	v_mov_b32_e32 v119, 0
	v_mov_b32_e32 v120, 0
	v_mov_b32_e32 v121, 0
	v_mov_b32_e32 v122, 0
	v_mov_b32_e32 v123, 0
	v_mov_b32_e32 v124, 0
	v_mov_b32_e32 v125, 0
	v_mov_b32_e32 v126, 0
	v_mov_b32_e32 v127, 0
	s_mov_b32 s98, 0
	s_mov_b32 s31, 24576
	s_waitcnt vmcnt(6)
	s_barrier
; #define LWRITE(S, buf) do { bf16_t* sA_ = sbase + (buf) * BUF; bf16_t* sB_ = sA_ + 256 * PITCH; \
;     _Pragma("unroll") for (int i_ = 0; i_ < 4; ++i_) *(u32x4*)(sA_ + (sr + i_ * 64) * PITCH + scv * 8) = ra[S][i_]; \
;     _Pragma("unroll") for (int i_ = 0; i_ < 2; ++i_) *(u32x4*)(sB_ + (sr + i_ * 64) * PITCH + scv * 8) = rb[S][i_]; } while (0)
; template <class Epi>
; DI void gemm_tile(char* smem, const bf16_t* __restrict__ A0, int lda0, int ksplit, const bf16_t* __restrict__ A1, int lda1,
;                   const bf16_t* __restrict__ Bt, int K, int row0, int col0, const Epi& epi, int tid) {
;     ...
;     for (int kt = 0; kt < nk; kt += 2) {
;       LWRITE(1, 1);
;       __builtin_amdgcn_sched_barrier(0);
;       GLOAD(1, (kt + 3 < last ? kt + 3 : last));
;       __builtin_amdgcn_sched_barrier(0);
;       COMPUTE(0);
	ds_read_b128 v[128:131], v231 offset:0
	ds_read_b128 v[132:135], v231 offset:1024
	ds_read_b128 v[136:139], v231 offset:2048
	ds_read_b128 v[140:143], v231 offset:3072
	ds_read_b128 v[144:147], v230 offset:0
	ds_read_b128 v[148:151], v230 offset:1024
	ds_read_b128 v[152:155], v230 offset:2048
	ds_read_b128 v[156:159], v230 offset:3072
	ds_read_b128 v[160:163], v230 offset:4096
	ds_read_b128 v[164:167], v230 offset:5120
	ds_read_b128 v[168:171], v230 offset:6144
	ds_read_b128 v[172:175], v230 offset:7168
	s_waitcnt vmcnt(0)
	s_waitcnt lgkmcnt(0)
	s_barrier
	v_add_u32_e32 v232, s31, v230
	v_add_u32_e32 v233, s31, v231
	s_setprio 1
	v_mfma_f32_16x16x32_bf16 v[0:3], v[128:131], v[144:147], v[0:3]
	v_mfma_f32_16x16x32_bf16 v[4:7], v[132:135], v[144:147], v[4:7]
	v_mfma_f32_16x16x32_bf16 v[8:11], v[136:139], v[144:147], v[8:11]
	v_mfma_f32_16x16x32_bf16 v[12:15], v[140:143], v[144:147], v[12:15]
	ds_read_b128 v[176:179], v233 offset:0
	ds_read_b128 v[180:183], v233 offset:1024
	v_mfma_f32_16x16x32_bf16 v[16:19], v[128:131], v[148:151], v[16:19]
	v_mfma_f32_16x16x32_bf16 v[20:23], v[132:135], v[148:151], v[20:23]
	v_mfma_f32_16x16x32_bf16 v[24:27], v[136:139], v[148:151], v[24:27]
	v_mfma_f32_16x16x32_bf16 v[28:31], v[140:143], v[148:151], v[28:31]
	ds_read_b128 v[184:187], v233 offset:2048
	ds_read_b128 v[188:191], v233 offset:3072
	v_mfma_f32_16x16x32_bf16 v[32:35], v[128:131], v[152:155], v[32:35]
	v_mfma_f32_16x16x32_bf16 v[36:39], v[132:135], v[152:155], v[36:39]
	v_mfma_f32_16x16x32_bf16 v[40:43], v[136:139], v[152:155], v[40:43]
	v_mfma_f32_16x16x32_bf16 v[44:47], v[140:143], v[152:155], v[44:47]
	ds_read_b128 v[192:195], v232 offset:0
	ds_read_b128 v[196:199], v232 offset:1024
	v_mfma_f32_16x16x32_bf16 v[48:51], v[128:131], v[156:159], v[48:51]
	v_mfma_f32_16x16x32_bf16 v[52:55], v[132:135], v[156:159], v[52:55]
	v_mfma_f32_16x16x32_bf16 v[56:59], v[136:139], v[156:159], v[56:59]
	v_mfma_f32_16x16x32_bf16 v[60:63], v[140:143], v[156:159], v[60:63]
	ds_read_b128 v[200:203], v232 offset:2048
	ds_read_b128 v[204:207], v232 offset:3072
	v_mfma_f32_16x16x32_bf16 v[64:67], v[128:131], v[160:163], v[64:67]
	v_mfma_f32_16x16x32_bf16 v[68:71], v[132:135], v[160:163], v[68:71]
	v_mfma_f32_16x16x32_bf16 v[72:75], v[136:139], v[160:163], v[72:75]
	v_mfma_f32_16x16x32_bf16 v[76:79], v[140:143], v[160:163], v[76:79]
	ds_read_b128 v[208:211], v232 offset:4096
	v_mfma_f32_16x16x32_bf16 v[80:83], v[128:131], v[164:167], v[80:83]
	v_mfma_f32_16x16x32_bf16 v[84:87], v[132:135], v[164:167], v[84:87]
	v_mfma_f32_16x16x32_bf16 v[88:91], v[136:139], v[164:167], v[88:91]
	v_mfma_f32_16x16x32_bf16 v[92:95], v[140:143], v[164:167], v[92:95]
	ds_read_b128 v[212:215], v232 offset:5120
	s_cmp_eq_u32 s25, 0
	s_cbranch_scc0 .Lg3b_hi0
	s_setprio 0

; #define LWRITE(S, buf) do { bf16_t* sA_ = sbase + (buf) * BUF; bf16_t* sB_ = sA_ + 256 * PITCH; \
;     _Pragma("unroll") for (int i_ = 0; i_ < 4; ++i_) *(u32x4*)(sA_ + (sr + i_ * 64) * PITCH + scv * 8) = ra[S][i_]; \
;     _Pragma("unroll") for (int i_ = 0; i_ < 2; ++i_) *(u32x4*)(sB_ + (sr + i_ * 64) * PITCH + scv * 8) = rb[S][i_]; } while (0)
; template <class Epi>
; DI void gemm_tile(char* smem, const bf16_t* __restrict__ A0, int lda0, int ksplit, const bf16_t* __restrict__ A1, int lda1,
;                   const bf16_t* __restrict__ Bt, int K, int row0, int col0, const Epi& epi, int tid) {
;     ...
;   const int lane = tid & 63, wid = tid >> 6, wr = wid >> 1, wc = wid & 1, fr = lane & 15, fq = lane >> 4;
;   f32x4 acc[8][4];
; #pragma unroll
;   for (int m = 0; m < 8; ++m)
; #pragma unroll
;     for (int n = 0; n < 4; ++n) acc[m][n] = (f32x4){0.f, 0.f, 0.f, 0.f};
;   u32x4 ra[2][4], rb[2][2];
;   const int nk = K / BK;
;   const int sr = tid >> 2, scv = tid & 3;
;     ...
;   __syncthreads();
;   {
;     const int last = nk - 1;
;     GLOAD(0, 0);
;     __builtin_amdgcn_sched_barrier(0);
;     GLOAD(1, 1);
;     __builtin_amdgcn_sched_barrier(0);
;     LWRITE(0, 0);
;     __builtin_amdgcn_sched_barrier(0);
;     GLOAD(0, (2 < last ? 2 : last));
;     __builtin_amdgcn_sched_barrier(0);
;     __syncthreads();
; template <class Epi>
; DI void gemm_phase(char* smem, const bf16_t* A0, int lda0, int ksplit, const bf16_t* A1, int lda1, const bf16_t* Bt, int K, int nN, const Epi& epi, int tid) {
;     ...
;     const int x = blockIdx.x & 7, l = blockIdx.x >> 3, L = G >> 3, per = 8 * nN, tot = 2 * per;
;     for (int q = l; q < tot; q += L) { const int rgl = q / per, rem = q % per, ct = rem >> 3, rt = (x * 2 + rgl) * 8 + (rem & 7);
;       gemm_tile(smem, A0, lda0, ksplit, A1, lda1, Bt, K, rt * 256, ct * 128, epi, tid); }
.Lg3c_tile:
	s_cmpk_ge_u32 s15, 64
	s_cbranch_scc1 .Lg3c_done
	s_cmpk_ge_u32 s15, 32
	s_cselect_b32 s27, 1, 0
	s_cselect_b32 s26, 32, 0
	s_sub_u32 s26, s15, s26
	s_add_u32 s27, s27, s101
	s_lshl_b32 s27, s27, 3
	s_and_b32 s29, s26, 7
	s_add_u32 s29, s29, s27
	s_lshl_b32 s29, s29, 8
	s_lshr_b32 s28, s26, 3
	s_lshl_b32 s28, s28, 7
	s_mul_i32 s27, s29, 512
	s_add_u32 s27, s27, 0x1ea00080
	s_add_u32 s0, s92, s27
	s_addc_u32 s1, s93, 0
	s_mul_i32 s27, s28, 128
	s_add_u32 s27, s27, 0x34c0000
	s_add_u32 s2, s92, s27
	s_addc_u32 s3, s93, 0
	s_waitcnt lgkmcnt(0)
	s_barrier
	s_mov_b32 s99, 0
	s_mov_b32 s30, 0
	s_add_u32 s26, s30, s100
	s_add_u32 m0, s26, 0
	s_nop 0
	global_load_lds_dwordx4 v224, s[0:1]
	s_add_u32 m0, s26, 4096
	s_nop 0
	global_load_lds_dwordx4 v225, s[0:1]
	s_add_u32 m0, s26, 8192
	s_nop 0
	global_load_lds_dwordx4 v226, s[0:1]
	s_add_u32 m0, s26, 12288
	s_nop 0
	global_load_lds_dwordx4 v227, s[0:1]
	s_add_u32 m0, s26, 16384
	s_nop 0
	global_load_lds_dwordx4 v228, s[2:3]
	s_add_u32 m0, s26, 20480
	s_nop 0
	global_load_lds_dwordx4 v229, s[2:3]
	s_add_u32 s0, s0, 64
	s_addc_u32 s1, s1, 0
	s_add_u32 s2, s2, 64
	s_addc_u32 s3, s3, 0
	s_add_u32 s99, s99, 1
	s_add_u32 s30, s30, 24576
	s_cmp_eq_u32 s30, 73728
	s_cselect_b32 s30, 0, s30
	s_add_u32 s26, s30, s100
	s_add_u32 m0, s26, 0
	s_nop 0
	global_load_lds_dwordx4 v224, s[0:1]
	s_add_u32 m0, s26, 4096
	s_nop 0
	global_load_lds_dwordx4 v225, s[0:1]
	s_add_u32 m0, s26, 8192
	s_nop 0
	global_load_lds_dwordx4 v226, s[0:1]
	s_add_u32 m0, s26, 12288
	s_nop 0
	global_load_lds_dwordx4 v227, s[0:1]
	s_add_u32 m0, s26, 16384
	s_nop 0
	global_load_lds_dwordx4 v228, s[2:3]
	s_add_u32 m0, s26, 20480
	s_nop 0
	global_load_lds_dwordx4 v229, s[2:3]
	s_add_u32 s0, s0, 64
	s_addc_u32 s1, s1, 0
	s_add_u32 s2, s2, 64
	s_addc_u32 s3, s3, 0
	s_add_u32 s99, s99, 1
	s_add_u32 s30, s30, 24576
	s_cmp_eq_u32 s30, 73728
	s_cselect_b32 s30, 0, s30
	v_mov_b32_e32 v0, 0
	v_mov_b32_e32 v1, 0
	v_mov_b32_e32 v2, 0
	v_mov_b32_e32 v3, 0
	v_mov_b32_e32 v4, 0
	v_mov_b32_e32 v5, 0
	v_mov_b32_e32 v6, 0
	v_mov_b32_e32 v7, 0
	v_mov_b32_e32 v8, 0
	v_mov_b32_e32 v9, 0
	v_mov_b32_e32 v10, 0
	v_mov_b32_e32 v11, 0
	v_mov_b32_e32 v12, 0
	v_mov_b32_e32 v13, 0
	v_mov_b32_e32 v14, 0
	v_mov_b32_e32 v15, 0
	v_mov_b32_e32 v16, 0
	v_mov_b32_e32 v17, 0
	v_mov_b32_e32 v18, 0
	v_mov_b32_e32 v19, 0
	v_mov_b32_e32 v20, 0
	v_mov_b32_e32 v21, 0
	v_mov_b32_e32 v22, 0
	v_mov_b32_e32 v23, 0
	v_mov_b32_e32 v24, 0
	v_mov_b32_e32 v25, 0
	v_mov_b32_e32 v26, 0
	v_mov_b32_e32 v27, 0
	v_mov_b32_e32 v28, 0
	v_mov_b32_e32 v29, 0
	v_mov_b32_e32 v30, 0
	v_mov_b32_e32 v31, 0
	v_mov_b32_e32 v32, 0
	v_mov_b32_e32 v33, 0
	v_mov_b32_e32 v34, 0
	v_mov_b32_e32 v35, 0
	v_mov_b32_e32 v36, 0
	v_mov_b32_e32 v37, 0
	v_mov_b32_e32 v38, 0
	v_mov_b32_e32 v39, 0
	v_mov_b32_e32 v40, 0
	v_mov_b32_e32 v41, 0
	v_mov_b32_e32 v42, 0
	v_mov_b32_e32 v43, 0
	v_mov_b32_e32 v44, 0
	v_mov_b32_e32 v45, 0
	v_mov_b32_e32 v46, 0
	v_mov_b32_e32 v47, 0
	v_mov_b32_e32 v48, 0
	v_mov_b32_e32 v49, 0
	v_mov_b32_e32 v50, 0
	v_mov_b32_e32 v51, 0
	v_mov_b32_e32 v52, 0
	v_mov_b32_e32 v53, 0
	v_mov_b32_e32 v54, 0
	v_mov_b32_e32 v55, 0
	v_mov_b32_e32 v56, 0
	v_mov_b32_e32 v57, 0
	v_mov_b32_e32 v58, 0
	v_mov_b32_e32 v59, 0
	v_mov_b32_e32 v60, 0
	v_mov_b32_e32 v61, 0
	v_mov_b32_e32 v62, 0
	v_mov_b32_e32 v63, 0
	v_mov_b32_e32 v64, 0
	v_mov_b32_e32 v65, 0
	v_mov_b32_e32 v66, 0
	v_mov_b32_e32 v67, 0
	v_mov_b32_e32 v68, 0
	v_mov_b32_e32 v69, 0
	v_mov_b32_e32 v70, 0
	v_mov_b32_e32 v71, 0
	v_mov_b32_e32 v72, 0
	v_mov_b32_e32 v73, 0
	v_mov_b32_e32 v74, 0
	v_mov_b32_e32 v75, 0
	v_mov_b32_e32 v76, 0
	v_mov_b32_e32 v77, 0
	v_mov_b32_e32 v78, 0
	v_mov_b32_e32 v79, 0
	v_mov_b32_e32 v80, 0
	v_mov_b32_e32 v81, 0
	v_mov_b32_e32 v82, 0
	v_mov_b32_e32 v83, 0
	v_mov_b32_e32 v84, 0
	v_mov_b32_e32 v85, 0
	v_mov_b32_e32 v86, 0
	v_mov_b32_e32 v87, 0
	v_mov_b32_e32 v88, 0
	v_mov_b32_e32 v89, 0
	v_mov_b32_e32 v90, 0
	v_mov_b32_e32 v91, 0
	v_mov_b32_e32 v92, 0
	v_mov_b32_e32 v93, 0
	v_mov_b32_e32 v94, 0
	v_mov_b32_e32 v95, 0
	v_mov_b32_e32 v96, 0
	v_mov_b32_e32 v97, 0
	v_mov_b32_e32 v98, 0
	v_mov_b32_e32 v99, 0
	v_mov_b32_e32 v100, 0
	v_mov_b32_e32 v101, 0
	v_mov_b32_e32 v102, 0
	v_mov_b32_e32 v103, 0
	v_mov_b32_e32 v104, 0
	v_mov_b32_e32 v105, 0
	v_mov_b32_e32 v106, 0
	v_mov_b32_e32 v107, 0
	v_mov_b32_e32 v108, 0
	v_mov_b32_e32 v109, 0
	v_mov_b32_e32 v110, 0
	v_mov_b32_e32 v111, 0
	v_mov_b32_e32 v112, 0
	v_mov_b32_e32 v113, 0
	v_mov_b32_e32 v114, 0
	v_mov_b32_e32 v115, 0
	v_mov_b32_e32 v116, 0
	v_mov_b32_e32 v117, 0
	v_mov_b32_e32 v118, 0
	v_mov_b32_e32 v119, 0
	v_mov_b32_e32 v120, 0
	v_mov_b32_e32 v121, 0
	v_mov_b32_e32 v122, 0
	v_mov_b32_e32 v123, 0
	v_mov_b32_e32 v124, 0
	v_mov_b32_e32 v125, 0
	v_mov_b32_e32 v126, 0
	v_mov_b32_e32 v127, 0
	s_mov_b32 s98, 0
	s_mov_b32 s31, 24576
	s_waitcnt vmcnt(6)
	s_barrier
; #define LWRITE(S, buf) do { bf16_t* sA_ = sbase + (buf) * BUF; bf16_t* sB_ = sA_ + 256 * PITCH; \
;     _Pragma("unroll") for (int i_ = 0; i_ < 4; ++i_) *(u32x4*)(sA_ + (sr + i_ * 64) * PITCH + scv * 8) = ra[S][i_]; \
;     _Pragma("unroll") for (int i_ = 0; i_ < 2; ++i_) *(u32x4*)(sB_ + (sr + i_ * 64) * PITCH + scv * 8) = rb[S][i_]; } while (0)
; template <class Epi>
; DI void gemm_tile(char* smem, const bf16_t* __restrict__ A0, int lda0, int ksplit, const bf16_t* __restrict__ A1, int lda1,
;                   const bf16_t* __restrict__ Bt, int K, int row0, int col0, const Epi& epi, int tid) {
;     ...
;     for (int kt = 0; kt < nk; kt += 2) {
;       LWRITE(1, 1);
;       __builtin_amdgcn_sched_barrier(0);
;       GLOAD(1, (kt + 3 < last ? kt + 3 : last));
;       __builtin_amdgcn_sched_barrier(0);
;       COMPUTE(0);
	ds_read_b128 v[128:131], v231 offset:0
	ds_read_b128 v[132:135], v231 offset:1024
	ds_read_b128 v[136:139], v231 offset:2048
	ds_read_b128 v[140:143], v231 offset:3072
	ds_read_b128 v[144:147], v230 offset:0
	ds_read_b128 v[148:151], v230 offset:1024
	ds_read_b128 v[152:155], v230 offset:2048
	ds_read_b128 v[156:159], v230 offset:3072
	ds_read_b128 v[160:163], v230 offset:4096
	ds_read_b128 v[164:167], v230 offset:5120
	ds_read_b128 v[168:171], v230 offset:6144
	ds_read_b128 v[172:175], v230 offset:7168
	s_waitcnt vmcnt(0)
	s_waitcnt lgkmcnt(0)
	s_barrier
	v_add_u32_e32 v232, s31, v230
	v_add_u32_e32 v233, s31, v231
	s_setprio 1
	v_mfma_f32_16x16x32_bf16 v[0:3], v[128:131], v[144:147], v[0:3]
	v_mfma_f32_16x16x32_bf16 v[4:7], v[132:135], v[144:147], v[4:7]
	v_mfma_f32_16x16x32_bf16 v[8:11], v[136:139], v[144:147], v[8:11]
	v_mfma_f32_16x16x32_bf16 v[12:15], v[140:143], v[144:147], v[12:15]
	ds_read_b128 v[176:179], v233 offset:0
	ds_read_b128 v[180:183], v233 offset:1024
	v_mfma_f32_16x16x32_bf16 v[16:19], v[128:131], v[148:151], v[16:19]
	v_mfma_f32_16x16x32_bf16 v[20:23], v[132:135], v[148:151], v[20:23]
	v_mfma_f32_16x16x32_bf16 v[24:27], v[136:139], v[148:151], v[24:27]
	v_mfma_f32_16x16x32_bf16 v[28:31], v[140:143], v[148:151], v[28:31]
	ds_read_b128 v[184:187], v233 offset:2048
	ds_read_b128 v[188:191], v233 offset:3072
	v_mfma_f32_16x16x32_bf16 v[32:35], v[128:131], v[152:155], v[32:35]
	v_mfma_f32_16x16x32_bf16 v[36:39], v[132:135], v[152:155], v[36:39]
	v_mfma_f32_16x16x32_bf16 v[40:43], v[136:139], v[152:155], v[40:43]
	v_mfma_f32_16x16x32_bf16 v[44:47], v[140:143], v[152:155], v[44:47]
	ds_read_b128 v[192:195], v232 offset:0
	ds_read_b128 v[196:199], v232 offset:1024
	v_mfma_f32_16x16x32_bf16 v[48:51], v[128:131], v[156:159], v[48:51]
	v_mfma_f32_16x16x32_bf16 v[52:55], v[132:135], v[156:159], v[52:55]
	v_mfma_f32_16x16x32_bf16 v[56:59], v[136:139], v[156:159], v[56:59]
	v_mfma_f32_16x16x32_bf16 v[60:63], v[140:143], v[156:159], v[60:63]
	ds_read_b128 v[200:203], v232 offset:2048
	ds_read_b128 v[204:207], v232 offset:3072
	v_mfma_f32_16x16x32_bf16 v[64:67], v[128:131], v[160:163], v[64:67]
	v_mfma_f32_16x16x32_bf16 v[68:71], v[132:135], v[160:163], v[68:71]
	v_mfma_f32_16x16x32_bf16 v[72:75], v[136:139], v[160:163], v[72:75]
	v_mfma_f32_16x16x32_bf16 v[76:79], v[140:143], v[160:163], v[76:79]
	ds_read_b128 v[208:211], v232 offset:4096
	v_mfma_f32_16x16x32_bf16 v[80:83], v[128:131], v[164:167], v[80:83]
	v_mfma_f32_16x16x32_bf16 v[84:87], v[132:135], v[164:167], v[84:87]
	v_mfma_f32_16x16x32_bf16 v[88:91], v[136:139], v[164:167], v[88:91]
	v_mfma_f32_16x16x32_bf16 v[92:95], v[140:143], v[164:167], v[92:95]
	ds_read_b128 v[212:215], v232 offset:5120
	s_cmp_eq_u32 s25, 0
	s_cbranch_scc0 .Lg3c_hi0
	s_setprio 0

; #define LWRITE(S, buf) do { bf16_t* sA_ = sbase + (buf) * BUF; bf16_t* sB_ = sA_ + 256 * PITCH; \
;     _Pragma("unroll") for (int i_ = 0; i_ < 4; ++i_) *(u32x4*)(sA_ + (sr + i_ * 64) * PITCH + scv * 8) = ra[S][i_]; \
;     _Pragma("unroll") for (int i_ = 0; i_ < 2; ++i_) *(u32x4*)(sB_ + (sr + i_ * 64) * PITCH + scv * 8) = rb[S][i_]; } while (0)
; template <class Epi>
; DI void gemm_tile(char* smem, const bf16_t* __restrict__ A0, int lda0, int ksplit, const bf16_t* __restrict__ A1, int lda1,
;                   const bf16_t* __restrict__ Bt, int K, int row0, int col0, const Epi& epi, int tid) {
;     ...
;   const int lane = tid & 63, wid = tid >> 6, wr = wid >> 1, wc = wid & 1, fr = lane & 15, fq = lane >> 4;
;   f32x4 acc[8][4];
; #pragma unroll
;   for (int m = 0; m < 8; ++m)
; #pragma unroll
;     for (int n = 0; n < 4; ++n) acc[m][n] = (f32x4){0.f, 0.f, 0.f, 0.f};
;   u32x4 ra[2][4], rb[2][2];
;   const int nk = K / BK;
;   const int sr = tid >> 2, scv = tid & 3;
;     ...
;   __syncthreads();
;   {
;     const int last = nk - 1;
;     GLOAD(0, 0);
;     __builtin_amdgcn_sched_barrier(0);
;     GLOAD(1, 1);
;     __builtin_amdgcn_sched_barrier(0);
;     LWRITE(0, 0);
;     __builtin_amdgcn_sched_barrier(0);
;     GLOAD(0, (2 < last ? 2 : last));
;     __builtin_amdgcn_sched_barrier(0);
;     __syncthreads();
; template <class Epi>
; DI void gemm_phase(char* smem, const bf16_t* A0, int lda0, int ksplit, const bf16_t* A1, int lda1, const bf16_t* Bt, int K, int nN, const Epi& epi, int tid) {
;     ...
;     const int x = blockIdx.x & 7, l = blockIdx.x >> 3, L = G >> 3, per = 8 * nN, tot = 2 * per;
;     for (int q = l; q < tot; q += L) { const int rgl = q / per, rem = q % per, ct = rem >> 3, rt = (x * 2 + rgl) * 8 + (rem & 7);
;       gemm_tile(smem, A0, lda0, ksplit, A1, lda1, Bt, K, rt * 256, ct * 128, epi, tid); }
.Lg3d_tile:
	s_cmpk_ge_u32 s15, 64
	s_cbranch_scc1 .Lg3d_done
	s_cmpk_ge_u32 s15, 32
	s_cselect_b32 s27, 1, 0
	s_cselect_b32 s26, 32, 0
	s_sub_u32 s26, s15, s26
	s_add_u32 s27, s27, s101
	s_lshl_b32 s27, s27, 3
	s_and_b32 s29, s26, 7
	s_add_u32 s29, s29, s27
	s_lshl_b32 s29, s29, 8
	s_lshr_b32 s28, s26, 3
	s_lshl_b32 s28, s28, 7
	s_mul_i32 s27, s29, 512
	s_add_u32 s27, s27, 0x1ea00100
	s_add_u32 s0, s92, s27
	s_addc_u32 s1, s93, 0
	s_mul_i32 s27, s28, 256
	s_add_u32 s27, s27, 0x3480000
	s_add_u32 s2, s92, s27
	s_addc_u32 s3, s93, 0
	s_waitcnt lgkmcnt(0)
	s_barrier
	s_mov_b32 s99, 0
	s_mov_b32 s30, 0
	s_add_u32 s26, s30, s100
	s_add_u32 m0, s26, 0
	s_nop 0
	global_load_lds_dwordx4 v224, s[0:1]
	s_add_u32 m0, s26, 4096
	s_nop 0
	global_load_lds_dwordx4 v225, s[0:1]
	s_add_u32 m0, s26, 8192
	s_nop 0
	global_load_lds_dwordx4 v226, s[0:1]
	s_add_u32 m0, s26, 12288
	s_nop 0
	global_load_lds_dwordx4 v227, s[0:1]
	s_add_u32 m0, s26, 16384
	s_nop 0
	global_load_lds_dwordx4 v228, s[2:3]
	s_add_u32 m0, s26, 20480
	s_nop 0
	global_load_lds_dwordx4 v229, s[2:3]
	s_add_u32 s0, s0, 64
	s_addc_u32 s1, s1, 0
	s_add_u32 s2, s2, 64
	s_addc_u32 s3, s3, 0
	s_add_u32 s99, s99, 1
	s_add_u32 s30, s30, 24576
	s_cmp_eq_u32 s30, 73728
	s_cselect_b32 s30, 0, s30
	s_add_u32 s26, s30, s100
	s_add_u32 m0, s26, 0
	s_nop 0
	global_load_lds_dwordx4 v224, s[0:1]
	s_add_u32 m0, s26, 4096
	s_nop 0
	global_load_lds_dwordx4 v225, s[0:1]
	s_add_u32 m0, s26, 8192
	s_nop 0
	global_load_lds_dwordx4 v226, s[0:1]
	s_add_u32 m0, s26, 12288
	s_nop 0
	global_load_lds_dwordx4 v227, s[0:1]
	s_add_u32 m0, s26, 16384
	s_nop 0
	global_load_lds_dwordx4 v228, s[2:3]
	s_add_u32 m0, s26, 20480
	s_nop 0
	global_load_lds_dwordx4 v229, s[2:3]
	s_add_u32 s0, s0, 64
	s_addc_u32 s1, s1, 0
	s_add_u32 s2, s2, 64
	s_addc_u32 s3, s3, 0
	s_add_u32 s99, s99, 1
	s_add_u32 s30, s30, 24576
	s_cmp_eq_u32 s30, 73728
	s_cselect_b32 s30, 0, s30
	s_add_u32 s26, s30, s100
	s_add_u32 m0, s26, 0
	s_nop 0
	global_load_lds_dwordx4 v224, s[0:1]
	s_add_u32 m0, s26, 4096
	s_nop 0
	global_load_lds_dwordx4 v225, s[0:1]
	s_add_u32 m0, s26, 8192
	s_nop 0
	global_load_lds_dwordx4 v226, s[0:1]
	s_add_u32 m0, s26, 12288
	s_nop 0
	global_load_lds_dwordx4 v227, s[0:1]
	s_add_u32 m0, s26, 16384
	s_nop 0
	global_load_lds_dwordx4 v228, s[2:3]
	s_add_u32 m0, s26, 20480
	s_nop 0
	global_load_lds_dwordx4 v229, s[2:3]
	s_add_u32 s0, s0, 64
	s_addc_u32 s1, s1, 0
	s_add_u32 s2, s2, 64
	s_addc_u32 s3, s3, 0
	s_add_u32 s99, s99, 1
	s_add_u32 s30, s30, 24576
	s_cmp_eq_u32 s30, 73728
	s_cselect_b32 s30, 0, s30
	v_mov_b32_e32 v0, 0
	v_mov_b32_e32 v1, 0
	v_mov_b32_e32 v2, 0
	v_mov_b32_e32 v3, 0
	v_mov_b32_e32 v4, 0
	v_mov_b32_e32 v5, 0
	v_mov_b32_e32 v6, 0
	v_mov_b32_e32 v7, 0
	v_mov_b32_e32 v8, 0
	v_mov_b32_e32 v9, 0
	v_mov_b32_e32 v10, 0
	v_mov_b32_e32 v11, 0
	v_mov_b32_e32 v12, 0
	v_mov_b32_e32 v13, 0
	v_mov_b32_e32 v14, 0
	v_mov_b32_e32 v15, 0
	v_mov_b32_e32 v16, 0
	v_mov_b32_e32 v17, 0
	v_mov_b32_e32 v18, 0
	v_mov_b32_e32 v19, 0
	v_mov_b32_e32 v20, 0
	v_mov_b32_e32 v21, 0
	v_mov_b32_e32 v22, 0
	v_mov_b32_e32 v23, 0
	v_mov_b32_e32 v24, 0
	v_mov_b32_e32 v25, 0
	v_mov_b32_e32 v26, 0
	v_mov_b32_e32 v27, 0
	v_mov_b32_e32 v28, 0
	v_mov_b32_e32 v29, 0
	v_mov_b32_e32 v30, 0
	v_mov_b32_e32 v31, 0
	v_mov_b32_e32 v32, 0
	v_mov_b32_e32 v33, 0
	v_mov_b32_e32 v34, 0
	v_mov_b32_e32 v35, 0
	v_mov_b32_e32 v36, 0
	v_mov_b32_e32 v37, 0
	v_mov_b32_e32 v38, 0
	v_mov_b32_e32 v39, 0
	v_mov_b32_e32 v40, 0
	v_mov_b32_e32 v41, 0
	v_mov_b32_e32 v42, 0
	v_mov_b32_e32 v43, 0
	v_mov_b32_e32 v44, 0
	v_mov_b32_e32 v45, 0
	v_mov_b32_e32 v46, 0
	v_mov_b32_e32 v47, 0
	v_mov_b32_e32 v48, 0
	v_mov_b32_e32 v49, 0
	v_mov_b32_e32 v50, 0
	v_mov_b32_e32 v51, 0
	v_mov_b32_e32 v52, 0
	v_mov_b32_e32 v53, 0
	v_mov_b32_e32 v54, 0
	v_mov_b32_e32 v55, 0
	v_mov_b32_e32 v56, 0
	v_mov_b32_e32 v57, 0
	v_mov_b32_e32 v58, 0
	v_mov_b32_e32 v59, 0
	v_mov_b32_e32 v60, 0
	v_mov_b32_e32 v61, 0
	v_mov_b32_e32 v62, 0
	v_mov_b32_e32 v63, 0
	v_mov_b32_e32 v64, 0
	v_mov_b32_e32 v65, 0
	v_mov_b32_e32 v66, 0
	v_mov_b32_e32 v67, 0
	v_mov_b32_e32 v68, 0
	v_mov_b32_e32 v69, 0
	v_mov_b32_e32 v70, 0
	v_mov_b32_e32 v71, 0
	v_mov_b32_e32 v72, 0
	v_mov_b32_e32 v73, 0
	v_mov_b32_e32 v74, 0
	v_mov_b32_e32 v75, 0
	v_mov_b32_e32 v76, 0
	v_mov_b32_e32 v77, 0
	v_mov_b32_e32 v78, 0
	v_mov_b32_e32 v79, 0
	v_mov_b32_e32 v80, 0
	v_mov_b32_e32 v81, 0
	v_mov_b32_e32 v82, 0
	v_mov_b32_e32 v83, 0
	v_mov_b32_e32 v84, 0
	v_mov_b32_e32 v85, 0
	v_mov_b32_e32 v86, 0
	v_mov_b32_e32 v87, 0
	v_mov_b32_e32 v88, 0
	v_mov_b32_e32 v89, 0
	v_mov_b32_e32 v90, 0
	v_mov_b32_e32 v91, 0
	v_mov_b32_e32 v92, 0
	v_mov_b32_e32 v93, 0
	v_mov_b32_e32 v94, 0
	v_mov_b32_e32 v95, 0
	v_mov_b32_e32 v96, 0
	v_mov_b32_e32 v97, 0
	v_mov_b32_e32 v98, 0
	v_mov_b32_e32 v99, 0
	v_mov_b32_e32 v100, 0
	v_mov_b32_e32 v101, 0
	v_mov_b32_e32 v102, 0
	v_mov_b32_e32 v103, 0
	v_mov_b32_e32 v104, 0
	v_mov_b32_e32 v105, 0
	v_mov_b32_e32 v106, 0
	v_mov_b32_e32 v107, 0
	v_mov_b32_e32 v108, 0
	v_mov_b32_e32 v109, 0
	v_mov_b32_e32 v110, 0
	v_mov_b32_e32 v111, 0
	v_mov_b32_e32 v112, 0
	v_mov_b32_e32 v113, 0
	v_mov_b32_e32 v114, 0
	v_mov_b32_e32 v115, 0
	v_mov_b32_e32 v116, 0
	v_mov_b32_e32 v117, 0
	v_mov_b32_e32 v118, 0
	v_mov_b32_e32 v119, 0
	v_mov_b32_e32 v120, 0
	v_mov_b32_e32 v121, 0
	v_mov_b32_e32 v122, 0
	v_mov_b32_e32 v123, 0
	v_mov_b32_e32 v124, 0
	v_mov_b32_e32 v125, 0
	v_mov_b32_e32 v126, 0
	v_mov_b32_e32 v127, 0
	s_mov_b32 s98, 0
	s_mov_b32 s31, 24576
	s_waitcnt vmcnt(12)
	s_barrier
; #define LWRITE(S, buf) do { bf16_t* sA_ = sbase + (buf) * BUF; bf16_t* sB_ = sA_ + 256 * PITCH; \
;     _Pragma("unroll") for (int i_ = 0; i_ < 4; ++i_) *(u32x4*)(sA_ + (sr + i_ * 64) * PITCH + scv * 8) = ra[S][i_]; \
;     _Pragma("unroll") for (int i_ = 0; i_ < 2; ++i_) *(u32x4*)(sB_ + (sr + i_ * 64) * PITCH + scv * 8) = rb[S][i_]; } while (0)
; template <class Epi>
; DI void gemm_tile(char* smem, const bf16_t* __restrict__ A0, int lda0, int ksplit, const bf16_t* __restrict__ A1, int lda1,
;                   const bf16_t* __restrict__ Bt, int K, int row0, int col0, const Epi& epi, int tid) {
;     ...
;   __syncthreads();
;   {
;     const int last = nk - 1;
;     GLOAD(0, 0);
;     __builtin_amdgcn_sched_barrier(0);
;     GLOAD(1, 1);
;     __builtin_amdgcn_sched_barrier(0);
;     LWRITE(0, 0);
;     __builtin_amdgcn_sched_barrier(0);
;     GLOAD(0, (2 < last ? 2 : last));
;     __builtin_amdgcn_sched_barrier(0);
;     __syncthreads();
;     for (int kt = 0; kt < nk; kt += 2) {
;       LWRITE(1, 1);
;       __builtin_amdgcn_sched_barrier(0);
;       GLOAD(1, (kt + 3 < last ? kt + 3 : last));
;       __builtin_amdgcn_sched_barrier(0);
;       COMPUTE(0);
;       __syncthreads();
;       LWRITE(0, 0);
;       __builtin_amdgcn_sched_barrier(0);
;       GLOAD(0, (kt + 4 < last ? kt + 4 : last));
;       __builtin_amdgcn_sched_barrier(0);
;       COMPUTE(1);
	ds_read_b128 v[128:131], v231 offset:0
	ds_read_b128 v[132:135], v231 offset:1024
	ds_read_b128 v[136:139], v231 offset:2048
	ds_read_b128 v[140:143], v231 offset:3072
	ds_read_b128 v[144:147], v230 offset:0
	ds_read_b128 v[148:151], v230 offset:1024
	ds_read_b128 v[152:155], v230 offset:2048
	ds_read_b128 v[156:159], v230 offset:3072
	ds_read_b128 v[160:163], v230 offset:4096
	ds_read_b128 v[164:167], v230 offset:5120
	ds_read_b128 v[168:171], v230 offset:6144
	ds_read_b128 v[172:175], v230 offset:7168
	s_waitcnt vmcnt(6)
	s_waitcnt lgkmcnt(0)
	s_barrier
	v_add_u32_e32 v232, s31, v230
	v_add_u32_e32 v233, s31, v231
	s_add_u32 s26, s30, s100
	s_setprio 1
	v_mfma_f32_16x16x32_bf16 v[0:3], v[128:131], v[144:147], v[0:3]
	v_mfma_f32_16x16x32_bf16 v[4:7], v[132:135], v[144:147], v[4:7]
	v_mfma_f32_16x16x32_bf16 v[8:11], v[136:139], v[144:147], v[8:11]
	v_mfma_f32_16x16x32_bf16 v[12:15], v[140:143], v[144:147], v[12:15]
	ds_read_b128 v[176:179], v233 offset:0
	ds_read_b128 v[180:183], v233 offset:1024
	s_add_u32 m0, s26, 0
	s_nop 0
	global_load_lds_dwordx4 v224, s[0:1]
	v_mfma_f32_16x16x32_bf16 v[16:19], v[128:131], v[148:151], v[16:19]
	v_mfma_f32_16x16x32_bf16 v[20:23], v[132:135], v[148:151], v[20:23]
	v_mfma_f32_16x16x32_bf16 v[24:27], v[136:139], v[148:151], v[24:27]
	v_mfma_f32_16x16x32_bf16 v[28:31], v[140:143], v[148:151], v[28:31]
	ds_read_b128 v[184:187], v233 offset:2048
	ds_read_b128 v[188:191], v233 offset:3072
	s_add_u32 m0, s26, 4096
	s_nop 0
	global_load_lds_dwordx4 v225, s[0:1]
	v_mfma_f32_16x16x32_bf16 v[32:35], v[128:131], v[152:155], v[32:35]
	v_mfma_f32_16x16x32_bf16 v[36:39], v[132:135], v[152:155], v[36:39]
	v_mfma_f32_16x16x32_bf16 v[40:43], v[136:139], v[152:155], v[40:43]
	v_mfma_f32_16x16x32_bf16 v[44:47], v[140:143], v[152:155], v[44:47]
	ds_read_b128 v[192:195], v232 offset:0
	ds_read_b128 v[196:199], v232 offset:1024
	s_add_u32 m0, s26, 8192
	s_nop 0
	global_load_lds_dwordx4 v226, s[0:1]
	v_mfma_f32_16x16x32_bf16 v[48:51], v[128:131], v[156:159], v[48:51]
	v_mfma_f32_16x16x32_bf16 v[52:55], v[132:135], v[156:159], v[52:55]
	v_mfma_f32_16x16x32_bf16 v[56:59], v[136:139], v[156:159], v[56:59]
	v_mfma_f32_16x16x32_bf16 v[60:63], v[140:143], v[156:159], v[60:63]
	ds_read_b128 v[200:203], v232 offset:2048
	ds_read_b128 v[204:207], v232 offset:3072
	s_add_u32 m0, s26, 12288
	s_nop 0
	global_load_lds_dwordx4 v227, s[0:1]
	v_mfma_f32_16x16x32_bf16 v[64:67], v[128:131], v[160:163], v[64:67]
	v_mfma_f32_16x16x32_bf16 v[68:71], v[132:135], v[160:163], v[68:71]
	v_mfma_f32_16x16x32_bf16 v[72:75], v[136:139], v[160:163], v[72:75]
	v_mfma_f32_16x16x32_bf16 v[76:79], v[140:143], v[160:163], v[76:79]
	ds_read_b128 v[208:211], v232 offset:4096
	s_add_u32 m0, s26, 16384
	s_nop 0
	global_load_lds_dwordx4 v228, s[2:3]
	v_mfma_f32_16x16x32_bf16 v[80:83], v[128:131], v[164:167], v[80:83]
	v_mfma_f32_16x16x32_bf16 v[84:87], v[132:135], v[164:167], v[84:87]
	v_mfma_f32_16x16x32_bf16 v[88:91], v[136:139], v[164:167], v[88:91]
	v_mfma_f32_16x16x32_bf16 v[92:95], v[140:143], v[164:167], v[92:95]
	ds_read_b128 v[212:215], v232 offset:5120
	s_add_u32 m0, s26, 20480
	s_nop 0
	global_load_lds_dwordx4 v229, s[2:3]
	s_cmp_eq_u32 s25, 0
	s_cbranch_scc0 .Lg3d_hi0
	s_setprio 0
; #define LWRITE(S, buf) do { bf16_t* sA_ = sbase + (buf) * BUF; bf16_t* sB_ = sA_ + 256 * PITCH; \
;     _Pragma("unroll") for (int i_ = 0; i_ < 4; ++i_) *(u32x4*)(sA_ + (sr + i_ * 64) * PITCH + scv * 8) = ra[S][i_]; \
;     _Pragma("unroll") for (int i_ = 0; i_ < 2; ++i_) *(u32x4*)(sB_ + (sr + i_ * 64) * PITCH + scv * 8) = rb[S][i_]; } while (0)
; template <class Epi>
; DI void gemm_tile(char* smem, const bf16_t* __restrict__ A0, int lda0, int ksplit, const bf16_t* __restrict__ A1, int lda1,
;                   const bf16_t* __restrict__ Bt, int K, int row0, int col0, const Epi& epi, int tid) {
;     ...
;   __syncthreads();
;   {
;     const int last = nk - 1;
;     GLOAD(0, 0);
;     __builtin_amdgcn_sched_barrier(0);
;     GLOAD(1, 1);
;     __builtin_amdgcn_sched_barrier(0);
;     LWRITE(0, 0);
;     __builtin_amdgcn_sched_barrier(0);
;     GLOAD(0, (2 < last ? 2 : last));
;     __builtin_amdgcn_sched_barrier(0);
;     __syncthreads();
;     for (int kt = 0; kt < nk; kt += 2) {
;       LWRITE(1, 1);
;       __builtin_amdgcn_sched_barrier(0);
;       GLOAD(1, (kt + 3 < last ? kt + 3 : last));
;       __builtin_amdgcn_sched_barrier(0);
;       COMPUTE(0);
;       __syncthreads();
;       LWRITE(0, 0);
;       __builtin_amdgcn_sched_barrier(0);
;       GLOAD(0, (kt + 4 < last ? kt + 4 : last));
;       __builtin_amdgcn_sched_barrier(0);
;       COMPUTE(1);
;       __syncthreads();
.Lg3d_hi0:
	v_mfma_f32_16x16x32_bf16 v[96:99], v[128:131], v[168:171], v[96:99]
	v_mfma_f32_16x16x32_bf16 v[100:103], v[132:135], v[168:171], v[100:103]
	v_mfma_f32_16x16x32_bf16 v[104:107], v[136:139], v[168:171], v[104:107]
	v_mfma_f32_16x16x32_bf16 v[108:111], v[140:143], v[168:171], v[108:111]
	ds_read_b128 v[216:219], v232 offset:6144
	s_add_u32 s0, s0, 64
	s_addc_u32 s1, s1, 0
	s_add_u32 s2, s2, 64
	s_addc_u32 s3, s3, 0
	s_add_u32 s99, s99, 1
	s_add_u32 s30, s30, 24576
	s_cmp_eq_u32 s30, 73728
	s_cselect_b32 s30, 0, s30
	s_add_u32 s31, s31, 24576
	s_cmp_eq_u32 s31, 73728
	s_cselect_b32 s31, 0, s31
	v_mfma_f32_16x16x32_bf16 v[112:115], v[128:131], v[172:175], v[112:115]
	v_mfma_f32_16x16x32_bf16 v[116:119], v[132:135], v[172:175], v[116:119]
	v_mfma_f32_16x16x32_bf16 v[120:123], v[136:139], v[172:175], v[120:123]
	v_mfma_f32_16x16x32_bf16 v[124:127], v[140:143], v[172:175], v[124:127]
	ds_read_b128 v[220:223], v232 offset:7168
	s_waitcnt vmcnt(6)
	s_waitcnt lgkmcnt(0)
	s_barrier
	v_add_u32_e32 v232, s31, v230
	v_add_u32_e32 v233, s31, v231
	s_setprio 1
	v_mfma_f32_16x16x32_bf16 v[0:3], v[176:179], v[192:195], v[0:3]
	v_mfma_f32_16x16x32_bf16 v[4:7], v[180:183], v[192:195], v[4:7]
	v_mfma_f32_16x16x32_bf16 v[8:11], v[184:187], v[192:195], v[8:11]
	v_mfma_f32_16x16x32_bf16 v[12:15], v[188:191], v[192:195], v[12:15]
	ds_read_b128 v[128:131], v233 offset:0
	ds_read_b128 v[132:135], v233 offset:1024
	v_mfma_f32_16x16x32_bf16 v[16:19], v[176:179], v[196:199], v[16:19]
	v_mfma_f32_16x16x32_bf16 v[20:23], v[180:183], v[196:199], v[20:23]
	v_mfma_f32_16x16x32_bf16 v[24:27], v[184:187], v[196:199], v[24:27]
	v_mfma_f32_16x16x32_bf16 v[28:31], v[188:191], v[196:199], v[28:31]
	ds_read_b128 v[136:139], v233 offset:2048
	ds_read_b128 v[140:143], v233 offset:3072
	v_mfma_f32_16x16x32_bf16 v[32:35], v[176:179], v[200:203], v[32:35]
	v_mfma_f32_16x16x32_bf16 v[36:39], v[180:183], v[200:203], v[36:39]
	v_mfma_f32_16x16x32_bf16 v[40:43], v[184:187], v[200:203], v[40:43]
	v_mfma_f32_16x16x32_bf16 v[44:47], v[188:191], v[200:203], v[44:47]
	ds_read_b128 v[144:147], v232 offset:0
	ds_read_b128 v[148:151], v232 offset:1024
	v_mfma_f32_16x16x32_bf16 v[48:51], v[176:179], v[204:207], v[48:51]
	v_mfma_f32_16x16x32_bf16 v[52:55], v[180:183], v[204:207], v[52:55]
	v_mfma_f32_16x16x32_bf16 v[56:59], v[184:187], v[204:207], v[56:59]
	v_mfma_f32_16x16x32_bf16 v[60:63], v[188:191], v[204:207], v[60:63]
	ds_read_b128 v[152:155], v232 offset:2048
	ds_read_b128 v[156:159], v232 offset:3072
	v_mfma_f32_16x16x32_bf16 v[64:67], v[176:179], v[208:211], v[64:67]
	v_mfma_f32_16x16x32_bf16 v[68:71], v[180:183], v[208:211], v[68:71]
	v_mfma_f32_16x16x32_bf16 v[72:75], v[184:187], v[208:211], v[72:75]
	v_mfma_f32_16x16x32_bf16 v[76:79], v[188:191], v[208:211], v[76:79]
	ds_read_b128 v[160:163], v232 offset:4096
	v_mfma_f32_16x16x32_bf16 v[80:83], v[176:179], v[212:215], v[80:83]
	v_mfma_f32_16x16x32_bf16 v[84:87], v[180:183], v[212:215], v[84:87]
	v_mfma_f32_16x16x32_bf16 v[88:91], v[184:187], v[212:215], v[88:91]
	v_mfma_f32_16x16x32_bf16 v[92:95], v[188:191], v[212:215], v[92:95]
	ds_read_b128 v[164:167], v232 offset:5120
	s_cmp_eq_u32 s25, 0
	s_cbranch_scc0 .Lg3d_hi1
	s_setprio 0
.Lg3d_hi1:
	v_mfma_f32_16x16x32_bf16 v[96:99], v[176:179], v[216:219], v[96:99]
	v_mfma_f32_16x16x32_bf16 v[100:103], v[180:183], v[216:219], v[100:103]
	v_mfma_f32_16x16x32_bf16 v[104:107], v[184:187], v[216:219], v[104:107]
	v_mfma_f32_16x16x32_bf16 v[108:111], v[188:191], v[216:219], v[108:111]
	ds_read_b128 v[168:171], v232 offset:6144
	s_add_u32 s31, s31, 24576
	s_cmp_eq_u32 s31, 73728
	s_cselect_b32 s31, 0, s31
	v_mfma_f32_16x16x32_bf16 v[112:115], v[176:179], v[220:223], v[112:115]
	v_mfma_f32_16x16x32_bf16 v[116:119], v[180:183], v[220:223], v[116:119]
	v_mfma_f32_16x16x32_bf16 v[120:123], v[184:187], v[220:223], v[120:123]
	v_mfma_f32_16x16x32_bf16 v[124:127], v[188:191], v[220:223], v[124:127]
	ds_read_b128 v[172:175], v232 offset:7168
	s_waitcnt vmcnt(0)
	s_waitcnt lgkmcnt(0)
	s_barrier
	v_add_u32_e32 v232, s31, v230
	v_add_u32_e32 v233, s31, v231
	s_setprio 1
	v_mfma_f32_16x16x32_bf16 v[0:3], v[128:131], v[144:147], v[0:3]
	v_mfma_f32_16x16x32_bf16 v[4:7], v[132:135], v[144:147], v[4:7]
	v_mfma_f32_16x16x32_bf16 v[8:11], v[136:139], v[144:147], v[8:11]
	v_mfma_f32_16x16x32_bf16 v[12:15], v[140:143], v[144:147], v[12:15]
	ds_read_b128 v[176:179], v233 offset:0
	ds_read_b128 v[180:183], v233 offset:1024
	v_mfma_f32_16x16x32_bf16 v[16:19], v[128:131], v[148:151], v[16:19]
	v_mfma_f32_16x16x32_bf16 v[20:23], v[132:135], v[148:151], v[20:23]
	v_mfma_f32_16x16x32_bf16 v[24:27], v[136:139], v[148:151], v[24:27]
	v_mfma_f32_16x16x32_bf16 v[28:31], v[140:143], v[148:151], v[28:31]
	ds_read_b128 v[184:187], v233 offset:2048
	ds_read_b128 v[188:191], v233 offset:3072
	v_mfma_f32_16x16x32_bf16 v[32:35], v[128:131], v[152:155], v[32:35]
	v_mfma_f32_16x16x32_bf16 v[36:39], v[132:135], v[152:155], v[36:39]
	v_mfma_f32_16x16x32_bf16 v[40:43], v[136:139], v[152:155], v[40:43]
	v_mfma_f32_16x16x32_bf16 v[44:47], v[140:143], v[152:155], v[44:47]
	ds_read_b128 v[192:195], v232 offset:0
	ds_read_b128 v[196:199], v232 offset:1024
	v_mfma_f32_16x16x32_bf16 v[48:51], v[128:131], v[156:159], v[48:51]
	v_mfma_f32_16x16x32_bf16 v[52:55], v[132:135], v[156:159], v[52:55]
	v_mfma_f32_16x16x32_bf16 v[56:59], v[136:139], v[156:159], v[56:59]
	v_mfma_f32_16x16x32_bf16 v[60:63], v[140:143], v[156:159], v[60:63]
	ds_read_b128 v[200:203], v232 offset:2048
	ds_read_b128 v[204:207], v232 offset:3072
	v_mfma_f32_16x16x32_bf16 v[64:67], v[128:131], v[160:163], v[64:67]
	v_mfma_f32_16x16x32_bf16 v[68:71], v[132:135], v[160:163], v[68:71]
	v_mfma_f32_16x16x32_bf16 v[72:75], v[136:139], v[160:163], v[72:75]
	v_mfma_f32_16x16x32_bf16 v[76:79], v[140:143], v[160:163], v[76:79]
	ds_read_b128 v[208:211], v232 offset:4096
	v_mfma_f32_16x16x32_bf16 v[80:83], v[128:131], v[164:167], v[80:83]
	v_mfma_f32_16x16x32_bf16 v[84:87], v[132:135], v[164:167], v[84:87]
	v_mfma_f32_16x16x32_bf16 v[88:91], v[136:139], v[164:167], v[88:91]
	v_mfma_f32_16x16x32_bf16 v[92:95], v[140:143], v[164:167], v[92:95]
	ds_read_b128 v[212:215], v232 offset:5120
	s_cmp_eq_u32 s25, 0
	s_cbranch_scc0 .Lg3d_hi2
	s_setprio 0

; #define LWRITE(S, buf) do { bf16_t* sA_ = sbase + (buf) * BUF; bf16_t* sB_ = sA_ + 256 * PITCH; \
;     _Pragma("unroll") for (int i_ = 0; i_ < 4; ++i_) *(u32x4*)(sA_ + (sr + i_ * 64) * PITCH + scv * 8) = ra[S][i_]; \
;     _Pragma("unroll") for (int i_ = 0; i_ < 2; ++i_) *(u32x4*)(sB_ + (sr + i_ * 64) * PITCH + scv * 8) = rb[S][i_]; } while (0)
; template <class Epi>
; DI void gemm_tile(char* smem, const bf16_t* __restrict__ A0, int lda0, int ksplit, const bf16_t* __restrict__ A1, int lda1,
;                   const bf16_t* __restrict__ Bt, int K, int row0, int col0, const Epi& epi, int tid) {
;     ...
;   __syncthreads();
;   {
;     const int last = nk - 1;
;     GLOAD(0, 0);
;     __builtin_amdgcn_sched_barrier(0);
;     GLOAD(1, 1);
;     __builtin_amdgcn_sched_barrier(0);
;     LWRITE(0, 0);
;     __builtin_amdgcn_sched_barrier(0);
;     GLOAD(0, (2 < last ? 2 : last));
;     __builtin_amdgcn_sched_barrier(0);
;     __syncthreads();
;     for (int kt = 0; kt < nk; kt += 2) {
;       LWRITE(1, 1);
;       __builtin_amdgcn_sched_barrier(0);
;       GLOAD(1, (kt + 3 < last ? kt + 3 : last));
;       __builtin_amdgcn_sched_barrier(0);
;       COMPUTE(0);
;       __syncthreads();
;       LWRITE(0, 0);
;       __builtin_amdgcn_sched_barrier(0);
;       GLOAD(0, (kt + 4 < last ? kt + 4 : last));
;       __builtin_amdgcn_sched_barrier(0);
;       COMPUTE(1);
.Lg6_swb0:
	s_waitcnt vmcnt(6)
	s_waitcnt lgkmcnt(0)
	s_barrier
	v_add_u32_e32 v232, s100, v230
	v_add_u32_e32 v233, s100, v231
	s_add_u32 s19, s99, s13
	s_setprio 1
	v_mfma_f32_16x16x32_bf16 v[0:3], v[128:131], v[144:147], v[0:3]
	v_mfma_f32_16x16x32_bf16 v[4:7], v[132:135], v[144:147], v[4:7]
	v_mfma_f32_16x16x32_bf16 v[8:11], v[136:139], v[144:147], v[8:11]
	v_mfma_f32_16x16x32_bf16 v[12:15], v[140:143], v[144:147], v[12:15]
	ds_read_b128 v[176:179], v233 offset:0
	ds_read_b128 v[180:183], v233 offset:1024
	s_add_u32 m0, s19, 0
	s_nop 0
	global_load_lds_dwordx4 v224, s[0:1]
	v_mfma_f32_16x16x32_bf16 v[16:19], v[128:131], v[148:151], v[16:19]
	v_mfma_f32_16x16x32_bf16 v[20:23], v[132:135], v[148:151], v[20:23]
	v_mfma_f32_16x16x32_bf16 v[24:27], v[136:139], v[148:151], v[24:27]
	v_mfma_f32_16x16x32_bf16 v[28:31], v[140:143], v[148:151], v[28:31]
	ds_read_b128 v[184:187], v233 offset:2048
	ds_read_b128 v[188:191], v233 offset:3072
	s_add_u32 m0, s19, 4096
	s_nop 0
	global_load_lds_dwordx4 v225, s[0:1]
	v_mfma_f32_16x16x32_bf16 v[32:35], v[128:131], v[152:155], v[32:35]
	v_mfma_f32_16x16x32_bf16 v[36:39], v[132:135], v[152:155], v[36:39]
	v_mfma_f32_16x16x32_bf16 v[40:43], v[136:139], v[152:155], v[40:43]
	v_mfma_f32_16x16x32_bf16 v[44:47], v[140:143], v[152:155], v[44:47]
	ds_read_b128 v[192:195], v232 offset:0
	ds_read_b128 v[196:199], v232 offset:1024
	s_add_u32 m0, s19, 8192
	s_nop 0
	global_load_lds_dwordx4 v226, s[0:1]
	v_mfma_f32_16x16x32_bf16 v[48:51], v[128:131], v[156:159], v[48:51]
	v_mfma_f32_16x16x32_bf16 v[52:55], v[132:135], v[156:159], v[52:55]
	v_mfma_f32_16x16x32_bf16 v[56:59], v[136:139], v[156:159], v[56:59]
	v_mfma_f32_16x16x32_bf16 v[60:63], v[140:143], v[156:159], v[60:63]
	ds_read_b128 v[200:203], v232 offset:2048
	ds_read_b128 v[204:207], v232 offset:3072
	s_add_u32 m0, s19, 12288
	s_nop 0
	global_load_lds_dwordx4 v227, s[0:1]
	v_mfma_f32_16x16x32_bf16 v[64:67], v[128:131], v[160:163], v[64:67]
	v_mfma_f32_16x16x32_bf16 v[68:71], v[132:135], v[160:163], v[68:71]
	v_mfma_f32_16x16x32_bf16 v[72:75], v[136:139], v[160:163], v[72:75]
	v_mfma_f32_16x16x32_bf16 v[76:79], v[140:143], v[160:163], v[76:79]
	ds_read_b128 v[208:211], v232 offset:4096
	s_add_u32 m0, s19, 16384
	s_nop 0
	global_load_lds_dwordx4 v228, s[2:3]
	v_mfma_f32_16x16x32_bf16 v[80:83], v[128:131], v[164:167], v[80:83]
	v_mfma_f32_16x16x32_bf16 v[84:87], v[132:135], v[164:167], v[84:87]
	v_mfma_f32_16x16x32_bf16 v[88:91], v[136:139], v[164:167], v[88:91]
	v_mfma_f32_16x16x32_bf16 v[92:95], v[140:143], v[164:167], v[92:95]
	ds_read_b128 v[212:215], v232 offset:5120
	s_add_u32 m0, s19, 20480
	s_nop 0
	global_load_lds_dwordx4 v229, s[2:3]
	s_cmp_eq_u32 s18, 0
	s_cbranch_scc0 .Lg6_hi0
	s_setprio 0
.Lg6_hi0:
	v_mfma_f32_16x16x32_bf16 v[96:99], v[128:131], v[168:171], v[96:99]
	v_mfma_f32_16x16x32_bf16 v[100:103], v[132:135], v[168:171], v[100:103]
	v_mfma_f32_16x16x32_bf16 v[104:107], v[136:139], v[168:171], v[104:107]
	v_mfma_f32_16x16x32_bf16 v[108:111], v[140:143], v[168:171], v[108:111]
	ds_read_b128 v[216:219], v232 offset:6144
	s_add_u32 s0, s0, 64
	s_addc_u32 s1, s1, 0
	s_add_u32 s2, s2, 64
	s_addc_u32 s3, s3, 0
	s_add_u32 s22, s22, 1
	s_add_u32 s99, s99, 24576
	s_cmp_eq_u32 s99, 73728
	s_cselect_b32 s99, 0, s99
	s_add_u32 s100, s100, 24576
	s_cmp_eq_u32 s100, 73728
	s_cselect_b32 s100, 0, s100
	v_mfma_f32_16x16x32_bf16 v[112:115], v[128:131], v[172:175], v[112:115]
	v_mfma_f32_16x16x32_bf16 v[116:119], v[132:135], v[172:175], v[116:119]
	v_mfma_f32_16x16x32_bf16 v[120:123], v[136:139], v[172:175], v[120:123]
	v_mfma_f32_16x16x32_bf16 v[124:127], v[140:143], v[172:175], v[124:127]
	ds_read_b128 v[220:223], v232 offset:7168
	s_cmp_eq_u32 s22, 16
	s_cbranch_scc1 .Lg6_sw1
; #define LWRITE(S, buf) do { bf16_t* sA_ = sbase + (buf) * BUF; bf16_t* sB_ = sA_ + 256 * PITCH; \
;     _Pragma("unroll") for (int i_ = 0; i_ < 4; ++i_) *(u32x4*)(sA_ + (sr + i_ * 64) * PITCH + scv * 8) = ra[S][i_]; \
;     _Pragma("unroll") for (int i_ = 0; i_ < 2; ++i_) *(u32x4*)(sB_ + (sr + i_ * 64) * PITCH + scv * 8) = rb[S][i_]; } while (0)
; template <class Epi>
; DI void gemm_tile(char* smem, const bf16_t* __restrict__ A0, int lda0, int ksplit, const bf16_t* __restrict__ A1, int lda1,
;                   const bf16_t* __restrict__ Bt, int K, int row0, int col0, const Epi& epi, int tid) {
;     ...
;   __syncthreads();
;   {
;     const int last = nk - 1;
;     GLOAD(0, 0);
;     __builtin_amdgcn_sched_barrier(0);
;     GLOAD(1, 1);
;     __builtin_amdgcn_sched_barrier(0);
;     LWRITE(0, 0);
;     __builtin_amdgcn_sched_barrier(0);
;     GLOAD(0, (2 < last ? 2 : last));
;     __builtin_amdgcn_sched_barrier(0);
;     __syncthreads();
;     for (int kt = 0; kt < nk; kt += 2) {
;       LWRITE(1, 1);
;       __builtin_amdgcn_sched_barrier(0);
;       GLOAD(1, (kt + 3 < last ? kt + 3 : last));
;       __builtin_amdgcn_sched_barrier(0);
;       COMPUTE(0);
;       __syncthreads();
;       LWRITE(0, 0);
;       __builtin_amdgcn_sched_barrier(0);
;       GLOAD(0, (kt + 4 < last ? kt + 4 : last));
;       __builtin_amdgcn_sched_barrier(0);
;       COMPUTE(1);
;       __syncthreads();
.Lg6_swb1:
	s_waitcnt vmcnt(6)
	s_waitcnt lgkmcnt(0)
	s_barrier
	v_add_u32_e32 v232, s100, v230
	v_add_u32_e32 v233, s100, v231
	s_add_u32 s19, s99, s13
	s_setprio 1
	v_mfma_f32_16x16x32_bf16 v[0:3], v[176:179], v[192:195], v[0:3]
	v_mfma_f32_16x16x32_bf16 v[4:7], v[180:183], v[192:195], v[4:7]
	v_mfma_f32_16x16x32_bf16 v[8:11], v[184:187], v[192:195], v[8:11]
	v_mfma_f32_16x16x32_bf16 v[12:15], v[188:191], v[192:195], v[12:15]
	ds_read_b128 v[128:131], v233 offset:0
	ds_read_b128 v[132:135], v233 offset:1024
	s_add_u32 m0, s19, 0
	s_nop 0
	global_load_lds_dwordx4 v224, s[0:1]
	v_mfma_f32_16x16x32_bf16 v[16:19], v[176:179], v[196:199], v[16:19]
	v_mfma_f32_16x16x32_bf16 v[20:23], v[180:183], v[196:199], v[20:23]
	v_mfma_f32_16x16x32_bf16 v[24:27], v[184:187], v[196:199], v[24:27]
	v_mfma_f32_16x16x32_bf16 v[28:31], v[188:191], v[196:199], v[28:31]
	ds_read_b128 v[136:139], v233 offset:2048
	ds_read_b128 v[140:143], v233 offset:3072
	s_add_u32 m0, s19, 4096
	s_nop 0
	global_load_lds_dwordx4 v225, s[0:1]
	v_mfma_f32_16x16x32_bf16 v[32:35], v[176:179], v[200:203], v[32:35]
	v_mfma_f32_16x16x32_bf16 v[36:39], v[180:183], v[200:203], v[36:39]
	v_mfma_f32_16x16x32_bf16 v[40:43], v[184:187], v[200:203], v[40:43]
	v_mfma_f32_16x16x32_bf16 v[44:47], v[188:191], v[200:203], v[44:47]
	ds_read_b128 v[144:147], v232 offset:0
	ds_read_b128 v[148:151], v232 offset:1024
	s_add_u32 m0, s19, 8192
	s_nop 0
	global_load_lds_dwordx4 v226, s[0:1]
	v_mfma_f32_16x16x32_bf16 v[48:51], v[176:179], v[204:207], v[48:51]
	v_mfma_f32_16x16x32_bf16 v[52:55], v[180:183], v[204:207], v[52:55]
	v_mfma_f32_16x16x32_bf16 v[56:59], v[184:187], v[204:207], v[56:59]
	v_mfma_f32_16x16x32_bf16 v[60:63], v[188:191], v[204:207], v[60:63]
	ds_read_b128 v[152:155], v232 offset:2048
	ds_read_b128 v[156:159], v232 offset:3072
	s_add_u32 m0, s19, 12288
	s_nop 0
	global_load_lds_dwordx4 v227, s[0:1]
	v_mfma_f32_16x16x32_bf16 v[64:67], v[176:179], v[208:211], v[64:67]
	v_mfma_f32_16x16x32_bf16 v[68:71], v[180:183], v[208:211], v[68:71]
	v_mfma_f32_16x16x32_bf16 v[72:75], v[184:187], v[208:211], v[72:75]
	v_mfma_f32_16x16x32_bf16 v[76:79], v[188:191], v[208:211], v[76:79]
	ds_read_b128 v[160:163], v232 offset:4096
	s_add_u32 m0, s19, 16384
	s_nop 0
	global_load_lds_dwordx4 v228, s[2:3]
	v_mfma_f32_16x16x32_bf16 v[80:83], v[176:179], v[212:215], v[80:83]
	v_mfma_f32_16x16x32_bf16 v[84:87], v[180:183], v[212:215], v[84:87]
	v_mfma_f32_16x16x32_bf16 v[88:91], v[184:187], v[212:215], v[88:91]
	v_mfma_f32_16x16x32_bf16 v[92:95], v[188:191], v[212:215], v[92:95]
	ds_read_b128 v[164:167], v232 offset:5120
	s_add_u32 m0, s19, 20480
	s_nop 0
	global_load_lds_dwordx4 v229, s[2:3]
	s_cmp_eq_u32 s18, 0
	s_cbranch_scc0 .Lg6_hi1
	s_setprio 0
.Lg6_hi1:
	v_mfma_f32_16x16x32_bf16 v[96:99], v[176:179], v[216:219], v[96:99]
	v_mfma_f32_16x16x32_bf16 v[100:103], v[180:183], v[216:219], v[100:103]
	v_mfma_f32_16x16x32_bf16 v[104:107], v[184:187], v[216:219], v[104:107]
	v_mfma_f32_16x16x32_bf16 v[108:111], v[188:191], v[216:219], v[108:111]
	ds_read_b128 v[168:171], v232 offset:6144
	s_add_u32 s0, s0, 64
	s_addc_u32 s1, s1, 0
	s_add_u32 s2, s2, 64
	s_addc_u32 s3, s3, 0
	s_add_u32 s22, s22, 1
	s_add_u32 s99, s99, 24576
	s_cmp_eq_u32 s99, 73728
	s_cselect_b32 s99, 0, s99
	s_add_u32 s100, s100, 24576
	s_cmp_eq_u32 s100, 73728
	s_cselect_b32 s100, 0, s100
	v_mfma_f32_16x16x32_bf16 v[112:115], v[176:179], v[220:223], v[112:115]
	v_mfma_f32_16x16x32_bf16 v[116:119], v[180:183], v[220:223], v[116:119]
	v_mfma_f32_16x16x32_bf16 v[120:123], v[184:187], v[220:223], v[120:123]
	v_mfma_f32_16x16x32_bf16 v[124:127], v[188:191], v[220:223], v[124:127]
	ds_read_b128 v[172:175], v232 offset:7168
	s_add_u32 s101, s101, 2
	s_cmp_lt_u32 s101, 44
	s_cbranch_scc1 .Lg6_kloop
	s_cmp_eq_u32 s22, 16
	s_cbranch_scc1 .Lg6_sw2

; #define LWRITE(S, buf) do { bf16_t* sA_ = sbase + (buf) * BUF; bf16_t* sB_ = sA_ + 256 * PITCH; \
;     _Pragma("unroll") for (int i_ = 0; i_ < 4; ++i_) *(u32x4*)(sA_ + (sr + i_ * 64) * PITCH + scv * 8) = ra[S][i_]; \
;     _Pragma("unroll") for (int i_ = 0; i_ < 2; ++i_) *(u32x4*)(sB_ + (sr + i_ * 64) * PITCH + scv * 8) = rb[S][i_]; } while (0)
; template <class Epi>
; DI void gemm_tile(char* smem, const bf16_t* __restrict__ A0, int lda0, int ksplit, const bf16_t* __restrict__ A1, int lda1,
;                   const bf16_t* __restrict__ Bt, int K, int row0, int col0, const Epi& epi, int tid) {
;     ...
;   __syncthreads();
;   {
;     const int last = nk - 1;
;     GLOAD(0, 0);
;     __builtin_amdgcn_sched_barrier(0);
;     GLOAD(1, 1);
;     __builtin_amdgcn_sched_barrier(0);
;     LWRITE(0, 0);
;     __builtin_amdgcn_sched_barrier(0);
;     GLOAD(0, (2 < last ? 2 : last));
;     __builtin_amdgcn_sched_barrier(0);
;     __syncthreads();
;     for (int kt = 0; kt < nk; kt += 2) {
;       LWRITE(1, 1);
;       __builtin_amdgcn_sched_barrier(0);
;       GLOAD(1, (kt + 3 < last ? kt + 3 : last));
;       __builtin_amdgcn_sched_barrier(0);
;       COMPUTE(0);
;       __syncthreads();
;       LWRITE(0, 0);
;       __builtin_amdgcn_sched_barrier(0);
;       GLOAD(0, (kt + 4 < last ? kt + 4 : last));
;       __builtin_amdgcn_sched_barrier(0);
;       COMPUTE(1);
;       __syncthreads();
.Lg6_hi2:
	v_mfma_f32_16x16x32_bf16 v[96:99], v[128:131], v[168:171], v[96:99]
	v_mfma_f32_16x16x32_bf16 v[100:103], v[132:135], v[168:171], v[100:103]
	v_mfma_f32_16x16x32_bf16 v[104:107], v[136:139], v[168:171], v[104:107]
	v_mfma_f32_16x16x32_bf16 v[108:111], v[140:143], v[168:171], v[108:111]
	ds_read_b128 v[216:219], v232 offset:6144
	s_add_u32 s0, s0, 64
	s_addc_u32 s1, s1, 0
	s_add_u32 s2, s2, 64
	s_addc_u32 s3, s3, 0
	s_add_u32 s22, s22, 1
	s_add_u32 s99, s99, 24576
	s_cmp_eq_u32 s99, 73728
	s_cselect_b32 s99, 0, s99
	s_add_u32 s100, s100, 24576
	s_cmp_eq_u32 s100, 73728
	s_cselect_b32 s100, 0, s100
	v_mfma_f32_16x16x32_bf16 v[112:115], v[128:131], v[172:175], v[112:115]
	v_mfma_f32_16x16x32_bf16 v[116:119], v[132:135], v[172:175], v[116:119]
	v_mfma_f32_16x16x32_bf16 v[120:123], v[136:139], v[172:175], v[120:123]
	v_mfma_f32_16x16x32_bf16 v[124:127], v[140:143], v[172:175], v[124:127]
	ds_read_b128 v[220:223], v232 offset:7168
	s_waitcnt vmcnt(6)
	s_waitcnt lgkmcnt(0)
	s_barrier
	v_add_u32_e32 v232, s100, v230
	v_add_u32_e32 v233, s100, v231
	s_setprio 1
	v_mfma_f32_16x16x32_bf16 v[0:3], v[176:179], v[192:195], v[0:3]
	v_mfma_f32_16x16x32_bf16 v[4:7], v[180:183], v[192:195], v[4:7]
	v_mfma_f32_16x16x32_bf16 v[8:11], v[184:187], v[192:195], v[8:11]
	v_mfma_f32_16x16x32_bf16 v[12:15], v[188:191], v[192:195], v[12:15]
	ds_read_b128 v[128:131], v233 offset:0
	ds_read_b128 v[132:135], v233 offset:1024
	v_mfma_f32_16x16x32_bf16 v[16:19], v[176:179], v[196:199], v[16:19]
	v_mfma_f32_16x16x32_bf16 v[20:23], v[180:183], v[196:199], v[20:23]
	v_mfma_f32_16x16x32_bf16 v[24:27], v[184:187], v[196:199], v[24:27]
	v_mfma_f32_16x16x32_bf16 v[28:31], v[188:191], v[196:199], v[28:31]
	ds_read_b128 v[136:139], v233 offset:2048
	ds_read_b128 v[140:143], v233 offset:3072
	v_mfma_f32_16x16x32_bf16 v[32:35], v[176:179], v[200:203], v[32:35]
	v_mfma_f32_16x16x32_bf16 v[36:39], v[180:183], v[200:203], v[36:39]
	v_mfma_f32_16x16x32_bf16 v[40:43], v[184:187], v[200:203], v[40:43]
	v_mfma_f32_16x16x32_bf16 v[44:47], v[188:191], v[200:203], v[44:47]
	ds_read_b128 v[144:147], v232 offset:0
	ds_read_b128 v[148:151], v232 offset:1024
	v_mfma_f32_16x16x32_bf16 v[48:51], v[176:179], v[204:207], v[48:51]
	v_mfma_f32_16x16x32_bf16 v[52:55], v[180:183], v[204:207], v[52:55]
	v_mfma_f32_16x16x32_bf16 v[56:59], v[184:187], v[204:207], v[56:59]
	v_mfma_f32_16x16x32_bf16 v[60:63], v[188:191], v[204:207], v[60:63]
	ds_read_b128 v[152:155], v232 offset:2048
	ds_read_b128 v[156:159], v232 offset:3072
	v_mfma_f32_16x16x32_bf16 v[64:67], v[176:179], v[208:211], v[64:67]
	v_mfma_f32_16x16x32_bf16 v[68:71], v[180:183], v[208:211], v[68:71]
	v_mfma_f32_16x16x32_bf16 v[72:75], v[184:187], v[208:211], v[72:75]
	v_mfma_f32_16x16x32_bf16 v[76:79], v[188:191], v[208:211], v[76:79]
	ds_read_b128 v[160:163], v232 offset:4096
	v_mfma_f32_16x16x32_bf16 v[80:83], v[176:179], v[212:215], v[80:83]
	v_mfma_f32_16x16x32_bf16 v[84:87], v[180:183], v[212:215], v[84:87]
	v_mfma_f32_16x16x32_bf16 v[88:91], v[184:187], v[212:215], v[88:91]
	v_mfma_f32_16x16x32_bf16 v[92:95], v[188:191], v[212:215], v[92:95]
	ds_read_b128 v[164:167], v232 offset:5120
	s_cmp_eq_u32 s18, 0
	s_cbranch_scc0 .Lg6_hi3
	s_setprio 0
; #define LWRITE(S, buf) do { bf16_t* sA_ = sbase + (buf) * BUF; bf16_t* sB_ = sA_ + 256 * PITCH; \
;     _Pragma("unroll") for (int i_ = 0; i_ < 4; ++i_) *(u32x4*)(sA_ + (sr + i_ * 64) * PITCH + scv * 8) = ra[S][i_]; \
;     _Pragma("unroll") for (int i_ = 0; i_ < 2; ++i_) *(u32x4*)(sB_ + (sr + i_ * 64) * PITCH + scv * 8) = rb[S][i_]; } while (0)
; template <class Epi>
; DI void gemm_tile(char* smem, const bf16_t* __restrict__ A0, int lda0, int ksplit, const bf16_t* __restrict__ A1, int lda1,
;                   const bf16_t* __restrict__ Bt, int K, int row0, int col0, const Epi& epi, int tid) {
;     ...
;   __syncthreads();
;   {
;     const int last = nk - 1;
;     GLOAD(0, 0);
;     __builtin_amdgcn_sched_barrier(0);
;     GLOAD(1, 1);
;     __builtin_amdgcn_sched_barrier(0);
;     LWRITE(0, 0);
;     __builtin_amdgcn_sched_barrier(0);
;     GLOAD(0, (2 < last ? 2 : last));
;     __builtin_amdgcn_sched_barrier(0);
;     __syncthreads();
;     for (int kt = 0; kt < nk; kt += 2) {
;       LWRITE(1, 1);
;       __builtin_amdgcn_sched_barrier(0);
;       GLOAD(1, (kt + 3 < last ? kt + 3 : last));
;       __builtin_amdgcn_sched_barrier(0);
;       COMPUTE(0);
;       __syncthreads();
;       LWRITE(0, 0);
;       __builtin_amdgcn_sched_barrier(0);
;       GLOAD(0, (kt + 4 < last ? kt + 4 : last));
;       __builtin_amdgcn_sched_barrier(0);
;       COMPUTE(1);
;       __syncthreads();
;     }
.Lg6_hi3:
	v_mfma_f32_16x16x32_bf16 v[96:99], v[176:179], v[216:219], v[96:99]
	v_mfma_f32_16x16x32_bf16 v[100:103], v[180:183], v[216:219], v[100:103]
	v_mfma_f32_16x16x32_bf16 v[104:107], v[184:187], v[216:219], v[104:107]
	v_mfma_f32_16x16x32_bf16 v[108:111], v[188:191], v[216:219], v[108:111]
	ds_read_b128 v[168:171], v232 offset:6144
	s_add_u32 s100, s100, 24576
	s_cmp_eq_u32 s100, 73728
	s_cselect_b32 s100, 0, s100
	v_mfma_f32_16x16x32_bf16 v[112:115], v[176:179], v[220:223], v[112:115]
	v_mfma_f32_16x16x32_bf16 v[116:119], v[180:183], v[220:223], v[116:119]
	v_mfma_f32_16x16x32_bf16 v[120:123], v[184:187], v[220:223], v[120:123]
	v_mfma_f32_16x16x32_bf16 v[124:127], v[188:191], v[220:223], v[124:127]
	ds_read_b128 v[172:175], v232 offset:7168
	s_waitcnt vmcnt(0)
	s_waitcnt lgkmcnt(0)
	s_barrier
	v_add_u32_e32 v232, s100, v230
	v_add_u32_e32 v233, s100, v231
	s_setprio 1
	v_mfma_f32_16x16x32_bf16 v[0:3], v[128:131], v[144:147], v[0:3]
	v_mfma_f32_16x16x32_bf16 v[4:7], v[132:135], v[144:147], v[4:7]
	v_mfma_f32_16x16x32_bf16 v[8:11], v[136:139], v[144:147], v[8:11]
	v_mfma_f32_16x16x32_bf16 v[12:15], v[140:143], v[144:147], v[12:15]
	ds_read_b128 v[176:179], v233 offset:0
	ds_read_b128 v[180:183], v233 offset:1024
	v_mfma_f32_16x16x32_bf16 v[16:19], v[128:131], v[148:151], v[16:19]
	v_mfma_f32_16x16x32_bf16 v[20:23], v[132:135], v[148:151], v[20:23]
	v_mfma_f32_16x16x32_bf16 v[24:27], v[136:139], v[148:151], v[24:27]
	v_mfma_f32_16x16x32_bf16 v[28:31], v[140:143], v[148:151], v[28:31]
	ds_read_b128 v[184:187], v233 offset:2048
	ds_read_b128 v[188:191], v233 offset:3072
	v_mfma_f32_16x16x32_bf16 v[32:35], v[128:131], v[152:155], v[32:35]
	v_mfma_f32_16x16x32_bf16 v[36:39], v[132:135], v[152:155], v[36:39]
	v_mfma_f32_16x16x32_bf16 v[40:43], v[136:139], v[152:155], v[40:43]
	v_mfma_f32_16x16x32_bf16 v[44:47], v[140:143], v[152:155], v[44:47]
	ds_read_b128 v[192:195], v232 offset:0
	ds_read_b128 v[196:199], v232 offset:1024
	v_mfma_f32_16x16x32_bf16 v[48:51], v[128:131], v[156:159], v[48:51]
	v_mfma_f32_16x16x32_bf16 v[52:55], v[132:135], v[156:159], v[52:55]
	v_mfma_f32_16x16x32_bf16 v[56:59], v[136:139], v[156:159], v[56:59]
	v_mfma_f32_16x16x32_bf16 v[60:63], v[140:143], v[156:159], v[60:63]
	ds_read_b128 v[200:203], v232 offset:2048
	ds_read_b128 v[204:207], v232 offset:3072
	v_mfma_f32_16x16x32_bf16 v[64:67], v[128:131], v[160:163], v[64:67]
	v_mfma_f32_16x16x32_bf16 v[68:71], v[132:135], v[160:163], v[68:71]
	v_mfma_f32_16x16x32_bf16 v[72:75], v[136:139], v[160:163], v[72:75]
	v_mfma_f32_16x16x32_bf16 v[76:79], v[140:143], v[160:163], v[76:79]
	ds_read_b128 v[208:211], v232 offset:4096
	v_mfma_f32_16x16x32_bf16 v[80:83], v[128:131], v[164:167], v[80:83]
	v_mfma_f32_16x16x32_bf16 v[84:87], v[132:135], v[164:167], v[84:87]
	v_mfma_f32_16x16x32_bf16 v[88:91], v[136:139], v[164:167], v[88:91]
	v_mfma_f32_16x16x32_bf16 v[92:95], v[140:143], v[164:167], v[92:95]
	ds_read_b128 v[212:215], v232 offset:5120
	s_cmp_eq_u32 s18, 0
	s_cbranch_scc0 .Lg6_hi4
	s_setprio 0
.Lg6_hi4:
	v_mfma_f32_16x16x32_bf16 v[96:99], v[128:131], v[168:171], v[96:99]
	v_mfma_f32_16x16x32_bf16 v[100:103], v[132:135], v[168:171], v[100:103]
	v_mfma_f32_16x16x32_bf16 v[104:107], v[136:139], v[168:171], v[104:107]
	v_mfma_f32_16x16x32_bf16 v[108:111], v[140:143], v[168:171], v[108:111]
	ds_read_b128 v[216:219], v232 offset:6144
	s_add_u32 s100, s100, 24576
	s_cmp_eq_u32 s100, 73728
	s_cselect_b32 s100, 0, s100
	v_mfma_f32_16x16x32_bf16 v[112:115], v[128:131], v[172:175], v[112:115]
	v_mfma_f32_16x16x32_bf16 v[116:119], v[132:135], v[172:175], v[116:119]
	v_mfma_f32_16x16x32_bf16 v[120:123], v[136:139], v[172:175], v[120:123]
	v_mfma_f32_16x16x32_bf16 v[124:127], v[140:143], v[172:175], v[124:127]
	ds_read_b128 v[220:223], v232 offset:7168
	s_waitcnt lgkmcnt(0)
	s_barrier
	s_setprio 1
	v_mfma_f32_16x16x32_bf16 v[0:3], v[176:179], v[192:195], v[0:3]
	v_mfma_f32_16x16x32_bf16 v[4:7], v[180:183], v[192:195], v[4:7]
	v_mfma_f32_16x16x32_bf16 v[8:11], v[184:187], v[192:195], v[8:11]
	v_mfma_f32_16x16x32_bf16 v[12:15], v[188:191], v[192:195], v[12:15]
	v_mfma_f32_16x16x32_bf16 v[16:19], v[176:179], v[196:199], v[16:19]
	v_mfma_f32_16x16x32_bf16 v[20:23], v[180:183], v[196:199], v[20:23]
	v_mfma_f32_16x16x32_bf16 v[24:27], v[184:187], v[196:199], v[24:27]
	v_mfma_f32_16x16x32_bf16 v[28:31], v[188:191], v[196:199], v[28:31]
	v_mfma_f32_16x16x32_bf16 v[32:35], v[176:179], v[200:203], v[32:35]
	v_mfma_f32_16x16x32_bf16 v[36:39], v[180:183], v[200:203], v[36:39]
	v_mfma_f32_16x16x32_bf16 v[40:43], v[184:187], v[200:203], v[40:43]
	v_mfma_f32_16x16x32_bf16 v[44:47], v[188:191], v[200:203], v[44:47]
	v_mfma_f32_16x16x32_bf16 v[48:51], v[176:179], v[204:207], v[48:51]
	v_mfma_f32_16x16x32_bf16 v[52:55], v[180:183], v[204:207], v[52:55]
	v_mfma_f32_16x16x32_bf16 v[56:59], v[184:187], v[204:207], v[56:59]
	v_mfma_f32_16x16x32_bf16 v[60:63], v[188:191], v[204:207], v[60:63]
	v_mfma_f32_16x16x32_bf16 v[64:67], v[176:179], v[208:211], v[64:67]
	v_mfma_f32_16x16x32_bf16 v[68:71], v[180:183], v[208:211], v[68:71]
	v_mfma_f32_16x16x32_bf16 v[72:75], v[184:187], v[208:211], v[72:75]
	v_mfma_f32_16x16x32_bf16 v[76:79], v[188:191], v[208:211], v[76:79]
	v_mfma_f32_16x16x32_bf16 v[80:83], v[176:179], v[212:215], v[80:83]
	v_mfma_f32_16x16x32_bf16 v[84:87], v[180:183], v[212:215], v[84:87]
	v_mfma_f32_16x16x32_bf16 v[88:91], v[184:187], v[212:215], v[88:91]
	v_mfma_f32_16x16x32_bf16 v[92:95], v[188:191], v[212:215], v[92:95]
	s_cmp_eq_u32 s18, 0
	s_cbranch_scc0 .Lg6_hi5
	s_setprio 0

; #define LWRITE(S, buf) do { bf16_t* sA_ = sbase + (buf) * BUF; bf16_t* sB_ = sA_ + 256 * PITCH; \
;     _Pragma("unroll") for (int i_ = 0; i_ < 4; ++i_) *(u32x4*)(sA_ + (sr + i_ * 64) * PITCH + scv * 8) = ra[S][i_]; \
;     _Pragma("unroll") for (int i_ = 0; i_ < 2; ++i_) *(u32x4*)(sB_ + (sr + i_ * 64) * PITCH + scv * 8) = rb[S][i_]; } while (0)
; template <class Epi>
; DI void gemm_tile(char* smem, const bf16_t* __restrict__ A0, int lda0, int ksplit, const bf16_t* __restrict__ A1, int lda1,
;                   const bf16_t* __restrict__ Bt, int K, int row0, int col0, const Epi& epi, int tid) {
;     ...
;   __syncthreads();
;   {
;     const int last = nk - 1;
;     GLOAD(0, 0);
;     __builtin_amdgcn_sched_barrier(0);
;     GLOAD(1, 1);
;     __builtin_amdgcn_sched_barrier(0);
;     LWRITE(0, 0);
;     __builtin_amdgcn_sched_barrier(0);
;     GLOAD(0, (2 < last ? 2 : last));
;     __builtin_amdgcn_sched_barrier(0);
;     __syncthreads();
;     for (int kt = 0; kt < nk; kt += 2) {
;       LWRITE(1, 1);
;       __builtin_amdgcn_sched_barrier(0);
;       GLOAD(1, (kt + 3 < last ? kt + 3 : last));
;       __builtin_amdgcn_sched_barrier(0);
;       COMPUTE(0);
;       __syncthreads();
;       LWRITE(0, 0);
;       __builtin_amdgcn_sched_barrier(0);
;       GLOAD(0, (kt + 4 < last ? kt + 4 : last));
;       __builtin_amdgcn_sched_barrier(0);
;       COMPUTE(1);
.Lg8_kloop:
	s_waitcnt vmcnt(6)
	s_waitcnt lgkmcnt(0)
	s_barrier
	v_add_u32_e32 v232, s98, v230
	v_add_u32_e32 v233, s98, v231
	s_add_u32 s11, s19, s101
	s_setprio 1
	v_mfma_f32_16x16x32_bf16 v[0:3], v[128:131], v[144:147], v[0:3]
	v_mfma_f32_16x16x32_bf16 v[4:7], v[132:135], v[144:147], v[4:7]
	v_mfma_f32_16x16x32_bf16 v[8:11], v[136:139], v[144:147], v[8:11]
	v_mfma_f32_16x16x32_bf16 v[12:15], v[140:143], v[144:147], v[12:15]
	ds_read_b128 v[176:179], v233 offset:0
	ds_read_b128 v[180:183], v233 offset:1024
	s_add_u32 m0, s11, 0
	s_nop 0
	global_load_lds_dwordx4 v224, s[0:1]
	v_mfma_f32_16x16x32_bf16 v[16:19], v[128:131], v[148:151], v[16:19]
	v_mfma_f32_16x16x32_bf16 v[20:23], v[132:135], v[148:151], v[20:23]
	v_mfma_f32_16x16x32_bf16 v[24:27], v[136:139], v[148:151], v[24:27]
	v_mfma_f32_16x16x32_bf16 v[28:31], v[140:143], v[148:151], v[28:31]
	ds_read_b128 v[184:187], v233 offset:2048
	ds_read_b128 v[188:191], v233 offset:3072
	s_add_u32 m0, s11, 4096
	s_nop 0
	global_load_lds_dwordx4 v225, s[0:1]
	v_mfma_f32_16x16x32_bf16 v[32:35], v[128:131], v[152:155], v[32:35]
	v_mfma_f32_16x16x32_bf16 v[36:39], v[132:135], v[152:155], v[36:39]
	v_mfma_f32_16x16x32_bf16 v[40:43], v[136:139], v[152:155], v[40:43]
	v_mfma_f32_16x16x32_bf16 v[44:47], v[140:143], v[152:155], v[44:47]
	ds_read_b128 v[192:195], v232 offset:0
	ds_read_b128 v[196:199], v232 offset:1024
	s_add_u32 m0, s11, 8192
	s_nop 0
	global_load_lds_dwordx4 v226, s[0:1]
	v_mfma_f32_16x16x32_bf16 v[48:51], v[128:131], v[156:159], v[48:51]
	v_mfma_f32_16x16x32_bf16 v[52:55], v[132:135], v[156:159], v[52:55]
	v_mfma_f32_16x16x32_bf16 v[56:59], v[136:139], v[156:159], v[56:59]
	v_mfma_f32_16x16x32_bf16 v[60:63], v[140:143], v[156:159], v[60:63]
	ds_read_b128 v[200:203], v232 offset:2048
	ds_read_b128 v[204:207], v232 offset:3072
	s_add_u32 m0, s11, 12288
	s_nop 0
	global_load_lds_dwordx4 v227, s[0:1]
	v_mfma_f32_16x16x32_bf16 v[64:67], v[128:131], v[160:163], v[64:67]
	v_mfma_f32_16x16x32_bf16 v[68:71], v[132:135], v[160:163], v[68:71]
	v_mfma_f32_16x16x32_bf16 v[72:75], v[136:139], v[160:163], v[72:75]
	v_mfma_f32_16x16x32_bf16 v[76:79], v[140:143], v[160:163], v[76:79]
	ds_read_b128 v[208:211], v232 offset:4096
	s_add_u32 m0, s11, 16384
	s_nop 0
	global_load_lds_dwordx4 v228, s[2:3]
	v_mfma_f32_16x16x32_bf16 v[80:83], v[128:131], v[164:167], v[80:83]
	v_mfma_f32_16x16x32_bf16 v[84:87], v[132:135], v[164:167], v[84:87]
	v_mfma_f32_16x16x32_bf16 v[88:91], v[136:139], v[164:167], v[88:91]
	v_mfma_f32_16x16x32_bf16 v[92:95], v[140:143], v[164:167], v[92:95]
	ds_read_b128 v[212:215], v232 offset:5120
	s_add_u32 m0, s11, 20480
	s_nop 0
	global_load_lds_dwordx4 v229, s[2:3]
	s_cmp_eq_u32 s10, 0
	s_cbranch_scc0 .Lg8_hi0
	s_setprio 0
.Lg8_hi0:
	v_mfma_f32_16x16x32_bf16 v[96:99], v[128:131], v[168:171], v[96:99]
	v_mfma_f32_16x16x32_bf16 v[100:103], v[132:135], v[168:171], v[100:103]
	v_mfma_f32_16x16x32_bf16 v[104:107], v[136:139], v[168:171], v[104:107]
	v_mfma_f32_16x16x32_bf16 v[108:111], v[140:143], v[168:171], v[108:111]
	ds_read_b128 v[216:219], v232 offset:6144
	s_add_u32 s0, s0, 64
	s_addc_u32 s1, s1, 0
	s_add_u32 s2, s2, 64
	s_addc_u32 s3, s3, 0
	s_add_u32 s100, s100, 1
	s_add_u32 s19, s19, 24576
	s_cmp_eq_u32 s19, 73728
	s_cselect_b32 s19, 0, s19
	s_add_u32 s98, s98, 24576
	s_cmp_eq_u32 s98, 73728
	s_cselect_b32 s98, 0, s98
	v_mfma_f32_16x16x32_bf16 v[112:115], v[128:131], v[172:175], v[112:115]
	v_mfma_f32_16x16x32_bf16 v[116:119], v[132:135], v[172:175], v[116:119]
	v_mfma_f32_16x16x32_bf16 v[120:123], v[136:139], v[172:175], v[120:123]
	v_mfma_f32_16x16x32_bf16 v[124:127], v[140:143], v[172:175], v[124:127]
	ds_read_b128 v[220:223], v232 offset:7168
	s_waitcnt vmcnt(6)
	s_waitcnt lgkmcnt(0)
	s_barrier
	v_add_u32_e32 v232, s98, v230
	v_add_u32_e32 v233, s98, v231
	s_add_u32 s11, s19, s101
	s_setprio 1
	v_mfma_f32_16x16x32_bf16 v[0:3], v[176:179], v[192:195], v[0:3]
	v_mfma_f32_16x16x32_bf16 v[4:7], v[180:183], v[192:195], v[4:7]
	v_mfma_f32_16x16x32_bf16 v[8:11], v[184:187], v[192:195], v[8:11]
	v_mfma_f32_16x16x32_bf16 v[12:15], v[188:191], v[192:195], v[12:15]
	ds_read_b128 v[128:131], v233 offset:0
	ds_read_b128 v[132:135], v233 offset:1024
	s_add_u32 m0, s11, 0
	s_nop 0
	global_load_lds_dwordx4 v224, s[0:1]
	v_mfma_f32_16x16x32_bf16 v[16:19], v[176:179], v[196:199], v[16:19]
	v_mfma_f32_16x16x32_bf16 v[20:23], v[180:183], v[196:199], v[20:23]
	v_mfma_f32_16x16x32_bf16 v[24:27], v[184:187], v[196:199], v[24:27]
	v_mfma_f32_16x16x32_bf16 v[28:31], v[188:191], v[196:199], v[28:31]
	ds_read_b128 v[136:139], v233 offset:2048
	ds_read_b128 v[140:143], v233 offset:3072
	s_add_u32 m0, s11, 4096
	s_nop 0
	global_load_lds_dwordx4 v225, s[0:1]
	v_mfma_f32_16x16x32_bf16 v[32:35], v[176:179], v[200:203], v[32:35]
	v_mfma_f32_16x16x32_bf16 v[36:39], v[180:183], v[200:203], v[36:39]
	v_mfma_f32_16x16x32_bf16 v[40:43], v[184:187], v[200:203], v[40:43]
	v_mfma_f32_16x16x32_bf16 v[44:47], v[188:191], v[200:203], v[44:47]
	ds_read_b128 v[144:147], v232 offset:0
	ds_read_b128 v[148:151], v232 offset:1024
	s_add_u32 m0, s11, 8192
	s_nop 0
	global_load_lds_dwordx4 v226, s[0:1]
	v_mfma_f32_16x16x32_bf16 v[48:51], v[176:179], v[204:207], v[48:51]
	v_mfma_f32_16x16x32_bf16 v[52:55], v[180:183], v[204:207], v[52:55]
	v_mfma_f32_16x16x32_bf16 v[56:59], v[184:187], v[204:207], v[56:59]
	v_mfma_f32_16x16x32_bf16 v[60:63], v[188:191], v[204:207], v[60:63]
	ds_read_b128 v[152:155], v232 offset:2048
	ds_read_b128 v[156:159], v232 offset:3072
	s_add_u32 m0, s11, 12288
	s_nop 0
	global_load_lds_dwordx4 v227, s[0:1]
	v_mfma_f32_16x16x32_bf16 v[64:67], v[176:179], v[208:211], v[64:67]
	v_mfma_f32_16x16x32_bf16 v[68:71], v[180:183], v[208:211], v[68:71]
	v_mfma_f32_16x16x32_bf16 v[72:75], v[184:187], v[208:211], v[72:75]
	v_mfma_f32_16x16x32_bf16 v[76:79], v[188:191], v[208:211], v[76:79]
	ds_read_b128 v[160:163], v232 offset:4096
	s_add_u32 m0, s11, 16384
	s_nop 0
	global_load_lds_dwordx4 v228, s[2:3]
	v_mfma_f32_16x16x32_bf16 v[80:83], v[176:179], v[212:215], v[80:83]
	v_mfma_f32_16x16x32_bf16 v[84:87], v[180:183], v[212:215], v[84:87]
	v_mfma_f32_16x16x32_bf16 v[88:91], v[184:187], v[212:215], v[88:91]
	v_mfma_f32_16x16x32_bf16 v[92:95], v[188:191], v[212:215], v[92:95]
	ds_read_b128 v[164:167], v232 offset:5120
	s_add_u32 m0, s11, 20480
	s_nop 0
	global_load_lds_dwordx4 v229, s[2:3]
	s_cmp_eq_u32 s10, 0
	s_cbranch_scc0 .Lg8_hi1
	s_setprio 0
; #define LWRITE(S, buf) do { bf16_t* sA_ = sbase + (buf) * BUF; bf16_t* sB_ = sA_ + 256 * PITCH; \
;     _Pragma("unroll") for (int i_ = 0; i_ < 4; ++i_) *(u32x4*)(sA_ + (sr + i_ * 64) * PITCH + scv * 8) = ra[S][i_]; \
;     _Pragma("unroll") for (int i_ = 0; i_ < 2; ++i_) *(u32x4*)(sB_ + (sr + i_ * 64) * PITCH + scv * 8) = rb[S][i_]; } while (0)
; template <class Epi>
; DI void gemm_tile(char* smem, const bf16_t* __restrict__ A0, int lda0, int ksplit, const bf16_t* __restrict__ A1, int lda1,
;                   const bf16_t* __restrict__ Bt, int K, int row0, int col0, const Epi& epi, int tid) {
;     ...
;   __syncthreads();
;   {
;     const int last = nk - 1;
;     GLOAD(0, 0);
;     __builtin_amdgcn_sched_barrier(0);
;     GLOAD(1, 1);
;     __builtin_amdgcn_sched_barrier(0);
;     LWRITE(0, 0);
;     __builtin_amdgcn_sched_barrier(0);
;     GLOAD(0, (2 < last ? 2 : last));
;     __builtin_amdgcn_sched_barrier(0);
;     __syncthreads();
;     for (int kt = 0; kt < nk; kt += 2) {
;       LWRITE(1, 1);
;       __builtin_amdgcn_sched_barrier(0);
;       GLOAD(1, (kt + 3 < last ? kt + 3 : last));
;       __builtin_amdgcn_sched_barrier(0);
;       COMPUTE(0);
;       __syncthreads();
;       LWRITE(0, 0);
;       __builtin_amdgcn_sched_barrier(0);
;       GLOAD(0, (kt + 4 < last ? kt + 4 : last));
;       __builtin_amdgcn_sched_barrier(0);
;       COMPUTE(1);
;       __syncthreads();
.Lg8_hi1:
	v_mfma_f32_16x16x32_bf16 v[96:99], v[176:179], v[216:219], v[96:99]
	v_mfma_f32_16x16x32_bf16 v[100:103], v[180:183], v[216:219], v[100:103]
	v_mfma_f32_16x16x32_bf16 v[104:107], v[184:187], v[216:219], v[104:107]
	v_mfma_f32_16x16x32_bf16 v[108:111], v[188:191], v[216:219], v[108:111]
	ds_read_b128 v[168:171], v232 offset:6144
	s_add_u32 s0, s0, 64
	s_addc_u32 s1, s1, 0
	s_add_u32 s2, s2, 64
	s_addc_u32 s3, s3, 0
	s_add_u32 s100, s100, 1
	s_add_u32 s19, s19, 24576
	s_cmp_eq_u32 s19, 73728
	s_cselect_b32 s19, 0, s19
	s_add_u32 s98, s98, 24576
	s_cmp_eq_u32 s98, 73728
	s_cselect_b32 s98, 0, s98
	v_mfma_f32_16x16x32_bf16 v[112:115], v[176:179], v[220:223], v[112:115]
	v_mfma_f32_16x16x32_bf16 v[116:119], v[180:183], v[220:223], v[116:119]
	v_mfma_f32_16x16x32_bf16 v[120:123], v[184:187], v[220:223], v[120:123]
	v_mfma_f32_16x16x32_bf16 v[124:127], v[188:191], v[220:223], v[124:127]
	ds_read_b128 v[172:175], v232 offset:7168
	s_add_u32 s99, s99, 2
	s_cmp_lt_u32 s99, 28
	s_cbranch_scc1 .Lg8_kloop
	s_waitcnt vmcnt(6)
	s_waitcnt lgkmcnt(0)
	s_barrier
	v_add_u32_e32 v232, s98, v230
	v_add_u32_e32 v233, s98, v231
	s_add_u32 s11, s19, s101
	s_setprio 1
	v_mfma_f32_16x16x32_bf16 v[0:3], v[128:131], v[144:147], v[0:3]
	v_mfma_f32_16x16x32_bf16 v[4:7], v[132:135], v[144:147], v[4:7]
	v_mfma_f32_16x16x32_bf16 v[8:11], v[136:139], v[144:147], v[8:11]
	v_mfma_f32_16x16x32_bf16 v[12:15], v[140:143], v[144:147], v[12:15]
	ds_read_b128 v[176:179], v233 offset:0
	ds_read_b128 v[180:183], v233 offset:1024
	s_add_u32 m0, s11, 0
	s_nop 0
	global_load_lds_dwordx4 v224, s[0:1]
	v_mfma_f32_16x16x32_bf16 v[16:19], v[128:131], v[148:151], v[16:19]
	v_mfma_f32_16x16x32_bf16 v[20:23], v[132:135], v[148:151], v[20:23]
	v_mfma_f32_16x16x32_bf16 v[24:27], v[136:139], v[148:151], v[24:27]
	v_mfma_f32_16x16x32_bf16 v[28:31], v[140:143], v[148:151], v[28:31]
	ds_read_b128 v[184:187], v233 offset:2048
	ds_read_b128 v[188:191], v233 offset:3072
	s_add_u32 m0, s11, 4096
	s_nop 0
	global_load_lds_dwordx4 v225, s[0:1]
	v_mfma_f32_16x16x32_bf16 v[32:35], v[128:131], v[152:155], v[32:35]
	v_mfma_f32_16x16x32_bf16 v[36:39], v[132:135], v[152:155], v[36:39]
	v_mfma_f32_16x16x32_bf16 v[40:43], v[136:139], v[152:155], v[40:43]
	v_mfma_f32_16x16x32_bf16 v[44:47], v[140:143], v[152:155], v[44:47]
	ds_read_b128 v[192:195], v232 offset:0
	ds_read_b128 v[196:199], v232 offset:1024
	s_add_u32 m0, s11, 8192
	s_nop 0
	global_load_lds_dwordx4 v226, s[0:1]
	v_mfma_f32_16x16x32_bf16 v[48:51], v[128:131], v[156:159], v[48:51]
	v_mfma_f32_16x16x32_bf16 v[52:55], v[132:135], v[156:159], v[52:55]
	v_mfma_f32_16x16x32_bf16 v[56:59], v[136:139], v[156:159], v[56:59]
	v_mfma_f32_16x16x32_bf16 v[60:63], v[140:143], v[156:159], v[60:63]
	ds_read_b128 v[200:203], v232 offset:2048
	ds_read_b128 v[204:207], v232 offset:3072
	s_add_u32 m0, s11, 12288
	s_nop 0
	global_load_lds_dwordx4 v227, s[0:1]
	v_mfma_f32_16x16x32_bf16 v[64:67], v[128:131], v[160:163], v[64:67]
	v_mfma_f32_16x16x32_bf16 v[68:71], v[132:135], v[160:163], v[68:71]
	v_mfma_f32_16x16x32_bf16 v[72:75], v[136:139], v[160:163], v[72:75]
	v_mfma_f32_16x16x32_bf16 v[76:79], v[140:143], v[160:163], v[76:79]
	ds_read_b128 v[208:211], v232 offset:4096
	s_add_u32 m0, s11, 16384
	s_nop 0
	global_load_lds_dwordx4 v228, s[2:3]
	v_mfma_f32_16x16x32_bf16 v[80:83], v[128:131], v[164:167], v[80:83]
	v_mfma_f32_16x16x32_bf16 v[84:87], v[132:135], v[164:167], v[84:87]
	v_mfma_f32_16x16x32_bf16 v[88:91], v[136:139], v[164:167], v[88:91]
	v_mfma_f32_16x16x32_bf16 v[92:95], v[140:143], v[164:167], v[92:95]
	ds_read_b128 v[212:215], v232 offset:5120
	s_add_u32 m0, s11, 20480
	s_nop 0
	global_load_lds_dwordx4 v229, s[2:3]
	s_cmp_eq_u32 s10, 0
	s_cbranch_scc0 .Lg8_hi2
	s_setprio 0
.Lg8_hi2:
	v_mfma_f32_16x16x32_bf16 v[96:99], v[128:131], v[168:171], v[96:99]
	v_mfma_f32_16x16x32_bf16 v[100:103], v[132:135], v[168:171], v[100:103]
	v_mfma_f32_16x16x32_bf16 v[104:107], v[136:139], v[168:171], v[104:107]
	v_mfma_f32_16x16x32_bf16 v[108:111], v[140:143], v[168:171], v[108:111]
	ds_read_b128 v[216:219], v232 offset:6144
	s_add_u32 s0, s0, 64
	s_addc_u32 s1, s1, 0
	s_add_u32 s2, s2, 64
	s_addc_u32 s3, s3, 0
	s_add_u32 s100, s100, 1
	s_add_u32 s19, s19, 24576
	s_cmp_eq_u32 s19, 73728
	s_cselect_b32 s19, 0, s19
	s_add_u32 s98, s98, 24576
	s_cmp_eq_u32 s98, 73728
	s_cselect_b32 s98, 0, s98
	v_mfma_f32_16x16x32_bf16 v[112:115], v[128:131], v[172:175], v[112:115]
	v_mfma_f32_16x16x32_bf16 v[116:119], v[132:135], v[172:175], v[116:119]
	v_mfma_f32_16x16x32_bf16 v[120:123], v[136:139], v[172:175], v[120:123]
	v_mfma_f32_16x16x32_bf16 v[124:127], v[140:143], v[172:175], v[124:127]
	ds_read_b128 v[220:223], v232 offset:7168
	s_waitcnt vmcnt(6)
	s_waitcnt lgkmcnt(0)
	s_barrier
	v_add_u32_e32 v232, s98, v230
	v_add_u32_e32 v233, s98, v231
	s_setprio 1
	v_mfma_f32_16x16x32_bf16 v[0:3], v[176:179], v[192:195], v[0:3]
	v_mfma_f32_16x16x32_bf16 v[4:7], v[180:183], v[192:195], v[4:7]
	v_mfma_f32_16x16x32_bf16 v[8:11], v[184:187], v[192:195], v[8:11]
	v_mfma_f32_16x16x32_bf16 v[12:15], v[188:191], v[192:195], v[12:15]
	ds_read_b128 v[128:131], v233 offset:0
	ds_read_b128 v[132:135], v233 offset:1024
	v_mfma_f32_16x16x32_bf16 v[16:19], v[176:179], v[196:199], v[16:19]
	v_mfma_f32_16x16x32_bf16 v[20:23], v[180:183], v[196:199], v[20:23]
	v_mfma_f32_16x16x32_bf16 v[24:27], v[184:187], v[196:199], v[24:27]
	v_mfma_f32_16x16x32_bf16 v[28:31], v[188:191], v[196:199], v[28:31]
	ds_read_b128 v[136:139], v233 offset:2048
	ds_read_b128 v[140:143], v233 offset:3072
	v_mfma_f32_16x16x32_bf16 v[32:35], v[176:179], v[200:203], v[32:35]
	v_mfma_f32_16x16x32_bf16 v[36:39], v[180:183], v[200:203], v[36:39]
	v_mfma_f32_16x16x32_bf16 v[40:43], v[184:187], v[200:203], v[40:43]
	v_mfma_f32_16x16x32_bf16 v[44:47], v[188:191], v[200:203], v[44:47]
	ds_read_b128 v[144:147], v232 offset:0
	ds_read_b128 v[148:151], v232 offset:1024
	v_mfma_f32_16x16x32_bf16 v[48:51], v[176:179], v[204:207], v[48:51]
	v_mfma_f32_16x16x32_bf16 v[52:55], v[180:183], v[204:207], v[52:55]
	v_mfma_f32_16x16x32_bf16 v[56:59], v[184:187], v[204:207], v[56:59]
	v_mfma_f32_16x16x32_bf16 v[60:63], v[188:191], v[204:207], v[60:63]
	ds_read_b128 v[152:155], v232 offset:2048
	ds_read_b128 v[156:159], v232 offset:3072
	v_mfma_f32_16x16x32_bf16 v[64:67], v[176:179], v[208:211], v[64:67]
	v_mfma_f32_16x16x32_bf16 v[68:71], v[180:183], v[208:211], v[68:71]
	v_mfma_f32_16x16x32_bf16 v[72:75], v[184:187], v[208:211], v[72:75]
	v_mfma_f32_16x16x32_bf16 v[76:79], v[188:191], v[208:211], v[76:79]
	ds_read_b128 v[160:163], v232 offset:4096
	v_mfma_f32_16x16x32_bf16 v[80:83], v[176:179], v[212:215], v[80:83]
	v_mfma_f32_16x16x32_bf16 v[84:87], v[180:183], v[212:215], v[84:87]
	v_mfma_f32_16x16x32_bf16 v[88:91], v[184:187], v[212:215], v[88:91]
	v_mfma_f32_16x16x32_bf16 v[92:95], v[188:191], v[212:215], v[92:95]
	ds_read_b128 v[164:167], v232 offset:5120
	s_cmp_eq_u32 s10, 0
	s_cbranch_scc0 .Lg8_hi3
	s_setprio 0
; #define LWRITE(S, buf) do { bf16_t* sA_ = sbase + (buf) * BUF; bf16_t* sB_ = sA_ + 256 * PITCH; \
;     _Pragma("unroll") for (int i_ = 0; i_ < 4; ++i_) *(u32x4*)(sA_ + (sr + i_ * 64) * PITCH + scv * 8) = ra[S][i_]; \
;     _Pragma("unroll") for (int i_ = 0; i_ < 2; ++i_) *(u32x4*)(sB_ + (sr + i_ * 64) * PITCH + scv * 8) = rb[S][i_]; } while (0)
; template <class Epi>
; DI void gemm_tile(char* smem, const bf16_t* __restrict__ A0, int lda0, int ksplit, const bf16_t* __restrict__ A1, int lda1,
;                   const bf16_t* __restrict__ Bt, int K, int row0, int col0, const Epi& epi, int tid) {
;     ...
;   __syncthreads();
;   {
;     const int last = nk - 1;
;     GLOAD(0, 0);
;     __builtin_amdgcn_sched_barrier(0);
;     GLOAD(1, 1);
;     __builtin_amdgcn_sched_barrier(0);
;     LWRITE(0, 0);
;     __builtin_amdgcn_sched_barrier(0);
;     GLOAD(0, (2 < last ? 2 : last));
;     __builtin_amdgcn_sched_barrier(0);
;     __syncthreads();
;     for (int kt = 0; kt < nk; kt += 2) {
;       LWRITE(1, 1);
;       __builtin_amdgcn_sched_barrier(0);
;       GLOAD(1, (kt + 3 < last ? kt + 3 : last));
;       __builtin_amdgcn_sched_barrier(0);
;       COMPUTE(0);
;       __syncthreads();
;       LWRITE(0, 0);
;       __builtin_amdgcn_sched_barrier(0);
;       GLOAD(0, (kt + 4 < last ? kt + 4 : last));
;       __builtin_amdgcn_sched_barrier(0);
;       COMPUTE(1);
;       __syncthreads();
;     }
.Lg8_hi3:
	v_mfma_f32_16x16x32_bf16 v[96:99], v[176:179], v[216:219], v[96:99]
	v_mfma_f32_16x16x32_bf16 v[100:103], v[180:183], v[216:219], v[100:103]
	v_mfma_f32_16x16x32_bf16 v[104:107], v[184:187], v[216:219], v[104:107]
	v_mfma_f32_16x16x32_bf16 v[108:111], v[188:191], v[216:219], v[108:111]
	ds_read_b128 v[168:171], v232 offset:6144
	s_add_u32 s98, s98, 24576
	s_cmp_eq_u32 s98, 73728
	s_cselect_b32 s98, 0, s98
	v_mfma_f32_16x16x32_bf16 v[112:115], v[176:179], v[220:223], v[112:115]
	v_mfma_f32_16x16x32_bf16 v[116:119], v[180:183], v[220:223], v[116:119]
	v_mfma_f32_16x16x32_bf16 v[120:123], v[184:187], v[220:223], v[120:123]
	v_mfma_f32_16x16x32_bf16 v[124:127], v[188:191], v[220:223], v[124:127]
	ds_read_b128 v[172:175], v232 offset:7168
	s_waitcnt vmcnt(0)
	s_waitcnt lgkmcnt(0)
	s_barrier
	v_add_u32_e32 v232, s98, v230
	v_add_u32_e32 v233, s98, v231
	s_setprio 1
	v_mfma_f32_16x16x32_bf16 v[0:3], v[128:131], v[144:147], v[0:3]
	v_mfma_f32_16x16x32_bf16 v[4:7], v[132:135], v[144:147], v[4:7]
	v_mfma_f32_16x16x32_bf16 v[8:11], v[136:139], v[144:147], v[8:11]
	v_mfma_f32_16x16x32_bf16 v[12:15], v[140:143], v[144:147], v[12:15]
	ds_read_b128 v[176:179], v233 offset:0
	ds_read_b128 v[180:183], v233 offset:1024
	v_mfma_f32_16x16x32_bf16 v[16:19], v[128:131], v[148:151], v[16:19]
	v_mfma_f32_16x16x32_bf16 v[20:23], v[132:135], v[148:151], v[20:23]
	v_mfma_f32_16x16x32_bf16 v[24:27], v[136:139], v[148:151], v[24:27]
	v_mfma_f32_16x16x32_bf16 v[28:31], v[140:143], v[148:151], v[28:31]
	ds_read_b128 v[184:187], v233 offset:2048
	ds_read_b128 v[188:191], v233 offset:3072
	v_mfma_f32_16x16x32_bf16 v[32:35], v[128:131], v[152:155], v[32:35]
	v_mfma_f32_16x16x32_bf16 v[36:39], v[132:135], v[152:155], v[36:39]
	v_mfma_f32_16x16x32_bf16 v[40:43], v[136:139], v[152:155], v[40:43]
	v_mfma_f32_16x16x32_bf16 v[44:47], v[140:143], v[152:155], v[44:47]
	ds_read_b128 v[192:195], v232 offset:0
	ds_read_b128 v[196:199], v232 offset:1024
	v_mfma_f32_16x16x32_bf16 v[48:51], v[128:131], v[156:159], v[48:51]
	v_mfma_f32_16x16x32_bf16 v[52:55], v[132:135], v[156:159], v[52:55]
	v_mfma_f32_16x16x32_bf16 v[56:59], v[136:139], v[156:159], v[56:59]
	v_mfma_f32_16x16x32_bf16 v[60:63], v[140:143], v[156:159], v[60:63]
	ds_read_b128 v[200:203], v232 offset:2048
	ds_read_b128 v[204:207], v232 offset:3072
	v_mfma_f32_16x16x32_bf16 v[64:67], v[128:131], v[160:163], v[64:67]
	v_mfma_f32_16x16x32_bf16 v[68:71], v[132:135], v[160:163], v[68:71]
	v_mfma_f32_16x16x32_bf16 v[72:75], v[136:139], v[160:163], v[72:75]
	v_mfma_f32_16x16x32_bf16 v[76:79], v[140:143], v[160:163], v[76:79]
	ds_read_b128 v[208:211], v232 offset:4096
	v_mfma_f32_16x16x32_bf16 v[80:83], v[128:131], v[164:167], v[80:83]
	v_mfma_f32_16x16x32_bf16 v[84:87], v[132:135], v[164:167], v[84:87]
	v_mfma_f32_16x16x32_bf16 v[88:91], v[136:139], v[164:167], v[88:91]
	v_mfma_f32_16x16x32_bf16 v[92:95], v[140:143], v[164:167], v[92:95]
	ds_read_b128 v[212:215], v232 offset:5120
	s_cmp_eq_u32 s10, 0
	s_cbranch_scc0 .Lg8_hi4
	s_setprio 0
.Lg8_hi4:
	v_mfma_f32_16x16x32_bf16 v[96:99], v[128:131], v[168:171], v[96:99]
	v_mfma_f32_16x16x32_bf16 v[100:103], v[132:135], v[168:171], v[100:103]
	v_mfma_f32_16x16x32_bf16 v[104:107], v[136:139], v[168:171], v[104:107]
	v_mfma_f32_16x16x32_bf16 v[108:111], v[140:143], v[168:171], v[108:111]
	ds_read_b128 v[216:219], v232 offset:6144
	s_add_u32 s98, s98, 24576
	s_cmp_eq_u32 s98, 73728
	s_cselect_b32 s98, 0, s98
	v_mfma_f32_16x16x32_bf16 v[112:115], v[128:131], v[172:175], v[112:115]
	v_mfma_f32_16x16x32_bf16 v[116:119], v[132:135], v[172:175], v[116:119]
	v_mfma_f32_16x16x32_bf16 v[120:123], v[136:139], v[172:175], v[120:123]
	v_mfma_f32_16x16x32_bf16 v[124:127], v[140:143], v[172:175], v[124:127]
	ds_read_b128 v[220:223], v232 offset:7168
	s_waitcnt lgkmcnt(0)
	s_barrier
	s_setprio 1
	v_mfma_f32_16x16x32_bf16 v[0:3], v[176:179], v[192:195], v[0:3]
	v_mfma_f32_16x16x32_bf16 v[4:7], v[180:183], v[192:195], v[4:7]
	v_mfma_f32_16x16x32_bf16 v[8:11], v[184:187], v[192:195], v[8:11]
	v_mfma_f32_16x16x32_bf16 v[12:15], v[188:191], v[192:195], v[12:15]
	v_mfma_f32_16x16x32_bf16 v[16:19], v[176:179], v[196:199], v[16:19]
	v_mfma_f32_16x16x32_bf16 v[20:23], v[180:183], v[196:199], v[20:23]
	v_mfma_f32_16x16x32_bf16 v[24:27], v[184:187], v[196:199], v[24:27]
	v_mfma_f32_16x16x32_bf16 v[28:31], v[188:191], v[196:199], v[28:31]
	v_mfma_f32_16x16x32_bf16 v[32:35], v[176:179], v[200:203], v[32:35]
	v_mfma_f32_16x16x32_bf16 v[36:39], v[180:183], v[200:203], v[36:39]
	v_mfma_f32_16x16x32_bf16 v[40:43], v[184:187], v[200:203], v[40:43]
	v_mfma_f32_16x16x32_bf16 v[44:47], v[188:191], v[200:203], v[44:47]
	v_mfma_f32_16x16x32_bf16 v[48:51], v[176:179], v[204:207], v[48:51]
	v_mfma_f32_16x16x32_bf16 v[52:55], v[180:183], v[204:207], v[52:55]
	v_mfma_f32_16x16x32_bf16 v[56:59], v[184:187], v[204:207], v[56:59]
	v_mfma_f32_16x16x32_bf16 v[60:63], v[188:191], v[204:207], v[60:63]
	v_mfma_f32_16x16x32_bf16 v[64:67], v[176:179], v[208:211], v[64:67]
	v_mfma_f32_16x16x32_bf16 v[68:71], v[180:183], v[208:211], v[68:71]
	v_mfma_f32_16x16x32_bf16 v[72:75], v[184:187], v[208:211], v[72:75]
	v_mfma_f32_16x16x32_bf16 v[76:79], v[188:191], v[208:211], v[76:79]
	v_mfma_f32_16x16x32_bf16 v[80:83], v[176:179], v[212:215], v[80:83]
	v_mfma_f32_16x16x32_bf16 v[84:87], v[180:183], v[212:215], v[84:87]
	v_mfma_f32_16x16x32_bf16 v[88:91], v[184:187], v[212:215], v[88:91]
	v_mfma_f32_16x16x32_bf16 v[92:95], v[188:191], v[212:215], v[92:95]
	s_cmp_eq_u32 s10, 0
	s_cbranch_scc0 .Lg8_hi5
	s_setprio 0

; #define LWRITE(S, buf) do { bf16_t* sA_ = sbase + (buf) * BUF; bf16_t* sB_ = sA_ + 256 * PITCH; \
;     _Pragma("unroll") for (int i_ = 0; i_ < 4; ++i_) *(u32x4*)(sA_ + (sr + i_ * 64) * PITCH + scv * 8) = ra[S][i_]; \
;     _Pragma("unroll") for (int i_ = 0; i_ < 2; ++i_) *(u32x4*)(sB_ + (sr + i_ * 64) * PITCH + scv * 8) = rb[S][i_]; } while (0)
; template <class Epi>
; DI void gemm_tile(char* smem, const bf16_t* __restrict__ A0, int lda0, int ksplit, const bf16_t* __restrict__ A1, int lda1,
;                   const bf16_t* __restrict__ Bt, int K, int row0, int col0, const Epi& epi, int tid) {
;     ...
;   __syncthreads();
;   {
;     const int last = nk - 1;
;     GLOAD(0, 0);
;     __builtin_amdgcn_sched_barrier(0);
;     GLOAD(1, 1);
;     __builtin_amdgcn_sched_barrier(0);
;     LWRITE(0, 0);
;     __builtin_amdgcn_sched_barrier(0);
;     GLOAD(0, (2 < last ? 2 : last));
;     __builtin_amdgcn_sched_barrier(0);
;     __syncthreads();
;     for (int kt = 0; kt < nk; kt += 2) {
;       LWRITE(1, 1);
;       __builtin_amdgcn_sched_barrier(0);
;       GLOAD(1, (kt + 3 < last ? kt + 3 : last));
;       __builtin_amdgcn_sched_barrier(0);
;       COMPUTE(0);
;       __syncthreads();
;       LWRITE(0, 0);
;       __builtin_amdgcn_sched_barrier(0);
;       GLOAD(0, (kt + 4 < last ? kt + 4 : last));
;       __builtin_amdgcn_sched_barrier(0);
;       COMPUTE(1);
.Lg9_kloop:
	s_waitcnt vmcnt(6)
	s_waitcnt lgkmcnt(0)
	s_barrier
	v_add_u32_e32 v232, s98, v230
	v_add_u32_e32 v233, s98, v231
	s_add_u32 s9, s17, s101
	s_setprio 1
	v_mfma_f32_16x16x32_bf16 v[0:3], v[128:131], v[144:147], v[0:3]
	v_mfma_f32_16x16x32_bf16 v[4:7], v[132:135], v[144:147], v[4:7]
	v_mfma_f32_16x16x32_bf16 v[8:11], v[136:139], v[144:147], v[8:11]
	v_mfma_f32_16x16x32_bf16 v[12:15], v[140:143], v[144:147], v[12:15]
	ds_read_b128 v[176:179], v233 offset:0
	ds_read_b128 v[180:183], v233 offset:1024
	s_add_u32 m0, s9, 0
	s_nop 0
	global_load_lds_dwordx4 v224, s[0:1]
	v_mfma_f32_16x16x32_bf16 v[16:19], v[128:131], v[148:151], v[16:19]
	v_mfma_f32_16x16x32_bf16 v[20:23], v[132:135], v[148:151], v[20:23]
	v_mfma_f32_16x16x32_bf16 v[24:27], v[136:139], v[148:151], v[24:27]
	v_mfma_f32_16x16x32_bf16 v[28:31], v[140:143], v[148:151], v[28:31]
	ds_read_b128 v[184:187], v233 offset:2048
	ds_read_b128 v[188:191], v233 offset:3072
	s_add_u32 m0, s9, 4096
	s_nop 0
	global_load_lds_dwordx4 v225, s[0:1]
	v_mfma_f32_16x16x32_bf16 v[32:35], v[128:131], v[152:155], v[32:35]
	v_mfma_f32_16x16x32_bf16 v[36:39], v[132:135], v[152:155], v[36:39]
	v_mfma_f32_16x16x32_bf16 v[40:43], v[136:139], v[152:155], v[40:43]
	v_mfma_f32_16x16x32_bf16 v[44:47], v[140:143], v[152:155], v[44:47]
	ds_read_b128 v[192:195], v232 offset:0
	ds_read_b128 v[196:199], v232 offset:1024
	s_add_u32 m0, s9, 8192
	s_nop 0
	global_load_lds_dwordx4 v226, s[0:1]
	v_mfma_f32_16x16x32_bf16 v[48:51], v[128:131], v[156:159], v[48:51]
	v_mfma_f32_16x16x32_bf16 v[52:55], v[132:135], v[156:159], v[52:55]
	v_mfma_f32_16x16x32_bf16 v[56:59], v[136:139], v[156:159], v[56:59]
	v_mfma_f32_16x16x32_bf16 v[60:63], v[140:143], v[156:159], v[60:63]
	ds_read_b128 v[200:203], v232 offset:2048
	ds_read_b128 v[204:207], v232 offset:3072
	s_add_u32 m0, s9, 12288
	s_nop 0
	global_load_lds_dwordx4 v227, s[0:1]
	v_mfma_f32_16x16x32_bf16 v[64:67], v[128:131], v[160:163], v[64:67]
	v_mfma_f32_16x16x32_bf16 v[68:71], v[132:135], v[160:163], v[68:71]
	v_mfma_f32_16x16x32_bf16 v[72:75], v[136:139], v[160:163], v[72:75]
	v_mfma_f32_16x16x32_bf16 v[76:79], v[140:143], v[160:163], v[76:79]
	ds_read_b128 v[208:211], v232 offset:4096
	s_add_u32 m0, s9, 16384
	s_nop 0
	global_load_lds_dwordx4 v228, s[2:3]
	v_mfma_f32_16x16x32_bf16 v[80:83], v[128:131], v[164:167], v[80:83]
	v_mfma_f32_16x16x32_bf16 v[84:87], v[132:135], v[164:167], v[84:87]
	v_mfma_f32_16x16x32_bf16 v[88:91], v[136:139], v[164:167], v[88:91]
	v_mfma_f32_16x16x32_bf16 v[92:95], v[140:143], v[164:167], v[92:95]
	ds_read_b128 v[212:215], v232 offset:5120
	s_add_u32 m0, s9, 20480
	s_nop 0
	global_load_lds_dwordx4 v229, s[2:3]
	s_cmp_eq_u32 s8, 0
	s_cbranch_scc0 .Lg9_hi0
	s_setprio 0
.Lg9_hi0:
	v_mfma_f32_16x16x32_bf16 v[96:99], v[128:131], v[168:171], v[96:99]
	v_mfma_f32_16x16x32_bf16 v[100:103], v[132:135], v[168:171], v[100:103]
	v_mfma_f32_16x16x32_bf16 v[104:107], v[136:139], v[168:171], v[104:107]
	v_mfma_f32_16x16x32_bf16 v[108:111], v[140:143], v[168:171], v[108:111]
	ds_read_b128 v[216:219], v232 offset:6144
	s_add_u32 s0, s0, 64
	s_addc_u32 s1, s1, 0
	s_add_u32 s2, s2, 64
	s_addc_u32 s3, s3, 0
	s_add_u32 s100, s100, 1
	s_add_u32 s17, s17, 24576
	s_cmp_eq_u32 s17, 73728
	s_cselect_b32 s17, 0, s17
	s_add_u32 s98, s98, 24576
	s_cmp_eq_u32 s98, 73728
	s_cselect_b32 s98, 0, s98
	v_mfma_f32_16x16x32_bf16 v[112:115], v[128:131], v[172:175], v[112:115]
	v_mfma_f32_16x16x32_bf16 v[116:119], v[132:135], v[172:175], v[116:119]
	v_mfma_f32_16x16x32_bf16 v[120:123], v[136:139], v[172:175], v[120:123]
	v_mfma_f32_16x16x32_bf16 v[124:127], v[140:143], v[172:175], v[124:127]
	ds_read_b128 v[220:223], v232 offset:7168
	s_waitcnt vmcnt(6)
	s_waitcnt lgkmcnt(0)
	s_barrier
	v_add_u32_e32 v232, s98, v230
	v_add_u32_e32 v233, s98, v231
	s_add_u32 s9, s17, s101
	s_setprio 1
	v_mfma_f32_16x16x32_bf16 v[0:3], v[176:179], v[192:195], v[0:3]
	v_mfma_f32_16x16x32_bf16 v[4:7], v[180:183], v[192:195], v[4:7]
	v_mfma_f32_16x16x32_bf16 v[8:11], v[184:187], v[192:195], v[8:11]
	v_mfma_f32_16x16x32_bf16 v[12:15], v[188:191], v[192:195], v[12:15]
	ds_read_b128 v[128:131], v233 offset:0
	ds_read_b128 v[132:135], v233 offset:1024
	s_add_u32 m0, s9, 0
	s_nop 0
	global_load_lds_dwordx4 v224, s[0:1]
	v_mfma_f32_16x16x32_bf16 v[16:19], v[176:179], v[196:199], v[16:19]
	v_mfma_f32_16x16x32_bf16 v[20:23], v[180:183], v[196:199], v[20:23]
	v_mfma_f32_16x16x32_bf16 v[24:27], v[184:187], v[196:199], v[24:27]
	v_mfma_f32_16x16x32_bf16 v[28:31], v[188:191], v[196:199], v[28:31]
	ds_read_b128 v[136:139], v233 offset:2048
	ds_read_b128 v[140:143], v233 offset:3072
	s_add_u32 m0, s9, 4096
	s_nop 0
	global_load_lds_dwordx4 v225, s[0:1]
	v_mfma_f32_16x16x32_bf16 v[32:35], v[176:179], v[200:203], v[32:35]
	v_mfma_f32_16x16x32_bf16 v[36:39], v[180:183], v[200:203], v[36:39]
	v_mfma_f32_16x16x32_bf16 v[40:43], v[184:187], v[200:203], v[40:43]
	v_mfma_f32_16x16x32_bf16 v[44:47], v[188:191], v[200:203], v[44:47]
	ds_read_b128 v[144:147], v232 offset:0
	ds_read_b128 v[148:151], v232 offset:1024
	s_add_u32 m0, s9, 8192
	s_nop 0
	global_load_lds_dwordx4 v226, s[0:1]
	v_mfma_f32_16x16x32_bf16 v[48:51], v[176:179], v[204:207], v[48:51]
	v_mfma_f32_16x16x32_bf16 v[52:55], v[180:183], v[204:207], v[52:55]
	v_mfma_f32_16x16x32_bf16 v[56:59], v[184:187], v[204:207], v[56:59]
	v_mfma_f32_16x16x32_bf16 v[60:63], v[188:191], v[204:207], v[60:63]
	ds_read_b128 v[152:155], v232 offset:2048
	ds_read_b128 v[156:159], v232 offset:3072
	s_add_u32 m0, s9, 12288
	s_nop 0
	global_load_lds_dwordx4 v227, s[0:1]
	v_mfma_f32_16x16x32_bf16 v[64:67], v[176:179], v[208:211], v[64:67]
	v_mfma_f32_16x16x32_bf16 v[68:71], v[180:183], v[208:211], v[68:71]
	v_mfma_f32_16x16x32_bf16 v[72:75], v[184:187], v[208:211], v[72:75]
	v_mfma_f32_16x16x32_bf16 v[76:79], v[188:191], v[208:211], v[76:79]
	ds_read_b128 v[160:163], v232 offset:4096
	s_add_u32 m0, s9, 16384
	s_nop 0
	global_load_lds_dwordx4 v228, s[2:3]
	v_mfma_f32_16x16x32_bf16 v[80:83], v[176:179], v[212:215], v[80:83]
	v_mfma_f32_16x16x32_bf16 v[84:87], v[180:183], v[212:215], v[84:87]
	v_mfma_f32_16x16x32_bf16 v[88:91], v[184:187], v[212:215], v[88:91]
	v_mfma_f32_16x16x32_bf16 v[92:95], v[188:191], v[212:215], v[92:95]
	ds_read_b128 v[164:167], v232 offset:5120
	s_add_u32 m0, s9, 20480
	s_nop 0
	global_load_lds_dwordx4 v229, s[2:3]
	s_cmp_eq_u32 s8, 0
	s_cbranch_scc0 .Lg9_hi1
	s_setprio 0
; #define LWRITE(S, buf) do { bf16_t* sA_ = sbase + (buf) * BUF; bf16_t* sB_ = sA_ + 256 * PITCH; \
;     _Pragma("unroll") for (int i_ = 0; i_ < 4; ++i_) *(u32x4*)(sA_ + (sr + i_ * 64) * PITCH + scv * 8) = ra[S][i_]; \
;     _Pragma("unroll") for (int i_ = 0; i_ < 2; ++i_) *(u32x4*)(sB_ + (sr + i_ * 64) * PITCH + scv * 8) = rb[S][i_]; } while (0)
; template <class Epi>
; DI void gemm_tile(char* smem, const bf16_t* __restrict__ A0, int lda0, int ksplit, const bf16_t* __restrict__ A1, int lda1,
;                   const bf16_t* __restrict__ Bt, int K, int row0, int col0, const Epi& epi, int tid) {
;     ...
;   __syncthreads();
;   {
;     const int last = nk - 1;
;     GLOAD(0, 0);
;     __builtin_amdgcn_sched_barrier(0);
;     GLOAD(1, 1);
;     __builtin_amdgcn_sched_barrier(0);
;     LWRITE(0, 0);
;     __builtin_amdgcn_sched_barrier(0);
;     GLOAD(0, (2 < last ? 2 : last));
;     __builtin_amdgcn_sched_barrier(0);
;     __syncthreads();
;     for (int kt = 0; kt < nk; kt += 2) {
;       LWRITE(1, 1);
;       __builtin_amdgcn_sched_barrier(0);
;       GLOAD(1, (kt + 3 < last ? kt + 3 : last));
;       __builtin_amdgcn_sched_barrier(0);
;       COMPUTE(0);
;       __syncthreads();
;       LWRITE(0, 0);
;       __builtin_amdgcn_sched_barrier(0);
;       GLOAD(0, (kt + 4 < last ? kt + 4 : last));
;       __builtin_amdgcn_sched_barrier(0);
;       COMPUTE(1);
;       __syncthreads();
.Lg9_hi1:
	v_mfma_f32_16x16x32_bf16 v[96:99], v[176:179], v[216:219], v[96:99]
	v_mfma_f32_16x16x32_bf16 v[100:103], v[180:183], v[216:219], v[100:103]
	v_mfma_f32_16x16x32_bf16 v[104:107], v[184:187], v[216:219], v[104:107]
	v_mfma_f32_16x16x32_bf16 v[108:111], v[188:191], v[216:219], v[108:111]
	ds_read_b128 v[168:171], v232 offset:6144
	s_add_u32 s0, s0, 64
	s_addc_u32 s1, s1, 0
	s_add_u32 s2, s2, 64
	s_addc_u32 s3, s3, 0
	s_add_u32 s100, s100, 1
	s_add_u32 s17, s17, 24576
	s_cmp_eq_u32 s17, 73728
	s_cselect_b32 s17, 0, s17
	s_add_u32 s98, s98, 24576
	s_cmp_eq_u32 s98, 73728
	s_cselect_b32 s98, 0, s98
	v_mfma_f32_16x16x32_bf16 v[112:115], v[176:179], v[220:223], v[112:115]
	v_mfma_f32_16x16x32_bf16 v[116:119], v[180:183], v[220:223], v[116:119]
	v_mfma_f32_16x16x32_bf16 v[120:123], v[184:187], v[220:223], v[120:123]
	v_mfma_f32_16x16x32_bf16 v[124:127], v[188:191], v[220:223], v[124:127]
	ds_read_b128 v[172:175], v232 offset:7168
	s_add_u32 s99, s99, 2
	s_cmp_lt_u32 s99, 124
	s_cbranch_scc1 .Lg9_kloop
	s_waitcnt vmcnt(6)
	s_waitcnt lgkmcnt(0)
	s_barrier
	v_add_u32_e32 v232, s98, v230
	v_add_u32_e32 v233, s98, v231
	s_add_u32 s9, s17, s101
	s_setprio 1
	v_mfma_f32_16x16x32_bf16 v[0:3], v[128:131], v[144:147], v[0:3]
	v_mfma_f32_16x16x32_bf16 v[4:7], v[132:135], v[144:147], v[4:7]
	v_mfma_f32_16x16x32_bf16 v[8:11], v[136:139], v[144:147], v[8:11]
	v_mfma_f32_16x16x32_bf16 v[12:15], v[140:143], v[144:147], v[12:15]
	ds_read_b128 v[176:179], v233 offset:0
	ds_read_b128 v[180:183], v233 offset:1024
	s_add_u32 m0, s9, 0
	s_nop 0
	global_load_lds_dwordx4 v224, s[0:1]
	v_mfma_f32_16x16x32_bf16 v[16:19], v[128:131], v[148:151], v[16:19]
	v_mfma_f32_16x16x32_bf16 v[20:23], v[132:135], v[148:151], v[20:23]
	v_mfma_f32_16x16x32_bf16 v[24:27], v[136:139], v[148:151], v[24:27]
	v_mfma_f32_16x16x32_bf16 v[28:31], v[140:143], v[148:151], v[28:31]
	ds_read_b128 v[184:187], v233 offset:2048
	ds_read_b128 v[188:191], v233 offset:3072
	s_add_u32 m0, s9, 4096
	s_nop 0
	global_load_lds_dwordx4 v225, s[0:1]
	v_mfma_f32_16x16x32_bf16 v[32:35], v[128:131], v[152:155], v[32:35]
	v_mfma_f32_16x16x32_bf16 v[36:39], v[132:135], v[152:155], v[36:39]
	v_mfma_f32_16x16x32_bf16 v[40:43], v[136:139], v[152:155], v[40:43]
	v_mfma_f32_16x16x32_bf16 v[44:47], v[140:143], v[152:155], v[44:47]
	ds_read_b128 v[192:195], v232 offset:0
	ds_read_b128 v[196:199], v232 offset:1024
	s_add_u32 m0, s9, 8192
	s_nop 0
	global_load_lds_dwordx4 v226, s[0:1]
	v_mfma_f32_16x16x32_bf16 v[48:51], v[128:131], v[156:159], v[48:51]
	v_mfma_f32_16x16x32_bf16 v[52:55], v[132:135], v[156:159], v[52:55]
	v_mfma_f32_16x16x32_bf16 v[56:59], v[136:139], v[156:159], v[56:59]
	v_mfma_f32_16x16x32_bf16 v[60:63], v[140:143], v[156:159], v[60:63]
	ds_read_b128 v[200:203], v232 offset:2048
	ds_read_b128 v[204:207], v232 offset:3072
	s_add_u32 m0, s9, 12288
	s_nop 0
	global_load_lds_dwordx4 v227, s[0:1]
	v_mfma_f32_16x16x32_bf16 v[64:67], v[128:131], v[160:163], v[64:67]
	v_mfma_f32_16x16x32_bf16 v[68:71], v[132:135], v[160:163], v[68:71]
	v_mfma_f32_16x16x32_bf16 v[72:75], v[136:139], v[160:163], v[72:75]
	v_mfma_f32_16x16x32_bf16 v[76:79], v[140:143], v[160:163], v[76:79]
	ds_read_b128 v[208:211], v232 offset:4096
	s_add_u32 m0, s9, 16384
	s_nop 0
	global_load_lds_dwordx4 v228, s[2:3]
	v_mfma_f32_16x16x32_bf16 v[80:83], v[128:131], v[164:167], v[80:83]
	v_mfma_f32_16x16x32_bf16 v[84:87], v[132:135], v[164:167], v[84:87]
	v_mfma_f32_16x16x32_bf16 v[88:91], v[136:139], v[164:167], v[88:91]
	v_mfma_f32_16x16x32_bf16 v[92:95], v[140:143], v[164:167], v[92:95]
	ds_read_b128 v[212:215], v232 offset:5120
	s_add_u32 m0, s9, 20480
	s_nop 0
	global_load_lds_dwordx4 v229, s[2:3]
	s_cmp_eq_u32 s8, 0
	s_cbranch_scc0 .Lg9_hi2
	s_setprio 0
.Lg9_hi2:
	v_mfma_f32_16x16x32_bf16 v[96:99], v[128:131], v[168:171], v[96:99]
	v_mfma_f32_16x16x32_bf16 v[100:103], v[132:135], v[168:171], v[100:103]
	v_mfma_f32_16x16x32_bf16 v[104:107], v[136:139], v[168:171], v[104:107]
	v_mfma_f32_16x16x32_bf16 v[108:111], v[140:143], v[168:171], v[108:111]
	ds_read_b128 v[216:219], v232 offset:6144
	s_add_u32 s0, s0, 64
	s_addc_u32 s1, s1, 0
	s_add_u32 s2, s2, 64
	s_addc_u32 s3, s3, 0
	s_add_u32 s100, s100, 1
	s_add_u32 s17, s17, 24576
	s_cmp_eq_u32 s17, 73728
	s_cselect_b32 s17, 0, s17
	s_add_u32 s98, s98, 24576
	s_cmp_eq_u32 s98, 73728
	s_cselect_b32 s98, 0, s98
	v_mfma_f32_16x16x32_bf16 v[112:115], v[128:131], v[172:175], v[112:115]
	v_mfma_f32_16x16x32_bf16 v[116:119], v[132:135], v[172:175], v[116:119]
	v_mfma_f32_16x16x32_bf16 v[120:123], v[136:139], v[172:175], v[120:123]
	v_mfma_f32_16x16x32_bf16 v[124:127], v[140:143], v[172:175], v[124:127]
	ds_read_b128 v[220:223], v232 offset:7168
	s_waitcnt vmcnt(6)
	s_waitcnt lgkmcnt(0)
	s_barrier
	v_add_u32_e32 v232, s98, v230
	v_add_u32_e32 v233, s98, v231
	s_setprio 1
	v_mfma_f32_16x16x32_bf16 v[0:3], v[176:179], v[192:195], v[0:3]
	v_mfma_f32_16x16x32_bf16 v[4:7], v[180:183], v[192:195], v[4:7]
	v_mfma_f32_16x16x32_bf16 v[8:11], v[184:187], v[192:195], v[8:11]
	v_mfma_f32_16x16x32_bf16 v[12:15], v[188:191], v[192:195], v[12:15]
	ds_read_b128 v[128:131], v233 offset:0
	ds_read_b128 v[132:135], v233 offset:1024
	v_mfma_f32_16x16x32_bf16 v[16:19], v[176:179], v[196:199], v[16:19]
	v_mfma_f32_16x16x32_bf16 v[20:23], v[180:183], v[196:199], v[20:23]
	v_mfma_f32_16x16x32_bf16 v[24:27], v[184:187], v[196:199], v[24:27]
	v_mfma_f32_16x16x32_bf16 v[28:31], v[188:191], v[196:199], v[28:31]
	ds_read_b128 v[136:139], v233 offset:2048
	ds_read_b128 v[140:143], v233 offset:3072
	v_mfma_f32_16x16x32_bf16 v[32:35], v[176:179], v[200:203], v[32:35]
	v_mfma_f32_16x16x32_bf16 v[36:39], v[180:183], v[200:203], v[36:39]
	v_mfma_f32_16x16x32_bf16 v[40:43], v[184:187], v[200:203], v[40:43]
	v_mfma_f32_16x16x32_bf16 v[44:47], v[188:191], v[200:203], v[44:47]
	ds_read_b128 v[144:147], v232 offset:0
	ds_read_b128 v[148:151], v232 offset:1024
	v_mfma_f32_16x16x32_bf16 v[48:51], v[176:179], v[204:207], v[48:51]
	v_mfma_f32_16x16x32_bf16 v[52:55], v[180:183], v[204:207], v[52:55]
	v_mfma_f32_16x16x32_bf16 v[56:59], v[184:187], v[204:207], v[56:59]
	v_mfma_f32_16x16x32_bf16 v[60:63], v[188:191], v[204:207], v[60:63]
	ds_read_b128 v[152:155], v232 offset:2048
	ds_read_b128 v[156:159], v232 offset:3072
	v_mfma_f32_16x16x32_bf16 v[64:67], v[176:179], v[208:211], v[64:67]
	v_mfma_f32_16x16x32_bf16 v[68:71], v[180:183], v[208:211], v[68:71]
	v_mfma_f32_16x16x32_bf16 v[72:75], v[184:187], v[208:211], v[72:75]
	v_mfma_f32_16x16x32_bf16 v[76:79], v[188:191], v[208:211], v[76:79]
	ds_read_b128 v[160:163], v232 offset:4096
	v_mfma_f32_16x16x32_bf16 v[80:83], v[176:179], v[212:215], v[80:83]
	v_mfma_f32_16x16x32_bf16 v[84:87], v[180:183], v[212:215], v[84:87]
	v_mfma_f32_16x16x32_bf16 v[88:91], v[184:187], v[212:215], v[88:91]
	v_mfma_f32_16x16x32_bf16 v[92:95], v[188:191], v[212:215], v[92:95]
	ds_read_b128 v[164:167], v232 offset:5120
	s_cmp_eq_u32 s8, 0
	s_cbranch_scc0 .Lg9_hi3
	s_setprio 0
; #define LWRITE(S, buf) do { bf16_t* sA_ = sbase + (buf) * BUF; bf16_t* sB_ = sA_ + 256 * PITCH; \
;     _Pragma("unroll") for (int i_ = 0; i_ < 4; ++i_) *(u32x4*)(sA_ + (sr + i_ * 64) * PITCH + scv * 8) = ra[S][i_]; \
;     _Pragma("unroll") for (int i_ = 0; i_ < 2; ++i_) *(u32x4*)(sB_ + (sr + i_ * 64) * PITCH + scv * 8) = rb[S][i_]; } while (0)
; template <class Epi>
; DI void gemm_tile(char* smem, const bf16_t* __restrict__ A0, int lda0, int ksplit, const bf16_t* __restrict__ A1, int lda1,
;                   const bf16_t* __restrict__ Bt, int K, int row0, int col0, const Epi& epi, int tid) {
;     ...
;   __syncthreads();
;   {
;     const int last = nk - 1;
;     GLOAD(0, 0);
;     __builtin_amdgcn_sched_barrier(0);
;     GLOAD(1, 1);
;     __builtin_amdgcn_sched_barrier(0);
;     LWRITE(0, 0);
;     __builtin_amdgcn_sched_barrier(0);
;     GLOAD(0, (2 < last ? 2 : last));
;     __builtin_amdgcn_sched_barrier(0);
;     __syncthreads();
;     for (int kt = 0; kt < nk; kt += 2) {
;       LWRITE(1, 1);
;       __builtin_amdgcn_sched_barrier(0);
;       GLOAD(1, (kt + 3 < last ? kt + 3 : last));
;       __builtin_amdgcn_sched_barrier(0);
;       COMPUTE(0);
;       __syncthreads();
;       LWRITE(0, 0);
;       __builtin_amdgcn_sched_barrier(0);
;       GLOAD(0, (kt + 4 < last ? kt + 4 : last));
;       __builtin_amdgcn_sched_barrier(0);
;       COMPUTE(1);
;       __syncthreads();
;     }
.Lg9_hi3:
	v_mfma_f32_16x16x32_bf16 v[96:99], v[176:179], v[216:219], v[96:99]
	v_mfma_f32_16x16x32_bf16 v[100:103], v[180:183], v[216:219], v[100:103]
	v_mfma_f32_16x16x32_bf16 v[104:107], v[184:187], v[216:219], v[104:107]
	v_mfma_f32_16x16x32_bf16 v[108:111], v[188:191], v[216:219], v[108:111]
	ds_read_b128 v[168:171], v232 offset:6144
	s_add_u32 s98, s98, 24576
	s_cmp_eq_u32 s98, 73728
	s_cselect_b32 s98, 0, s98
	v_mfma_f32_16x16x32_bf16 v[112:115], v[176:179], v[220:223], v[112:115]
	v_mfma_f32_16x16x32_bf16 v[116:119], v[180:183], v[220:223], v[116:119]
	v_mfma_f32_16x16x32_bf16 v[120:123], v[184:187], v[220:223], v[120:123]
	v_mfma_f32_16x16x32_bf16 v[124:127], v[188:191], v[220:223], v[124:127]
	ds_read_b128 v[172:175], v232 offset:7168
	s_waitcnt vmcnt(0)
	s_waitcnt lgkmcnt(0)
	s_barrier
	v_add_u32_e32 v232, s98, v230
	v_add_u32_e32 v233, s98, v231
	s_setprio 1
	v_mfma_f32_16x16x32_bf16 v[0:3], v[128:131], v[144:147], v[0:3]
	v_mfma_f32_16x16x32_bf16 v[4:7], v[132:135], v[144:147], v[4:7]
	v_mfma_f32_16x16x32_bf16 v[8:11], v[136:139], v[144:147], v[8:11]
	v_mfma_f32_16x16x32_bf16 v[12:15], v[140:143], v[144:147], v[12:15]
	ds_read_b128 v[176:179], v233 offset:0
	ds_read_b128 v[180:183], v233 offset:1024
	v_mfma_f32_16x16x32_bf16 v[16:19], v[128:131], v[148:151], v[16:19]
	v_mfma_f32_16x16x32_bf16 v[20:23], v[132:135], v[148:151], v[20:23]
	v_mfma_f32_16x16x32_bf16 v[24:27], v[136:139], v[148:151], v[24:27]
	v_mfma_f32_16x16x32_bf16 v[28:31], v[140:143], v[148:151], v[28:31]
	ds_read_b128 v[184:187], v233 offset:2048
	ds_read_b128 v[188:191], v233 offset:3072
	v_mfma_f32_16x16x32_bf16 v[32:35], v[128:131], v[152:155], v[32:35]
	v_mfma_f32_16x16x32_bf16 v[36:39], v[132:135], v[152:155], v[36:39]
	v_mfma_f32_16x16x32_bf16 v[40:43], v[136:139], v[152:155], v[40:43]
	v_mfma_f32_16x16x32_bf16 v[44:47], v[140:143], v[152:155], v[44:47]
	ds_read_b128 v[192:195], v232 offset:0
	ds_read_b128 v[196:199], v232 offset:1024
	v_mfma_f32_16x16x32_bf16 v[48:51], v[128:131], v[156:159], v[48:51]
	v_mfma_f32_16x16x32_bf16 v[52:55], v[132:135], v[156:159], v[52:55]
	v_mfma_f32_16x16x32_bf16 v[56:59], v[136:139], v[156:159], v[56:59]
	v_mfma_f32_16x16x32_bf16 v[60:63], v[140:143], v[156:159], v[60:63]
	ds_read_b128 v[200:203], v232 offset:2048
	ds_read_b128 v[204:207], v232 offset:3072
	v_mfma_f32_16x16x32_bf16 v[64:67], v[128:131], v[160:163], v[64:67]
	v_mfma_f32_16x16x32_bf16 v[68:71], v[132:135], v[160:163], v[68:71]
	v_mfma_f32_16x16x32_bf16 v[72:75], v[136:139], v[160:163], v[72:75]
	v_mfma_f32_16x16x32_bf16 v[76:79], v[140:143], v[160:163], v[76:79]
	ds_read_b128 v[208:211], v232 offset:4096
	v_mfma_f32_16x16x32_bf16 v[80:83], v[128:131], v[164:167], v[80:83]
	v_mfma_f32_16x16x32_bf16 v[84:87], v[132:135], v[164:167], v[84:87]
	v_mfma_f32_16x16x32_bf16 v[88:91], v[136:139], v[164:167], v[88:91]
	v_mfma_f32_16x16x32_bf16 v[92:95], v[140:143], v[164:167], v[92:95]
	ds_read_b128 v[212:215], v232 offset:5120
	s_cmp_eq_u32 s8, 0
	s_cbranch_scc0 .Lg9_hi4
	s_setprio 0
.Lg9_hi4:
	v_mfma_f32_16x16x32_bf16 v[96:99], v[128:131], v[168:171], v[96:99]
	v_mfma_f32_16x16x32_bf16 v[100:103], v[132:135], v[168:171], v[100:103]
	v_mfma_f32_16x16x32_bf16 v[104:107], v[136:139], v[168:171], v[104:107]
	v_mfma_f32_16x16x32_bf16 v[108:111], v[140:143], v[168:171], v[108:111]
	ds_read_b128 v[216:219], v232 offset:6144
	s_add_u32 s98, s98, 24576
	s_cmp_eq_u32 s98, 73728
	s_cselect_b32 s98, 0, s98
	v_mfma_f32_16x16x32_bf16 v[112:115], v[128:131], v[172:175], v[112:115]
	v_mfma_f32_16x16x32_bf16 v[116:119], v[132:135], v[172:175], v[116:119]
	v_mfma_f32_16x16x32_bf16 v[120:123], v[136:139], v[172:175], v[120:123]
	v_mfma_f32_16x16x32_bf16 v[124:127], v[140:143], v[172:175], v[124:127]
	ds_read_b128 v[220:223], v232 offset:7168
	s_waitcnt lgkmcnt(0)
	s_barrier
	s_setprio 1
	v_mfma_f32_16x16x32_bf16 v[0:3], v[176:179], v[192:195], v[0:3]
	v_mfma_f32_16x16x32_bf16 v[4:7], v[180:183], v[192:195], v[4:7]
	v_mfma_f32_16x16x32_bf16 v[8:11], v[184:187], v[192:195], v[8:11]
	v_mfma_f32_16x16x32_bf16 v[12:15], v[188:191], v[192:195], v[12:15]
	v_mfma_f32_16x16x32_bf16 v[16:19], v[176:179], v[196:199], v[16:19]
	v_mfma_f32_16x16x32_bf16 v[20:23], v[180:183], v[196:199], v[20:23]
	v_mfma_f32_16x16x32_bf16 v[24:27], v[184:187], v[196:199], v[24:27]
	v_mfma_f32_16x16x32_bf16 v[28:31], v[188:191], v[196:199], v[28:31]
	v_mfma_f32_16x16x32_bf16 v[32:35], v[176:179], v[200:203], v[32:35]
	v_mfma_f32_16x16x32_bf16 v[36:39], v[180:183], v[200:203], v[36:39]
	v_mfma_f32_16x16x32_bf16 v[40:43], v[184:187], v[200:203], v[40:43]
	v_mfma_f32_16x16x32_bf16 v[44:47], v[188:191], v[200:203], v[44:47]
	v_mfma_f32_16x16x32_bf16 v[48:51], v[176:179], v[204:207], v[48:51]
	v_mfma_f32_16x16x32_bf16 v[52:55], v[180:183], v[204:207], v[52:55]
	v_mfma_f32_16x16x32_bf16 v[56:59], v[184:187], v[204:207], v[56:59]
	v_mfma_f32_16x16x32_bf16 v[60:63], v[188:191], v[204:207], v[60:63]
	v_mfma_f32_16x16x32_bf16 v[64:67], v[176:179], v[208:211], v[64:67]
	v_mfma_f32_16x16x32_bf16 v[68:71], v[180:183], v[208:211], v[68:71]
	v_mfma_f32_16x16x32_bf16 v[72:75], v[184:187], v[208:211], v[72:75]
	v_mfma_f32_16x16x32_bf16 v[76:79], v[188:191], v[208:211], v[76:79]
	v_mfma_f32_16x16x32_bf16 v[80:83], v[176:179], v[212:215], v[80:83]
	v_mfma_f32_16x16x32_bf16 v[84:87], v[180:183], v[212:215], v[84:87]
	v_mfma_f32_16x16x32_bf16 v[88:91], v[184:187], v[212:215], v[88:91]
	v_mfma_f32_16x16x32_bf16 v[92:95], v[188:191], v[212:215], v[92:95]
	s_cmp_eq_u32 s8, 0
	s_cbranch_scc0 .Lg9_hi5
	s_setprio 0

; #define LWRITE(S, buf) do { bf16_t* sA_ = sbase + (buf) * BUF; bf16_t* sB_ = sA_ + 256 * PITCH; \
;     _Pragma("unroll") for (int i_ = 0; i_ < 4; ++i_) *(u32x4*)(sA_ + (sr + i_ * 64) * PITCH + scv * 8) = ra[S][i_]; \
;     _Pragma("unroll") for (int i_ = 0; i_ < 2; ++i_) *(u32x4*)(sB_ + (sr + i_ * 64) * PITCH + scv * 8) = rb[S][i_]; } while (0)
; template <class Epi>
; DI void gemm_tile(char* smem, const bf16_t* __restrict__ A0, int lda0, int ksplit, const bf16_t* __restrict__ A1, int lda1,
;                   const bf16_t* __restrict__ Bt, int K, int row0, int col0, const Epi& epi, int tid) {
;     ...
;   __syncthreads();
;   {
;     const int last = nk - 1;
;     GLOAD(0, 0);
;     __builtin_amdgcn_sched_barrier(0);
;     GLOAD(1, 1);
;     __builtin_amdgcn_sched_barrier(0);
;     LWRITE(0, 0);
;     __builtin_amdgcn_sched_barrier(0);
;     GLOAD(0, (2 < last ? 2 : last));
;     __builtin_amdgcn_sched_barrier(0);
;     __syncthreads();
;     for (int kt = 0; kt < nk; kt += 2) {
;       LWRITE(1, 1);
;       __builtin_amdgcn_sched_barrier(0);
;       GLOAD(1, (kt + 3 < last ? kt + 3 : last));
;       __builtin_amdgcn_sched_barrier(0);
;       COMPUTE(0);
;       __syncthreads();
;       LWRITE(0, 0);
;       __builtin_amdgcn_sched_barrier(0);
;       GLOAD(0, (kt + 4 < last ? kt + 4 : last));
;       __builtin_amdgcn_sched_barrier(0);
;       COMPUTE(1);
.Lg11_kloop:
	s_waitcnt vmcnt(6)
	s_waitcnt lgkmcnt(0)
	s_barrier
	v_add_u32_e32 v232, s30, v230
	v_add_u32_e32 v233, s30, v231
	s_add_u32 s25, s29, s99
	s_setprio 1
	v_mfma_f32_16x16x32_bf16 v[0:3], v[128:131], v[144:147], v[0:3]
	v_mfma_f32_16x16x32_bf16 v[4:7], v[132:135], v[144:147], v[4:7]
	v_mfma_f32_16x16x32_bf16 v[8:11], v[136:139], v[144:147], v[8:11]
	v_mfma_f32_16x16x32_bf16 v[12:15], v[140:143], v[144:147], v[12:15]
	ds_read_b128 v[176:179], v233 offset:0
	ds_read_b128 v[180:183], v233 offset:1024
	s_add_u32 m0, s25, 0
	s_nop 0
	global_load_lds_dwordx4 v224, s[0:1]
	v_mfma_f32_16x16x32_bf16 v[16:19], v[128:131], v[148:151], v[16:19]
	v_mfma_f32_16x16x32_bf16 v[20:23], v[132:135], v[148:151], v[20:23]
	v_mfma_f32_16x16x32_bf16 v[24:27], v[136:139], v[148:151], v[24:27]
	v_mfma_f32_16x16x32_bf16 v[28:31], v[140:143], v[148:151], v[28:31]
	ds_read_b128 v[184:187], v233 offset:2048
	ds_read_b128 v[188:191], v233 offset:3072
	s_add_u32 m0, s25, 4096
	s_nop 0
	global_load_lds_dwordx4 v225, s[0:1]
	v_mfma_f32_16x16x32_bf16 v[32:35], v[128:131], v[152:155], v[32:35]
	v_mfma_f32_16x16x32_bf16 v[36:39], v[132:135], v[152:155], v[36:39]
	v_mfma_f32_16x16x32_bf16 v[40:43], v[136:139], v[152:155], v[40:43]
	v_mfma_f32_16x16x32_bf16 v[44:47], v[140:143], v[152:155], v[44:47]
	ds_read_b128 v[192:195], v232 offset:0
	ds_read_b128 v[196:199], v232 offset:1024
	s_add_u32 m0, s25, 8192
	s_nop 0
	global_load_lds_dwordx4 v226, s[0:1]
	v_mfma_f32_16x16x32_bf16 v[48:51], v[128:131], v[156:159], v[48:51]
	v_mfma_f32_16x16x32_bf16 v[52:55], v[132:135], v[156:159], v[52:55]
	v_mfma_f32_16x16x32_bf16 v[56:59], v[136:139], v[156:159], v[56:59]
	v_mfma_f32_16x16x32_bf16 v[60:63], v[140:143], v[156:159], v[60:63]
	ds_read_b128 v[200:203], v232 offset:2048
	ds_read_b128 v[204:207], v232 offset:3072
	s_add_u32 m0, s25, 12288
	s_nop 0
	global_load_lds_dwordx4 v227, s[0:1]
	v_mfma_f32_16x16x32_bf16 v[64:67], v[128:131], v[160:163], v[64:67]
	v_mfma_f32_16x16x32_bf16 v[68:71], v[132:135], v[160:163], v[68:71]
	v_mfma_f32_16x16x32_bf16 v[72:75], v[136:139], v[160:163], v[72:75]
	v_mfma_f32_16x16x32_bf16 v[76:79], v[140:143], v[160:163], v[76:79]
	ds_read_b128 v[208:211], v232 offset:4096
	s_add_u32 m0, s25, 16384
	s_nop 0
	global_load_lds_dwordx4 v228, s[2:3]
	v_mfma_f32_16x16x32_bf16 v[80:83], v[128:131], v[164:167], v[80:83]
	v_mfma_f32_16x16x32_bf16 v[84:87], v[132:135], v[164:167], v[84:87]
	v_mfma_f32_16x16x32_bf16 v[88:91], v[136:139], v[164:167], v[88:91]
	v_mfma_f32_16x16x32_bf16 v[92:95], v[140:143], v[164:167], v[92:95]
	ds_read_b128 v[212:215], v232 offset:5120
	s_add_u32 m0, s25, 20480
	s_nop 0
	global_load_lds_dwordx4 v229, s[2:3]
	s_cmp_eq_u32 s24, 0
	s_cbranch_scc0 .Lg11_hi0
	s_setprio 0
.Lg11_hi0:
	v_mfma_f32_16x16x32_bf16 v[96:99], v[128:131], v[168:171], v[96:99]
	v_mfma_f32_16x16x32_bf16 v[100:103], v[132:135], v[168:171], v[100:103]
	v_mfma_f32_16x16x32_bf16 v[104:107], v[136:139], v[168:171], v[104:107]
	v_mfma_f32_16x16x32_bf16 v[108:111], v[140:143], v[168:171], v[108:111]
	ds_read_b128 v[216:219], v232 offset:6144
	s_add_u32 s0, s0, 64
	s_addc_u32 s1, s1, 0
	s_add_u32 s2, s2, 64
	s_addc_u32 s3, s3, 0
	s_add_u32 s98, s98, 1
	s_add_u32 s29, s29, 24576
	s_cmp_eq_u32 s29, 73728
	s_cselect_b32 s29, 0, s29
	s_add_u32 s30, s30, 24576
	s_cmp_eq_u32 s30, 73728
	s_cselect_b32 s30, 0, s30
	v_mfma_f32_16x16x32_bf16 v[112:115], v[128:131], v[172:175], v[112:115]
	v_mfma_f32_16x16x32_bf16 v[116:119], v[132:135], v[172:175], v[116:119]
	v_mfma_f32_16x16x32_bf16 v[120:123], v[136:139], v[172:175], v[120:123]
	v_mfma_f32_16x16x32_bf16 v[124:127], v[140:143], v[172:175], v[124:127]
	ds_read_b128 v[220:223], v232 offset:7168
	s_waitcnt vmcnt(6)
	s_waitcnt lgkmcnt(0)
	s_barrier
	v_add_u32_e32 v232, s30, v230
	v_add_u32_e32 v233, s30, v231
	s_add_u32 s25, s29, s99
	s_setprio 1
	v_mfma_f32_16x16x32_bf16 v[0:3], v[176:179], v[192:195], v[0:3]
	v_mfma_f32_16x16x32_bf16 v[4:7], v[180:183], v[192:195], v[4:7]
	v_mfma_f32_16x16x32_bf16 v[8:11], v[184:187], v[192:195], v[8:11]
	v_mfma_f32_16x16x32_bf16 v[12:15], v[188:191], v[192:195], v[12:15]
	ds_read_b128 v[128:131], v233 offset:0
	ds_read_b128 v[132:135], v233 offset:1024
	s_add_u32 m0, s25, 0
	s_nop 0
	global_load_lds_dwordx4 v224, s[0:1]
	v_mfma_f32_16x16x32_bf16 v[16:19], v[176:179], v[196:199], v[16:19]
	v_mfma_f32_16x16x32_bf16 v[20:23], v[180:183], v[196:199], v[20:23]
	v_mfma_f32_16x16x32_bf16 v[24:27], v[184:187], v[196:199], v[24:27]
	v_mfma_f32_16x16x32_bf16 v[28:31], v[188:191], v[196:199], v[28:31]
	ds_read_b128 v[136:139], v233 offset:2048
	ds_read_b128 v[140:143], v233 offset:3072
	s_add_u32 m0, s25, 4096
	s_nop 0
	global_load_lds_dwordx4 v225, s[0:1]
	v_mfma_f32_16x16x32_bf16 v[32:35], v[176:179], v[200:203], v[32:35]
	v_mfma_f32_16x16x32_bf16 v[36:39], v[180:183], v[200:203], v[36:39]
	v_mfma_f32_16x16x32_bf16 v[40:43], v[184:187], v[200:203], v[40:43]
	v_mfma_f32_16x16x32_bf16 v[44:47], v[188:191], v[200:203], v[44:47]
	ds_read_b128 v[144:147], v232 offset:0
	ds_read_b128 v[148:151], v232 offset:1024
	s_add_u32 m0, s25, 8192
	s_nop 0
	global_load_lds_dwordx4 v226, s[0:1]
	v_mfma_f32_16x16x32_bf16 v[48:51], v[176:179], v[204:207], v[48:51]
	v_mfma_f32_16x16x32_bf16 v[52:55], v[180:183], v[204:207], v[52:55]
	v_mfma_f32_16x16x32_bf16 v[56:59], v[184:187], v[204:207], v[56:59]
	v_mfma_f32_16x16x32_bf16 v[60:63], v[188:191], v[204:207], v[60:63]
	ds_read_b128 v[152:155], v232 offset:2048
	ds_read_b128 v[156:159], v232 offset:3072
	s_add_u32 m0, s25, 12288
	s_nop 0
	global_load_lds_dwordx4 v227, s[0:1]
	v_mfma_f32_16x16x32_bf16 v[64:67], v[176:179], v[208:211], v[64:67]
	v_mfma_f32_16x16x32_bf16 v[68:71], v[180:183], v[208:211], v[68:71]
	v_mfma_f32_16x16x32_bf16 v[72:75], v[184:187], v[208:211], v[72:75]
	v_mfma_f32_16x16x32_bf16 v[76:79], v[188:191], v[208:211], v[76:79]
	ds_read_b128 v[160:163], v232 offset:4096
	s_add_u32 m0, s25, 16384
	s_nop 0
	global_load_lds_dwordx4 v228, s[2:3]
	v_mfma_f32_16x16x32_bf16 v[80:83], v[176:179], v[212:215], v[80:83]
	v_mfma_f32_16x16x32_bf16 v[84:87], v[180:183], v[212:215], v[84:87]
	v_mfma_f32_16x16x32_bf16 v[88:91], v[184:187], v[212:215], v[88:91]
	v_mfma_f32_16x16x32_bf16 v[92:95], v[188:191], v[212:215], v[92:95]
	ds_read_b128 v[164:167], v232 offset:5120
	s_add_u32 m0, s25, 20480
	s_nop 0
	global_load_lds_dwordx4 v229, s[2:3]
	s_cmp_eq_u32 s24, 0
	s_cbranch_scc0 .Lg11_hi1
	s_setprio 0
; #define LWRITE(S, buf) do { bf16_t* sA_ = sbase + (buf) * BUF; bf16_t* sB_ = sA_ + 256 * PITCH; \
;     _Pragma("unroll") for (int i_ = 0; i_ < 4; ++i_) *(u32x4*)(sA_ + (sr + i_ * 64) * PITCH + scv * 8) = ra[S][i_]; \
;     _Pragma("unroll") for (int i_ = 0; i_ < 2; ++i_) *(u32x4*)(sB_ + (sr + i_ * 64) * PITCH + scv * 8) = rb[S][i_]; } while (0)
; template <class Epi>
; DI void gemm_tile(char* smem, const bf16_t* __restrict__ A0, int lda0, int ksplit, const bf16_t* __restrict__ A1, int lda1,
;                   const bf16_t* __restrict__ Bt, int K, int row0, int col0, const Epi& epi, int tid) {
;     ...
;   __syncthreads();
;   {
;     const int last = nk - 1;
;     GLOAD(0, 0);
;     __builtin_amdgcn_sched_barrier(0);
;     GLOAD(1, 1);
;     __builtin_amdgcn_sched_barrier(0);
;     LWRITE(0, 0);
;     __builtin_amdgcn_sched_barrier(0);
;     GLOAD(0, (2 < last ? 2 : last));
;     __builtin_amdgcn_sched_barrier(0);
;     __syncthreads();
;     for (int kt = 0; kt < nk; kt += 2) {
;       LWRITE(1, 1);
;       __builtin_amdgcn_sched_barrier(0);
;       GLOAD(1, (kt + 3 < last ? kt + 3 : last));
;       __builtin_amdgcn_sched_barrier(0);
;       COMPUTE(0);
;       __syncthreads();
;       LWRITE(0, 0);
;       __builtin_amdgcn_sched_barrier(0);
;       GLOAD(0, (kt + 4 < last ? kt + 4 : last));
;       __builtin_amdgcn_sched_barrier(0);
;       COMPUTE(1);
;       __syncthreads();
.Lg11_hi1:
	v_mfma_f32_16x16x32_bf16 v[96:99], v[176:179], v[216:219], v[96:99]
	v_mfma_f32_16x16x32_bf16 v[100:103], v[180:183], v[216:219], v[100:103]
	v_mfma_f32_16x16x32_bf16 v[104:107], v[184:187], v[216:219], v[104:107]
	v_mfma_f32_16x16x32_bf16 v[108:111], v[188:191], v[216:219], v[108:111]
	ds_read_b128 v[168:171], v232 offset:6144
	s_add_u32 s0, s0, 64
	s_addc_u32 s1, s1, 0
	s_add_u32 s2, s2, 64
	s_addc_u32 s3, s3, 0
	s_add_u32 s98, s98, 1
	s_add_u32 s29, s29, 24576
	s_cmp_eq_u32 s29, 73728
	s_cselect_b32 s29, 0, s29
	s_add_u32 s30, s30, 24576
	s_cmp_eq_u32 s30, 73728
	s_cselect_b32 s30, 0, s30
	v_mfma_f32_16x16x32_bf16 v[112:115], v[176:179], v[220:223], v[112:115]
	v_mfma_f32_16x16x32_bf16 v[116:119], v[180:183], v[220:223], v[116:119]
	v_mfma_f32_16x16x32_bf16 v[120:123], v[184:187], v[220:223], v[120:123]
	v_mfma_f32_16x16x32_bf16 v[124:127], v[188:191], v[220:223], v[124:127]
	ds_read_b128 v[172:175], v232 offset:7168
	s_add_u32 s31, s31, 2
	s_cmp_lt_u32 s31, 28
	s_cbranch_scc1 .Lg11_kloop
	s_waitcnt vmcnt(6)
	s_waitcnt lgkmcnt(0)
	s_barrier
	v_add_u32_e32 v232, s30, v230
	v_add_u32_e32 v233, s30, v231
	s_add_u32 s25, s29, s99
	s_setprio 1
	v_mfma_f32_16x16x32_bf16 v[0:3], v[128:131], v[144:147], v[0:3]
	v_mfma_f32_16x16x32_bf16 v[4:7], v[132:135], v[144:147], v[4:7]
	v_mfma_f32_16x16x32_bf16 v[8:11], v[136:139], v[144:147], v[8:11]
	v_mfma_f32_16x16x32_bf16 v[12:15], v[140:143], v[144:147], v[12:15]
	ds_read_b128 v[176:179], v233 offset:0
	ds_read_b128 v[180:183], v233 offset:1024
	s_add_u32 m0, s25, 0
	s_nop 0
	global_load_lds_dwordx4 v224, s[0:1]
	v_mfma_f32_16x16x32_bf16 v[16:19], v[128:131], v[148:151], v[16:19]
	v_mfma_f32_16x16x32_bf16 v[20:23], v[132:135], v[148:151], v[20:23]
	v_mfma_f32_16x16x32_bf16 v[24:27], v[136:139], v[148:151], v[24:27]
	v_mfma_f32_16x16x32_bf16 v[28:31], v[140:143], v[148:151], v[28:31]
	ds_read_b128 v[184:187], v233 offset:2048
	ds_read_b128 v[188:191], v233 offset:3072
	s_add_u32 m0, s25, 4096
	s_nop 0
	global_load_lds_dwordx4 v225, s[0:1]
	v_mfma_f32_16x16x32_bf16 v[32:35], v[128:131], v[152:155], v[32:35]
	v_mfma_f32_16x16x32_bf16 v[36:39], v[132:135], v[152:155], v[36:39]
	v_mfma_f32_16x16x32_bf16 v[40:43], v[136:139], v[152:155], v[40:43]
	v_mfma_f32_16x16x32_bf16 v[44:47], v[140:143], v[152:155], v[44:47]
	ds_read_b128 v[192:195], v232 offset:0
	ds_read_b128 v[196:199], v232 offset:1024
	s_add_u32 m0, s25, 8192
	s_nop 0
	global_load_lds_dwordx4 v226, s[0:1]
	v_mfma_f32_16x16x32_bf16 v[48:51], v[128:131], v[156:159], v[48:51]
	v_mfma_f32_16x16x32_bf16 v[52:55], v[132:135], v[156:159], v[52:55]
	v_mfma_f32_16x16x32_bf16 v[56:59], v[136:139], v[156:159], v[56:59]
	v_mfma_f32_16x16x32_bf16 v[60:63], v[140:143], v[156:159], v[60:63]
	ds_read_b128 v[200:203], v232 offset:2048
	ds_read_b128 v[204:207], v232 offset:3072
	s_add_u32 m0, s25, 12288
	s_nop 0
	global_load_lds_dwordx4 v227, s[0:1]
	v_mfma_f32_16x16x32_bf16 v[64:67], v[128:131], v[160:163], v[64:67]
	v_mfma_f32_16x16x32_bf16 v[68:71], v[132:135], v[160:163], v[68:71]
	v_mfma_f32_16x16x32_bf16 v[72:75], v[136:139], v[160:163], v[72:75]
	v_mfma_f32_16x16x32_bf16 v[76:79], v[140:143], v[160:163], v[76:79]
	ds_read_b128 v[208:211], v232 offset:4096
	s_add_u32 m0, s25, 16384
	s_nop 0
	global_load_lds_dwordx4 v228, s[2:3]
	v_mfma_f32_16x16x32_bf16 v[80:83], v[128:131], v[164:167], v[80:83]
	v_mfma_f32_16x16x32_bf16 v[84:87], v[132:135], v[164:167], v[84:87]
	v_mfma_f32_16x16x32_bf16 v[88:91], v[136:139], v[164:167], v[88:91]
	v_mfma_f32_16x16x32_bf16 v[92:95], v[140:143], v[164:167], v[92:95]
	ds_read_b128 v[212:215], v232 offset:5120
	s_add_u32 m0, s25, 20480
	s_nop 0
	global_load_lds_dwordx4 v229, s[2:3]
	s_cmp_eq_u32 s24, 0
	s_cbranch_scc0 .Lg11_hi2
	s_setprio 0
.Lg11_hi2:
	v_mfma_f32_16x16x32_bf16 v[96:99], v[128:131], v[168:171], v[96:99]
	v_mfma_f32_16x16x32_bf16 v[100:103], v[132:135], v[168:171], v[100:103]
	v_mfma_f32_16x16x32_bf16 v[104:107], v[136:139], v[168:171], v[104:107]
	v_mfma_f32_16x16x32_bf16 v[108:111], v[140:143], v[168:171], v[108:111]
	ds_read_b128 v[216:219], v232 offset:6144
	s_add_u32 s0, s0, 64
	s_addc_u32 s1, s1, 0
	s_add_u32 s2, s2, 64
	s_addc_u32 s3, s3, 0
	s_add_u32 s98, s98, 1
	s_add_u32 s29, s29, 24576
	s_cmp_eq_u32 s29, 73728
	s_cselect_b32 s29, 0, s29
	s_add_u32 s30, s30, 24576
	s_cmp_eq_u32 s30, 73728
	s_cselect_b32 s30, 0, s30
	v_mfma_f32_16x16x32_bf16 v[112:115], v[128:131], v[172:175], v[112:115]
	v_mfma_f32_16x16x32_bf16 v[116:119], v[132:135], v[172:175], v[116:119]
	v_mfma_f32_16x16x32_bf16 v[120:123], v[136:139], v[172:175], v[120:123]
	v_mfma_f32_16x16x32_bf16 v[124:127], v[140:143], v[172:175], v[124:127]
	ds_read_b128 v[220:223], v232 offset:7168
	s_waitcnt vmcnt(6)
	s_waitcnt lgkmcnt(0)
	s_barrier
	v_add_u32_e32 v232, s30, v230
	v_add_u32_e32 v233, s30, v231
	s_setprio 1
	v_mfma_f32_16x16x32_bf16 v[0:3], v[176:179], v[192:195], v[0:3]
	v_mfma_f32_16x16x32_bf16 v[4:7], v[180:183], v[192:195], v[4:7]
	v_mfma_f32_16x16x32_bf16 v[8:11], v[184:187], v[192:195], v[8:11]
	v_mfma_f32_16x16x32_bf16 v[12:15], v[188:191], v[192:195], v[12:15]
	ds_read_b128 v[128:131], v233 offset:0
	ds_read_b128 v[132:135], v233 offset:1024
	v_mfma_f32_16x16x32_bf16 v[16:19], v[176:179], v[196:199], v[16:19]
	v_mfma_f32_16x16x32_bf16 v[20:23], v[180:183], v[196:199], v[20:23]
	v_mfma_f32_16x16x32_bf16 v[24:27], v[184:187], v[196:199], v[24:27]
	v_mfma_f32_16x16x32_bf16 v[28:31], v[188:191], v[196:199], v[28:31]
	ds_read_b128 v[136:139], v233 offset:2048
	ds_read_b128 v[140:143], v233 offset:3072
	v_mfma_f32_16x16x32_bf16 v[32:35], v[176:179], v[200:203], v[32:35]
	v_mfma_f32_16x16x32_bf16 v[36:39], v[180:183], v[200:203], v[36:39]
	v_mfma_f32_16x16x32_bf16 v[40:43], v[184:187], v[200:203], v[40:43]
	v_mfma_f32_16x16x32_bf16 v[44:47], v[188:191], v[200:203], v[44:47]
	ds_read_b128 v[144:147], v232 offset:0
	ds_read_b128 v[148:151], v232 offset:1024
	v_mfma_f32_16x16x32_bf16 v[48:51], v[176:179], v[204:207], v[48:51]
	v_mfma_f32_16x16x32_bf16 v[52:55], v[180:183], v[204:207], v[52:55]
	v_mfma_f32_16x16x32_bf16 v[56:59], v[184:187], v[204:207], v[56:59]
	v_mfma_f32_16x16x32_bf16 v[60:63], v[188:191], v[204:207], v[60:63]
	ds_read_b128 v[152:155], v232 offset:2048
	ds_read_b128 v[156:159], v232 offset:3072
	v_mfma_f32_16x16x32_bf16 v[64:67], v[176:179], v[208:211], v[64:67]
	v_mfma_f32_16x16x32_bf16 v[68:71], v[180:183], v[208:211], v[68:71]
	v_mfma_f32_16x16x32_bf16 v[72:75], v[184:187], v[208:211], v[72:75]
	v_mfma_f32_16x16x32_bf16 v[76:79], v[188:191], v[208:211], v[76:79]
	ds_read_b128 v[160:163], v232 offset:4096
	v_mfma_f32_16x16x32_bf16 v[80:83], v[176:179], v[212:215], v[80:83]
	v_mfma_f32_16x16x32_bf16 v[84:87], v[180:183], v[212:215], v[84:87]
	v_mfma_f32_16x16x32_bf16 v[88:91], v[184:187], v[212:215], v[88:91]
	v_mfma_f32_16x16x32_bf16 v[92:95], v[188:191], v[212:215], v[92:95]
	ds_read_b128 v[164:167], v232 offset:5120
	s_cmp_eq_u32 s24, 0
	s_cbranch_scc0 .Lg11_hi3
	s_setprio 0
; #define LWRITE(S, buf) do { bf16_t* sA_ = sbase + (buf) * BUF; bf16_t* sB_ = sA_ + 256 * PITCH; \
;     _Pragma("unroll") for (int i_ = 0; i_ < 4; ++i_) *(u32x4*)(sA_ + (sr + i_ * 64) * PITCH + scv * 8) = ra[S][i_]; \
;     _Pragma("unroll") for (int i_ = 0; i_ < 2; ++i_) *(u32x4*)(sB_ + (sr + i_ * 64) * PITCH + scv * 8) = rb[S][i_]; } while (0)
; template <class Epi>
; DI void gemm_tile(char* smem, const bf16_t* __restrict__ A0, int lda0, int ksplit, const bf16_t* __restrict__ A1, int lda1,
;                   const bf16_t* __restrict__ Bt, int K, int row0, int col0, const Epi& epi, int tid) {
;     ...
;   __syncthreads();
;   {
;     const int last = nk - 1;
;     GLOAD(0, 0);
;     __builtin_amdgcn_sched_barrier(0);
;     GLOAD(1, 1);
;     __builtin_amdgcn_sched_barrier(0);
;     LWRITE(0, 0);
;     __builtin_amdgcn_sched_barrier(0);
;     GLOAD(0, (2 < last ? 2 : last));
;     __builtin_amdgcn_sched_barrier(0);
;     __syncthreads();
;     for (int kt = 0; kt < nk; kt += 2) {
;       LWRITE(1, 1);
;       __builtin_amdgcn_sched_barrier(0);
;       GLOAD(1, (kt + 3 < last ? kt + 3 : last));
;       __builtin_amdgcn_sched_barrier(0);
;       COMPUTE(0);
;       __syncthreads();
;       LWRITE(0, 0);
;       __builtin_amdgcn_sched_barrier(0);
;       GLOAD(0, (kt + 4 < last ? kt + 4 : last));
;       __builtin_amdgcn_sched_barrier(0);
;       COMPUTE(1);
;       __syncthreads();
;     }
.Lg11_hi3:
	v_mfma_f32_16x16x32_bf16 v[96:99], v[176:179], v[216:219], v[96:99]
	v_mfma_f32_16x16x32_bf16 v[100:103], v[180:183], v[216:219], v[100:103]
	v_mfma_f32_16x16x32_bf16 v[104:107], v[184:187], v[216:219], v[104:107]
	v_mfma_f32_16x16x32_bf16 v[108:111], v[188:191], v[216:219], v[108:111]
	ds_read_b128 v[168:171], v232 offset:6144
	s_add_u32 s30, s30, 24576
	s_cmp_eq_u32 s30, 73728
	s_cselect_b32 s30, 0, s30
	v_mfma_f32_16x16x32_bf16 v[112:115], v[176:179], v[220:223], v[112:115]
	v_mfma_f32_16x16x32_bf16 v[116:119], v[180:183], v[220:223], v[116:119]
	v_mfma_f32_16x16x32_bf16 v[120:123], v[184:187], v[220:223], v[120:123]
	v_mfma_f32_16x16x32_bf16 v[124:127], v[188:191], v[220:223], v[124:127]
	ds_read_b128 v[172:175], v232 offset:7168
	s_waitcnt vmcnt(0)
	s_waitcnt lgkmcnt(0)
	s_barrier
	v_add_u32_e32 v232, s30, v230
	v_add_u32_e32 v233, s30, v231
	s_setprio 1
	v_mfma_f32_16x16x32_bf16 v[0:3], v[128:131], v[144:147], v[0:3]
	v_mfma_f32_16x16x32_bf16 v[4:7], v[132:135], v[144:147], v[4:7]
	v_mfma_f32_16x16x32_bf16 v[8:11], v[136:139], v[144:147], v[8:11]
	v_mfma_f32_16x16x32_bf16 v[12:15], v[140:143], v[144:147], v[12:15]
	ds_read_b128 v[176:179], v233 offset:0
	ds_read_b128 v[180:183], v233 offset:1024
	v_mfma_f32_16x16x32_bf16 v[16:19], v[128:131], v[148:151], v[16:19]
	v_mfma_f32_16x16x32_bf16 v[20:23], v[132:135], v[148:151], v[20:23]
	v_mfma_f32_16x16x32_bf16 v[24:27], v[136:139], v[148:151], v[24:27]
	v_mfma_f32_16x16x32_bf16 v[28:31], v[140:143], v[148:151], v[28:31]
	ds_read_b128 v[184:187], v233 offset:2048
	ds_read_b128 v[188:191], v233 offset:3072
	v_mfma_f32_16x16x32_bf16 v[32:35], v[128:131], v[152:155], v[32:35]
	v_mfma_f32_16x16x32_bf16 v[36:39], v[132:135], v[152:155], v[36:39]
	v_mfma_f32_16x16x32_bf16 v[40:43], v[136:139], v[152:155], v[40:43]
	v_mfma_f32_16x16x32_bf16 v[44:47], v[140:143], v[152:155], v[44:47]
	ds_read_b128 v[192:195], v232 offset:0
	ds_read_b128 v[196:199], v232 offset:1024
	v_mfma_f32_16x16x32_bf16 v[48:51], v[128:131], v[156:159], v[48:51]
	v_mfma_f32_16x16x32_bf16 v[52:55], v[132:135], v[156:159], v[52:55]
	v_mfma_f32_16x16x32_bf16 v[56:59], v[136:139], v[156:159], v[56:59]
	v_mfma_f32_16x16x32_bf16 v[60:63], v[140:143], v[156:159], v[60:63]
	ds_read_b128 v[200:203], v232 offset:2048
	ds_read_b128 v[204:207], v232 offset:3072
	v_mfma_f32_16x16x32_bf16 v[64:67], v[128:131], v[160:163], v[64:67]
	v_mfma_f32_16x16x32_bf16 v[68:71], v[132:135], v[160:163], v[68:71]
	v_mfma_f32_16x16x32_bf16 v[72:75], v[136:139], v[160:163], v[72:75]
	v_mfma_f32_16x16x32_bf16 v[76:79], v[140:143], v[160:163], v[76:79]
	ds_read_b128 v[208:211], v232 offset:4096
	v_mfma_f32_16x16x32_bf16 v[80:83], v[128:131], v[164:167], v[80:83]
	v_mfma_f32_16x16x32_bf16 v[84:87], v[132:135], v[164:167], v[84:87]
	v_mfma_f32_16x16x32_bf16 v[88:91], v[136:139], v[164:167], v[88:91]
	v_mfma_f32_16x16x32_bf16 v[92:95], v[140:143], v[164:167], v[92:95]
	ds_read_b128 v[212:215], v232 offset:5120
	s_cmp_eq_u32 s24, 0
	s_cbranch_scc0 .Lg11_hi4
	s_setprio 0
.Lg11_hi4:
	v_mfma_f32_16x16x32_bf16 v[96:99], v[128:131], v[168:171], v[96:99]
	v_mfma_f32_16x16x32_bf16 v[100:103], v[132:135], v[168:171], v[100:103]
	v_mfma_f32_16x16x32_bf16 v[104:107], v[136:139], v[168:171], v[104:107]
	v_mfma_f32_16x16x32_bf16 v[108:111], v[140:143], v[168:171], v[108:111]
	ds_read_b128 v[216:219], v232 offset:6144
	s_add_u32 s30, s30, 24576
	s_cmp_eq_u32 s30, 73728
	s_cselect_b32 s30, 0, s30
	v_mfma_f32_16x16x32_bf16 v[112:115], v[128:131], v[172:175], v[112:115]
	v_mfma_f32_16x16x32_bf16 v[116:119], v[132:135], v[172:175], v[116:119]
	v_mfma_f32_16x16x32_bf16 v[120:123], v[136:139], v[172:175], v[120:123]
	v_mfma_f32_16x16x32_bf16 v[124:127], v[140:143], v[172:175], v[124:127]
	ds_read_b128 v[220:223], v232 offset:7168
	s_waitcnt lgkmcnt(0)
	s_barrier
	s_setprio 1
	v_mfma_f32_16x16x32_bf16 v[0:3], v[176:179], v[192:195], v[0:3]
	v_mfma_f32_16x16x32_bf16 v[4:7], v[180:183], v[192:195], v[4:7]
	v_mfma_f32_16x16x32_bf16 v[8:11], v[184:187], v[192:195], v[8:11]
	v_mfma_f32_16x16x32_bf16 v[12:15], v[188:191], v[192:195], v[12:15]
	v_mfma_f32_16x16x32_bf16 v[16:19], v[176:179], v[196:199], v[16:19]
	v_mfma_f32_16x16x32_bf16 v[20:23], v[180:183], v[196:199], v[20:23]
	v_mfma_f32_16x16x32_bf16 v[24:27], v[184:187], v[196:199], v[24:27]
	v_mfma_f32_16x16x32_bf16 v[28:31], v[188:191], v[196:199], v[28:31]
	v_mfma_f32_16x16x32_bf16 v[32:35], v[176:179], v[200:203], v[32:35]
	v_mfma_f32_16x16x32_bf16 v[36:39], v[180:183], v[200:203], v[36:39]
	v_mfma_f32_16x16x32_bf16 v[40:43], v[184:187], v[200:203], v[40:43]
	v_mfma_f32_16x16x32_bf16 v[44:47], v[188:191], v[200:203], v[44:47]
	v_mfma_f32_16x16x32_bf16 v[48:51], v[176:179], v[204:207], v[48:51]
	v_mfma_f32_16x16x32_bf16 v[52:55], v[180:183], v[204:207], v[52:55]
	v_mfma_f32_16x16x32_bf16 v[56:59], v[184:187], v[204:207], v[56:59]
	v_mfma_f32_16x16x32_bf16 v[60:63], v[188:191], v[204:207], v[60:63]
	v_mfma_f32_16x16x32_bf16 v[64:67], v[176:179], v[208:211], v[64:67]
	v_mfma_f32_16x16x32_bf16 v[68:71], v[180:183], v[208:211], v[68:71]
	v_mfma_f32_16x16x32_bf16 v[72:75], v[184:187], v[208:211], v[72:75]
	v_mfma_f32_16x16x32_bf16 v[76:79], v[188:191], v[208:211], v[76:79]
	v_mfma_f32_16x16x32_bf16 v[80:83], v[176:179], v[212:215], v[80:83]
	v_mfma_f32_16x16x32_bf16 v[84:87], v[180:183], v[212:215], v[84:87]
	v_mfma_f32_16x16x32_bf16 v[88:91], v[184:187], v[212:215], v[88:91]
	v_mfma_f32_16x16x32_bf16 v[92:95], v[188:191], v[212:215], v[92:95]
	s_cmp_eq_u32 s24, 0
	s_cbranch_scc0 .Lg11_hi5
	s_setprio 0

; #define LWRITE(S, buf) do { bf16_t* sA_ = sbase + (buf) * BUF; bf16_t* sB_ = sA_ + 256 * PITCH; \
;     _Pragma("unroll") for (int i_ = 0; i_ < 4; ++i_) *(u32x4*)(sA_ + (sr + i_ * 64) * PITCH + scv * 8) = ra[S][i_]; \
;     _Pragma("unroll") for (int i_ = 0; i_ < 2; ++i_) *(u32x4*)(sB_ + (sr + i_ * 64) * PITCH + scv * 8) = rb[S][i_]; } while (0)
; template <class Epi>
; DI void gemm_tile(char* smem, const bf16_t* __restrict__ A0, int lda0, int ksplit, const bf16_t* __restrict__ A1, int lda1,
;                   const bf16_t* __restrict__ Bt, int K, int row0, int col0, const Epi& epi, int tid) {
;     ...
;   __syncthreads();
;   {
;     const int last = nk - 1;
;     GLOAD(0, 0);
;     __builtin_amdgcn_sched_barrier(0);
;     GLOAD(1, 1);
;     __builtin_amdgcn_sched_barrier(0);
;     LWRITE(0, 0);
;     __builtin_amdgcn_sched_barrier(0);
;     GLOAD(0, (2 < last ? 2 : last));
;     __builtin_amdgcn_sched_barrier(0);
;     __syncthreads();
;     for (int kt = 0; kt < nk; kt += 2) {
;       LWRITE(1, 1);
;       __builtin_amdgcn_sched_barrier(0);
;       GLOAD(1, (kt + 3 < last ? kt + 3 : last));
;       __builtin_amdgcn_sched_barrier(0);
;       COMPUTE(0);
;       __syncthreads();
;       LWRITE(0, 0);
;       __builtin_amdgcn_sched_barrier(0);
;       GLOAD(0, (kt + 4 < last ? kt + 4 : last));
;       __builtin_amdgcn_sched_barrier(0);
;       COMPUTE(1);
;       __syncthreads();
.Lg14_hi1:
	v_mfma_f32_16x16x32_bf16 v[96:99], v[176:179], v[216:219], v[96:99]
	v_mfma_f32_16x16x32_bf16 v[100:103], v[180:183], v[216:219], v[100:103]
	v_mfma_f32_16x16x32_bf16 v[104:107], v[184:187], v[216:219], v[104:107]
	v_mfma_f32_16x16x32_bf16 v[108:111], v[188:191], v[216:219], v[108:111]
	ds_read_b128 v[168:171], v232 offset:6144
	s_add_u32 s0, s0, 64
	s_addc_u32 s1, s1, 0
	s_add_u32 s2, s2, 64
	s_addc_u32 s3, s3, 0
	s_add_u32 s100, s100, 1
	s_add_u32 s19, s19, 24576
	s_cmp_eq_u32 s19, 73728
	s_cselect_b32 s19, 0, s19
	s_add_u32 s98, s98, 24576
	s_cmp_eq_u32 s98, 73728
	s_cselect_b32 s98, 0, s98
	v_mfma_f32_16x16x32_bf16 v[112:115], v[176:179], v[220:223], v[112:115]
	v_mfma_f32_16x16x32_bf16 v[116:119], v[180:183], v[220:223], v[116:119]
	v_mfma_f32_16x16x32_bf16 v[120:123], v[184:187], v[220:223], v[120:123]
	v_mfma_f32_16x16x32_bf16 v[124:127], v[188:191], v[220:223], v[124:127]
	ds_read_b128 v[172:175], v232 offset:7168
	s_add_u32 s99, s99, 2
	s_cmp_lt_u32 s99, 12
	s_cbranch_scc1 .Lg14_kloop
	s_waitcnt vmcnt(6)
	s_waitcnt lgkmcnt(0)
	s_barrier
	v_add_u32_e32 v232, s98, v230
	v_add_u32_e32 v233, s98, v231
	s_add_u32 s11, s19, s101
	s_setprio 1
	v_mfma_f32_16x16x32_bf16 v[0:3], v[128:131], v[144:147], v[0:3]
	v_mfma_f32_16x16x32_bf16 v[4:7], v[132:135], v[144:147], v[4:7]
	v_mfma_f32_16x16x32_bf16 v[8:11], v[136:139], v[144:147], v[8:11]
	v_mfma_f32_16x16x32_bf16 v[12:15], v[140:143], v[144:147], v[12:15]
	ds_read_b128 v[176:179], v233 offset:0
	ds_read_b128 v[180:183], v233 offset:1024
	s_add_u32 m0, s11, 0
	s_nop 0
	global_load_lds_dwordx4 v224, s[0:1]
	v_mfma_f32_16x16x32_bf16 v[16:19], v[128:131], v[148:151], v[16:19]
	v_mfma_f32_16x16x32_bf16 v[20:23], v[132:135], v[148:151], v[20:23]
	v_mfma_f32_16x16x32_bf16 v[24:27], v[136:139], v[148:151], v[24:27]
	v_mfma_f32_16x16x32_bf16 v[28:31], v[140:143], v[148:151], v[28:31]
	ds_read_b128 v[184:187], v233 offset:2048
	ds_read_b128 v[188:191], v233 offset:3072
	s_add_u32 m0, s11, 4096
	s_nop 0
	global_load_lds_dwordx4 v225, s[0:1]
	v_mfma_f32_16x16x32_bf16 v[32:35], v[128:131], v[152:155], v[32:35]
	v_mfma_f32_16x16x32_bf16 v[36:39], v[132:135], v[152:155], v[36:39]
	v_mfma_f32_16x16x32_bf16 v[40:43], v[136:139], v[152:155], v[40:43]
	v_mfma_f32_16x16x32_bf16 v[44:47], v[140:143], v[152:155], v[44:47]
	ds_read_b128 v[192:195], v232 offset:0
	ds_read_b128 v[196:199], v232 offset:1024
	s_add_u32 m0, s11, 8192
	s_nop 0
	global_load_lds_dwordx4 v226, s[0:1]
	v_mfma_f32_16x16x32_bf16 v[48:51], v[128:131], v[156:159], v[48:51]
	v_mfma_f32_16x16x32_bf16 v[52:55], v[132:135], v[156:159], v[52:55]
	v_mfma_f32_16x16x32_bf16 v[56:59], v[136:139], v[156:159], v[56:59]
	v_mfma_f32_16x16x32_bf16 v[60:63], v[140:143], v[156:159], v[60:63]
	ds_read_b128 v[200:203], v232 offset:2048
	ds_read_b128 v[204:207], v232 offset:3072
	s_add_u32 m0, s11, 12288
	s_nop 0
	global_load_lds_dwordx4 v227, s[0:1]
	v_mfma_f32_16x16x32_bf16 v[64:67], v[128:131], v[160:163], v[64:67]
	v_mfma_f32_16x16x32_bf16 v[68:71], v[132:135], v[160:163], v[68:71]
	v_mfma_f32_16x16x32_bf16 v[72:75], v[136:139], v[160:163], v[72:75]
	v_mfma_f32_16x16x32_bf16 v[76:79], v[140:143], v[160:163], v[76:79]
	ds_read_b128 v[208:211], v232 offset:4096
	s_add_u32 m0, s11, 16384
	s_nop 0
	global_load_lds_dwordx4 v228, s[2:3]
	v_mfma_f32_16x16x32_bf16 v[80:83], v[128:131], v[164:167], v[80:83]
	v_mfma_f32_16x16x32_bf16 v[84:87], v[132:135], v[164:167], v[84:87]
	v_mfma_f32_16x16x32_bf16 v[88:91], v[136:139], v[164:167], v[88:91]
	v_mfma_f32_16x16x32_bf16 v[92:95], v[140:143], v[164:167], v[92:95]
	ds_read_b128 v[212:215], v232 offset:5120
	s_add_u32 m0, s11, 20480
	s_nop 0
	global_load_lds_dwordx4 v229, s[2:3]
	s_cmp_eq_u32 s10, 0
	s_cbranch_scc0 .Lg14_hi2
	s_setprio 0
